# LRU 16-token scan rewritten with DPP on fmac/mul (144 instead of 416 serial instructions); redundant adjacent s_setprio 0/1 pairs inside the GEMM MFMA streams removed; plus earlier epilogue changes
# speedup vs baseline: 1.0066x; 1.0066x over previous
; #define PG8_STAGE(bufoff, gbase, voff) do { _Pragma("unroll") for (int _i = 0; _i < 2; ++_i) \
;         __builtin_amdgcn_global_load_lds((const unsigned*)((const char*)(gbase) + (voff)[_i]), (PG8_LAS unsigned*)(lds + (bufoff) + ldsw + _i * 8192), 16, 0, 0); } while (0)
; #define PG8_LDA(dst, b, h) do { _Pragma("unroll") for (int m = 0; m < 4; ++m) _Pragma("unroll") for (int k = 0; k < 2; ++k) dst[m][k] = *(const PG8_LAS bf16x8*)(lds + PG8_SA(b, h) + aoff + m * 2048 + k * 1024); } while (0)
; #define PG8_LDB(dst, b, h) do { _Pragma("unroll") for (int n = 0; n < 2; ++n) _Pragma("unroll") for (int k = 0; k < 2; ++k) dst[n][k] = *(const PG8_LAS bf16x8*)(lds + PG8_SB(b, h) + boff + n * 2048 + k * 1024); } while (0)
; #define PG8_MMA(ai, bj, At, Bt) do { __builtin_amdgcn_s_setprio(1); _Pragma("unroll") for (int m = 0; m < 4; ++m) _Pragma("unroll") for (int n = 0; n < 2; ++n) _Pragma("unroll") for (int k = 0; k < 2; ++k) \
;         acc[ai][bj][m][n] = __builtin_amdgcn_mfma_f32_16x16x32_bf16(Bt[n][k], At[m][k], acc[ai][bj][m][n], 0, 0, 0); __builtin_amdgcn_s_setprio(0); } while (0)
; #define PG8_WAIT_V(n) asm volatile("s_waitcnt vmcnt(" #n ")" ::: "memory")
; #define PG8_WAIT_L(n) asm volatile("s_waitcnt lgkmcnt(" #n ")" ::: "memory")
; #define PG8_BAR __builtin_amdgcn_s_barrier()
; #define PG8_SCHED __builtin_amdgcn_sched_barrier(0)
; template <class Epi, class Sched, bool ALIGN_EPI = false, bool SP2 = false>
; __device__ __forceinline__ void gemm_phase(PG8_LAS unsigned char* lds, const Gemm g, const Sched& S, const Epi& E) {
;     ...
;             PG8_LDB(B0, 0, 0); PG8_LDB(B1, 0, 1); PG8_SCHED; PG8_LDA(At, 0, 0); PG8_STAGE(PG8_SA(1, 1), a1 + hstepA, voffA);
;             PG8_WAIT_V(8); PG8_WAIT_L(0); PG8_BAR; PG8_MMA(0, 0, At, B0); PG8_MMA(0, 1, At, B1); PG8_BAR; PG8_SCHED;
;             PG8_LDA(At, 0, 1); PG8_STAGE(PG8_SB(0, 0), b2, voffB); PG8_STAGE(PG8_SB(0, 1), b2 + hstepB, voffB); PG8_STAGE(PG8_SA(0, 0), a2, voffA);
;             PG8_WAIT_V(8); PG8_WAIT_L(0); PG8_BAR; PG8_MMA(1, 0, At, B0); PG8_MMA(1, 1, At, B1); PG8_BAR; PG8_SCHED;
.LBB0_122:
	ds_read_b128 v[146:149], v161
	ds_read_b128 v[150:153], v161 offset:1024
	ds_read_b128 v[166:169], v161 offset:2048
	ds_read_b128 v[170:173], v161 offset:3072
	ds_read_b128 v[174:177], v162
	ds_read_b128 v[178:181], v162 offset:1024
	ds_read_b128 v[182:185], v162 offset:2048
	ds_read_b128 v[186:189], v162 offset:3072
	s_add_u32 s26, s6, 0xfff00080
	s_addc_u32 s27, s7, -1
	s_cmp_eq_u32 s31, 28
	s_cselect_b32 s29, s3, s27
	s_cselect_b32 s28, s5, s26
	s_cselect_b32 s27, s10, s30
	s_cselect_b32 s26, s19, s21
	v_lshl_add_u64 v[154:155], s[6:7], 0, v[138:139]
	s_add_i32 m0, s39, 0xc000
	ds_read_b128 v[190:193], v163
	ds_read_b128 v[194:197], v163 offset:1024
	ds_read_b128 v[198:201], v163 offset:2048
	ds_read_b128 v[202:205], v163 offset:3072
	ds_read_b128 v[206:209], v163 offset:4096
	ds_read_b128 v[210:213], v163 offset:5120
	ds_read_b128 v[214:217], v163 offset:6144
	ds_read_b128 v[218:221], v163 offset:7168
	global_load_lds_dwordx4 v[154:155], off
	v_lshl_add_u64 v[154:155], s[6:7], 0, v[140:141]
	s_add_i32 m0, s39, 0xe000
	s_nop 0
	global_load_lds_dwordx4 v[154:155], off
	s_waitcnt vmcnt(8)
	s_waitcnt lgkmcnt(0)
	s_barrier
	s_setprio 1
	s_waitcnt lgkmcnt(0)
	v_mfma_f32_16x16x32_bf16 v[124:127], v[146:149], v[190:193], v[124:127]
	v_mfma_f32_16x16x32_bf16 v[120:123], v[166:169], v[190:193], v[120:123]
	v_mfma_f32_16x16x32_bf16 v[108:111], v[146:149], v[198:201], v[108:111]
	v_mfma_f32_16x16x32_bf16 v[104:107], v[166:169], v[198:201], v[104:107]
	v_mfma_f32_16x16x32_bf16 v[92:95], v[146:149], v[206:209], v[92:95]
	v_mfma_f32_16x16x32_bf16 v[88:91], v[166:169], v[206:209], v[88:91]
	v_mfma_f32_16x16x32_bf16 v[76:79], v[146:149], v[214:217], v[76:79]
	v_mfma_f32_16x16x32_bf16 v[72:75], v[166:169], v[214:217], v[72:75]
	v_mfma_f32_16x16x32_bf16 v[124:127], v[150:153], v[194:197], v[124:127]
	v_mfma_f32_16x16x32_bf16 v[120:123], v[170:173], v[194:197], v[120:123]
	v_mfma_f32_16x16x32_bf16 v[108:111], v[150:153], v[202:205], v[108:111]
	v_mfma_f32_16x16x32_bf16 v[104:107], v[170:173], v[202:205], v[104:107]
	v_mfma_f32_16x16x32_bf16 v[92:95], v[150:153], v[210:213], v[92:95]
	v_mfma_f32_16x16x32_bf16 v[88:91], v[170:173], v[210:213], v[88:91]
	v_mfma_f32_16x16x32_bf16 v[76:79], v[150:153], v[218:221], v[76:79]
	v_mfma_f32_16x16x32_bf16 v[72:75], v[170:173], v[218:221], v[72:75]
	v_mfma_f32_16x16x32_bf16 v[116:119], v[174:177], v[190:193], v[116:119]
	v_mfma_f32_16x16x32_bf16 v[112:115], v[182:185], v[190:193], v[112:115]
	v_mfma_f32_16x16x32_bf16 v[100:103], v[174:177], v[198:201], v[100:103]
	v_mfma_f32_16x16x32_bf16 v[96:99], v[182:185], v[198:201], v[96:99]
	v_mfma_f32_16x16x32_bf16 v[84:87], v[174:177], v[206:209], v[84:87]
	v_mfma_f32_16x16x32_bf16 v[80:83], v[182:185], v[206:209], v[80:83]
	v_mfma_f32_16x16x32_bf16 v[68:71], v[174:177], v[214:217], v[68:71]
	v_mfma_f32_16x16x32_bf16 v[64:67], v[182:185], v[214:217], v[64:67]
	v_mfma_f32_16x16x32_bf16 v[116:119], v[178:181], v[194:197], v[116:119]
	v_mfma_f32_16x16x32_bf16 v[112:115], v[186:189], v[194:197], v[112:115]
	v_mfma_f32_16x16x32_bf16 v[100:103], v[178:181], v[202:205], v[100:103]
	v_mfma_f32_16x16x32_bf16 v[96:99], v[186:189], v[202:205], v[96:99]
	v_mfma_f32_16x16x32_bf16 v[84:87], v[178:181], v[210:213], v[84:87]
	v_mfma_f32_16x16x32_bf16 v[80:83], v[186:189], v[210:213], v[80:83]
	v_mfma_f32_16x16x32_bf16 v[68:71], v[178:181], v[218:221], v[68:71]
	v_mfma_f32_16x16x32_bf16 v[64:67], v[186:189], v[218:221], v[64:67]
	s_setprio 0
	s_barrier
	s_add_i32 s34, s54, s38
	v_lshl_add_u64 v[154:155], s[26:27], 0, v[130:131]
	s_mov_b32 m0, s34
	ds_read_b128 v[190:193], v163 offset:16384
	ds_read_b128 v[194:197], v163 offset:17408
	ds_read_b128 v[198:201], v163 offset:18432
	ds_read_b128 v[202:205], v163 offset:19456
	ds_read_b128 v[206:209], v163 offset:20480
	ds_read_b128 v[210:213], v163 offset:21504
	ds_read_b128 v[214:217], v163 offset:22528
	ds_read_b128 v[218:221], v163 offset:23552
	global_load_lds_dwordx4 v[154:155], off
	s_add_i32 m0, s34, 0x2000
	s_add_u32 s34, s26, 0x80000
	v_lshl_add_u64 v[222:223], s[26:27], 0, v[134:135]
	s_addc_u32 s35, s27, 0
	s_add_i32 s68, s55, s38
	global_load_lds_dwordx4 v[222:223], off
	v_lshl_add_u64 v[224:225], s[34:35], 0, v[130:131]
	s_mov_b32 m0, s68
	v_lshl_add_u64 v[226:227], s[28:29], 0, v[132:133]
	global_load_lds_dwordx4 v[224:225], off
	v_lshl_add_u64 v[224:225], s[34:35], 0, v[134:135]
	s_add_i32 m0, s68, 0x2000
	s_nop 0
	global_load_lds_dwordx4 v[224:225], off
	v_lshl_add_u64 v[224:225], s[28:29], 0, v[128:129]
	s_mov_b32 m0, s39
	s_nop 0
	global_load_lds_dwordx4 v[224:225], off
	s_mov_b32 m0, s40
	s_nop 0
	global_load_lds_dwordx4 v[226:227], off
	s_waitcnt vmcnt(8)
	s_waitcnt lgkmcnt(0)
	s_barrier
; #define PG8_STAGE(bufoff, gbase, voff) do { _Pragma("unroll") for (int _i = 0; _i < 2; ++_i) \
;         __builtin_amdgcn_global_load_lds((const unsigned*)((const char*)(gbase) + (voff)[_i]), (PG8_LAS unsigned*)(lds + (bufoff) + ldsw + _i * 8192), 16, 0, 0); } while (0)
; #define PG8_LDA(dst, b, h) do { _Pragma("unroll") for (int m = 0; m < 4; ++m) _Pragma("unroll") for (int k = 0; k < 2; ++k) dst[m][k] = *(const PG8_LAS bf16x8*)(lds + PG8_SA(b, h) + aoff + m * 2048 + k * 1024); } while (0)
; #define PG8_LDB(dst, b, h) do { _Pragma("unroll") for (int n = 0; n < 2; ++n) _Pragma("unroll") for (int k = 0; k < 2; ++k) dst[n][k] = *(const PG8_LAS bf16x8*)(lds + PG8_SB(b, h) + boff + n * 2048 + k * 1024); } while (0)
; #define PG8_MMA(ai, bj, At, Bt) do { __builtin_amdgcn_s_setprio(1); _Pragma("unroll") for (int m = 0; m < 4; ++m) _Pragma("unroll") for (int n = 0; n < 2; ++n) _Pragma("unroll") for (int k = 0; k < 2; ++k) \
;         acc[ai][bj][m][n] = __builtin_amdgcn_mfma_f32_16x16x32_bf16(Bt[n][k], At[m][k], acc[ai][bj][m][n], 0, 0, 0); __builtin_amdgcn_s_setprio(0); } while (0)
; #define PG8_WAIT_V(n) asm volatile("s_waitcnt vmcnt(" #n ")" ::: "memory")
; #define PG8_WAIT_L(n) asm volatile("s_waitcnt lgkmcnt(" #n ")" ::: "memory")
; #define PG8_BAR __builtin_amdgcn_s_barrier()
; #define PG8_SCHED __builtin_amdgcn_sched_barrier(0)
; template <class Epi, class Sched, bool ALIGN_EPI = false, bool SP2 = false>
; __device__ __forceinline__ void gemm_phase(PG8_LAS unsigned char* lds, const Gemm g, const Sched& S, const Epi& E) {
;     ...
;             PG8_WAIT_V(8); PG8_WAIT_L(0); PG8_BAR; PG8_MMA(1, 0, At, B0); PG8_MMA(1, 1, At, B1); PG8_BAR; PG8_SCHED;
;             PG8_LDB(B0, 1, 0); PG8_LDB(B1, 1, 1); PG8_SCHED; PG8_LDA(At, 1, 0); PG8_STAGE(PG8_SA(0, 1), a2 + hstepA, voffA);
;             PG8_WAIT_V(8); PG8_WAIT_L(0); PG8_BAR; PG8_MMA(0, 0, At, B0); PG8_MMA(0, 1, At, B1); PG8_BAR; PG8_SCHED;
;             PG8_LDA(At, 1, 1); PG8_STAGE(PG8_SB(1, 0), b3, voffB); PG8_STAGE(PG8_SB(1, 1), b3 + hstepB, voffB); PG8_STAGE(PG8_SA(1, 0), a3, voffA);
;             PG8_WAIT_V(8); PG8_WAIT_L(0); PG8_BAR; PG8_MMA(1, 0, At, B0); PG8_MMA(1, 1, At, B1); PG8_BAR; PG8_SCHED;
	s_setprio 1
	s_waitcnt lgkmcnt(0)
	v_mfma_f32_16x16x32_bf16 v[60:63], v[146:149], v[190:193], v[60:63]
	v_mfma_f32_16x16x32_bf16 v[56:59], v[166:169], v[190:193], v[56:59]
	v_mfma_f32_16x16x32_bf16 v[44:47], v[146:149], v[198:201], v[44:47]
	v_mfma_f32_16x16x32_bf16 v[40:43], v[166:169], v[198:201], v[40:43]
	v_mfma_f32_16x16x32_bf16 v[28:31], v[146:149], v[206:209], v[28:31]
	v_mfma_f32_16x16x32_bf16 v[24:27], v[166:169], v[206:209], v[24:27]
	v_mfma_f32_16x16x32_bf16 v[12:15], v[146:149], v[214:217], v[12:15]
	v_mfma_f32_16x16x32_bf16 v[8:11], v[166:169], v[214:217], v[8:11]
	v_mfma_f32_16x16x32_bf16 v[60:63], v[150:153], v[194:197], v[60:63]
	v_mfma_f32_16x16x32_bf16 v[56:59], v[170:173], v[194:197], v[56:59]
	v_mfma_f32_16x16x32_bf16 v[44:47], v[150:153], v[202:205], v[44:47]
	v_mfma_f32_16x16x32_bf16 v[40:43], v[170:173], v[202:205], v[40:43]
	v_mfma_f32_16x16x32_bf16 v[28:31], v[150:153], v[210:213], v[28:31]
	v_mfma_f32_16x16x32_bf16 v[24:27], v[170:173], v[210:213], v[24:27]
	v_mfma_f32_16x16x32_bf16 v[12:15], v[150:153], v[218:221], v[12:15]
	v_mfma_f32_16x16x32_bf16 v[8:11], v[170:173], v[218:221], v[8:11]
	v_mfma_f32_16x16x32_bf16 v[52:55], v[174:177], v[190:193], v[52:55]
	v_mfma_f32_16x16x32_bf16 v[48:51], v[182:185], v[190:193], v[48:51]
	v_mfma_f32_16x16x32_bf16 v[36:39], v[174:177], v[198:201], v[36:39]
	v_mfma_f32_16x16x32_bf16 v[32:35], v[182:185], v[198:201], v[32:35]
	v_mfma_f32_16x16x32_bf16 v[20:23], v[174:177], v[206:209], v[20:23]
	v_mfma_f32_16x16x32_bf16 v[16:19], v[182:185], v[206:209], v[16:19]
	v_mfma_f32_16x16x32_bf16 v[4:7], v[174:177], v[214:217], v[4:7]
	v_mfma_f32_16x16x32_bf16 v[0:3], v[182:185], v[214:217], v[0:3]
	v_mfma_f32_16x16x32_bf16 v[52:55], v[178:181], v[194:197], v[52:55]
	v_mfma_f32_16x16x32_bf16 v[48:51], v[186:189], v[194:197], v[48:51]
	v_mfma_f32_16x16x32_bf16 v[36:39], v[178:181], v[202:205], v[36:39]
	v_mfma_f32_16x16x32_bf16 v[32:35], v[186:189], v[202:205], v[32:35]
	v_mfma_f32_16x16x32_bf16 v[20:23], v[178:181], v[210:213], v[20:23]
	v_mfma_f32_16x16x32_bf16 v[16:19], v[186:189], v[210:213], v[16:19]
	v_mfma_f32_16x16x32_bf16 v[4:7], v[178:181], v[218:221], v[4:7]
	v_mfma_f32_16x16x32_bf16 v[0:3], v[186:189], v[218:221], v[0:3]
	s_setprio 0
	s_barrier
	s_add_i32 s34, 0, 0x18000
	v_add_u32_e32 v136, s34, v159
	s_add_i32 s35, 0, 0x1c000
	ds_read_b128 v[146:149], v136
	ds_read_b128 v[150:153], v136 offset:1024
	ds_read_b128 v[166:169], v136 offset:2048
	ds_read_b128 v[170:173], v136 offset:3072
	v_add_u32_e32 v136, s35, v159
	ds_read_b128 v[174:177], v136
	ds_read_b128 v[178:181], v136 offset:1024
	ds_read_b128 v[182:185], v136 offset:2048
	ds_read_b128 v[186:189], v136 offset:3072
	s_add_u32 s28, s28, 0x100000
	s_addc_u32 s29, s29, 0
	s_mov_b32 m0, s41
	v_lshl_add_u64 v[228:229], s[28:29], 0, v[128:129]
	ds_read_b128 v[190:193], v163 offset:32768
	ds_read_b128 v[194:197], v163 offset:33792
	ds_read_b128 v[198:201], v163 offset:34816
	ds_read_b128 v[202:205], v163 offset:35840
	ds_read_b128 v[206:209], v163 offset:36864
	ds_read_b128 v[210:213], v163 offset:37888
	ds_read_b128 v[214:217], v163 offset:38912
	ds_read_b128 v[218:221], v163 offset:39936
	global_load_lds_dwordx4 v[228:229], off
	v_lshl_add_u64 v[228:229], s[28:29], 0, v[132:133]
	s_mov_b32 m0, s42
	s_nop 0
	global_load_lds_dwordx4 v[228:229], off
	s_waitcnt vmcnt(8)
	s_waitcnt lgkmcnt(0)
	s_barrier
	s_setprio 1
	s_waitcnt lgkmcnt(0)
	v_mfma_f32_16x16x32_bf16 v[124:127], v[146:149], v[190:193], v[124:127]
	v_mfma_f32_16x16x32_bf16 v[120:123], v[166:169], v[190:193], v[120:123]
	v_mfma_f32_16x16x32_bf16 v[108:111], v[146:149], v[198:201], v[108:111]
	v_mfma_f32_16x16x32_bf16 v[104:107], v[166:169], v[198:201], v[104:107]
	v_mfma_f32_16x16x32_bf16 v[92:95], v[146:149], v[206:209], v[92:95]
	v_mfma_f32_16x16x32_bf16 v[88:91], v[166:169], v[206:209], v[88:91]
	v_mfma_f32_16x16x32_bf16 v[76:79], v[146:149], v[214:217], v[76:79]
	v_mfma_f32_16x16x32_bf16 v[72:75], v[166:169], v[214:217], v[72:75]
	v_mfma_f32_16x16x32_bf16 v[124:127], v[150:153], v[194:197], v[124:127]
	v_mfma_f32_16x16x32_bf16 v[120:123], v[170:173], v[194:197], v[120:123]
	v_mfma_f32_16x16x32_bf16 v[108:111], v[150:153], v[202:205], v[108:111]
	v_mfma_f32_16x16x32_bf16 v[104:107], v[170:173], v[202:205], v[104:107]
	v_mfma_f32_16x16x32_bf16 v[92:95], v[150:153], v[210:213], v[92:95]
	v_mfma_f32_16x16x32_bf16 v[88:91], v[170:173], v[210:213], v[88:91]
	v_mfma_f32_16x16x32_bf16 v[76:79], v[150:153], v[218:221], v[76:79]
	v_mfma_f32_16x16x32_bf16 v[72:75], v[170:173], v[218:221], v[72:75]
	v_mfma_f32_16x16x32_bf16 v[116:119], v[174:177], v[190:193], v[116:119]
	v_mfma_f32_16x16x32_bf16 v[112:115], v[182:185], v[190:193], v[112:115]
	v_mfma_f32_16x16x32_bf16 v[100:103], v[174:177], v[198:201], v[100:103]
	v_mfma_f32_16x16x32_bf16 v[96:99], v[182:185], v[198:201], v[96:99]
	v_mfma_f32_16x16x32_bf16 v[84:87], v[174:177], v[206:209], v[84:87]
	v_mfma_f32_16x16x32_bf16 v[80:83], v[182:185], v[206:209], v[80:83]
	v_mfma_f32_16x16x32_bf16 v[68:71], v[174:177], v[214:217], v[68:71]
	v_mfma_f32_16x16x32_bf16 v[64:67], v[182:185], v[214:217], v[64:67]
	v_mfma_f32_16x16x32_bf16 v[116:119], v[178:181], v[194:197], v[116:119]
	v_mfma_f32_16x16x32_bf16 v[112:115], v[186:189], v[194:197], v[112:115]
	v_mfma_f32_16x16x32_bf16 v[100:103], v[178:181], v[202:205], v[100:103]
	v_mfma_f32_16x16x32_bf16 v[96:99], v[186:189], v[202:205], v[96:99]
	v_mfma_f32_16x16x32_bf16 v[84:87], v[178:181], v[210:213], v[84:87]
	v_mfma_f32_16x16x32_bf16 v[80:83], v[186:189], v[210:213], v[80:83]
	v_mfma_f32_16x16x32_bf16 v[68:71], v[178:181], v[218:221], v[68:71]
	v_mfma_f32_16x16x32_bf16 v[64:67], v[186:189], v[218:221], v[64:67]
	s_setprio 0
	s_barrier
; #define PG8_STAGE(bufoff, gbase, voff) do { _Pragma("unroll") for (int _i = 0; _i < 2; ++_i) \
;         __builtin_amdgcn_global_load_lds((const unsigned*)((const char*)(gbase) + (voff)[_i]), (PG8_LAS unsigned*)(lds + (bufoff) + ldsw + _i * 8192), 16, 0, 0); } while (0)
; #define PG8_LDA(dst, b, h) do { _Pragma("unroll") for (int m = 0; m < 4; ++m) _Pragma("unroll") for (int k = 0; k < 2; ++k) dst[m][k] = *(const PG8_LAS bf16x8*)(lds + PG8_SA(b, h) + aoff + m * 2048 + k * 1024); } while (0)
; #define PG8_MMA(ai, bj, At, Bt) do { __builtin_amdgcn_s_setprio(1); _Pragma("unroll") for (int m = 0; m < 4; ++m) _Pragma("unroll") for (int n = 0; n < 2; ++n) _Pragma("unroll") for (int k = 0; k < 2; ++k) \
;         acc[ai][bj][m][n] = __builtin_amdgcn_mfma_f32_16x16x32_bf16(Bt[n][k], At[m][k], acc[ai][bj][m][n], 0, 0, 0); __builtin_amdgcn_s_setprio(0); } while (0)
; #define PG8_WAIT_V(n) asm volatile("s_waitcnt vmcnt(" #n ")" ::: "memory")
; #define PG8_WAIT_L(n) asm volatile("s_waitcnt lgkmcnt(" #n ")" ::: "memory")
; #define PG8_BAR __builtin_amdgcn_s_barrier()
; #define PG8_SCHED __builtin_amdgcn_sched_barrier(0)
; template <class Epi, class Sched, bool ALIGN_EPI = false, bool SP2 = false>
; __device__ __forceinline__ void gemm_phase(PG8_LAS unsigned char* lds, const Gemm g, const Sched& S, const Epi& E) {
;     ...
;         for (int t = 0; t < nt; t += 2) {
;             const bool last = (t == nt - 2);
;             const char* a1 = cA + (size_t)(t + 1) * kstep;
;             const char* a2 = last ? nA : cA + (size_t)(t + 2) * kstep; const char* b2 = last ? nB : cB + (size_t)(t + 2) * kstep;
;     ...
;             PG8_LDA(At, 1, 1); PG8_STAGE(PG8_SB(1, 0), b3, voffB); PG8_STAGE(PG8_SB(1, 1), b3 + hstepB, voffB); PG8_STAGE(PG8_SA(1, 0), a3, voffA);
;             PG8_WAIT_V(8); PG8_WAIT_L(0); PG8_BAR; PG8_MMA(1, 0, At, B0); PG8_MMA(1, 1, At, B1); PG8_BAR; PG8_SCHED;
	s_add_i32 s28, s34, s38
	v_lshl_add_u64 v[154:155], v[154:155], 0, s[14:15]
	s_mov_b32 m0, s28
	ds_read_b128 v[190:193], v163 offset:49152
	ds_read_b128 v[194:197], v163 offset:50176
	ds_read_b128 v[198:201], v163 offset:51200
	ds_read_b128 v[202:205], v163 offset:52224
	ds_read_b128 v[206:209], v163 offset:53248
	ds_read_b128 v[210:213], v163 offset:54272
	ds_read_b128 v[214:217], v163 offset:55296
	ds_read_b128 v[218:221], v163 offset:56320
	global_load_lds_dwordx4 v[154:155], off
	s_add_i32 m0, s28, 0x2000
	s_add_u32 s26, s26, 0x80080
	v_lshl_add_u64 v[154:155], v[222:223], 0, s[14:15]
	s_addc_u32 s27, s27, 0
	s_add_i32 s28, s35, s38
	global_load_lds_dwordx4 v[154:155], off
	v_lshl_add_u64 v[154:155], s[26:27], 0, v[130:131]
	s_mov_b32 m0, s28
	s_nop 0
	global_load_lds_dwordx4 v[154:155], off
	v_lshl_add_u64 v[154:155], s[26:27], 0, v[134:135]
	s_add_i32 m0, s28, 0x2000
	s_nop 0
	global_load_lds_dwordx4 v[154:155], off
	v_lshl_add_u64 v[154:155], v[224:225], 0, s[14:15]
	s_mov_b32 m0, s47
	s_nop 0
	global_load_lds_dwordx4 v[154:155], off
	v_lshl_add_u64 v[154:155], v[226:227], 0, s[14:15]
	s_mov_b32 m0, s48
	s_nop 0
	global_load_lds_dwordx4 v[154:155], off
	s_waitcnt vmcnt(8)
	s_waitcnt lgkmcnt(0)
	s_barrier
	s_setprio 1
	s_waitcnt lgkmcnt(0)
	v_mfma_f32_16x16x32_bf16 v[60:63], v[146:149], v[190:193], v[60:63]
	v_mfma_f32_16x16x32_bf16 v[56:59], v[166:169], v[190:193], v[56:59]
	v_mfma_f32_16x16x32_bf16 v[44:47], v[146:149], v[198:201], v[44:47]
	v_mfma_f32_16x16x32_bf16 v[40:43], v[166:169], v[198:201], v[40:43]
	v_mfma_f32_16x16x32_bf16 v[28:31], v[146:149], v[206:209], v[28:31]
	v_mfma_f32_16x16x32_bf16 v[24:27], v[166:169], v[206:209], v[24:27]
	v_mfma_f32_16x16x32_bf16 v[12:15], v[146:149], v[214:217], v[12:15]
	v_mfma_f32_16x16x32_bf16 v[8:11], v[166:169], v[214:217], v[8:11]
	v_mfma_f32_16x16x32_bf16 v[60:63], v[150:153], v[194:197], v[60:63]
	v_mfma_f32_16x16x32_bf16 v[56:59], v[170:173], v[194:197], v[56:59]
	v_mfma_f32_16x16x32_bf16 v[44:47], v[150:153], v[202:205], v[44:47]
	v_mfma_f32_16x16x32_bf16 v[40:43], v[170:173], v[202:205], v[40:43]
	v_mfma_f32_16x16x32_bf16 v[28:31], v[150:153], v[210:213], v[28:31]
	v_mfma_f32_16x16x32_bf16 v[24:27], v[170:173], v[210:213], v[24:27]
	v_mfma_f32_16x16x32_bf16 v[12:15], v[150:153], v[218:221], v[12:15]
	v_mfma_f32_16x16x32_bf16 v[8:11], v[170:173], v[218:221], v[8:11]
	v_mfma_f32_16x16x32_bf16 v[52:55], v[174:177], v[190:193], v[52:55]
	v_mfma_f32_16x16x32_bf16 v[48:51], v[182:185], v[190:193], v[48:51]
	v_mfma_f32_16x16x32_bf16 v[36:39], v[174:177], v[198:201], v[36:39]
	v_mfma_f32_16x16x32_bf16 v[32:35], v[182:185], v[198:201], v[32:35]
	v_mfma_f32_16x16x32_bf16 v[20:23], v[174:177], v[206:209], v[20:23]
	v_mfma_f32_16x16x32_bf16 v[16:19], v[182:185], v[206:209], v[16:19]
	v_mfma_f32_16x16x32_bf16 v[4:7], v[174:177], v[214:217], v[4:7]
	v_mfma_f32_16x16x32_bf16 v[0:3], v[182:185], v[214:217], v[0:3]
	v_mfma_f32_16x16x32_bf16 v[52:55], v[178:181], v[194:197], v[52:55]
	v_mfma_f32_16x16x32_bf16 v[48:51], v[186:189], v[194:197], v[48:51]
	v_mfma_f32_16x16x32_bf16 v[36:39], v[178:181], v[202:205], v[36:39]
	v_mfma_f32_16x16x32_bf16 v[32:35], v[186:189], v[202:205], v[32:35]
	v_mfma_f32_16x16x32_bf16 v[20:23], v[178:181], v[210:213], v[20:23]
	v_mfma_f32_16x16x32_bf16 v[16:19], v[186:189], v[210:213], v[16:19]
	v_mfma_f32_16x16x32_bf16 v[4:7], v[178:181], v[218:221], v[4:7]
	v_mfma_f32_16x16x32_bf16 v[0:3], v[186:189], v[218:221], v[0:3]
	s_setprio 0
	s_barrier
	s_add_i32 s31, s31, 2
	s_add_u32 s6, s6, 0x100
	s_addc_u32 s7, s7, 0
	s_add_u32 s21, s21, 0x100
	s_addc_u32 s30, s30, 0
	s_cmp_gt_u32 s31, 29
	s_cbranch_scc0 .LBB0_122
	s_and_b64 vcc, exec, s[16:17]
	s_cbranch_vccz .LBB0_125
	s_barrier

; __device__ __forceinline__ unsigned cvt_pk_bf16(float lo, float hi) { unsigned r; asm volatile("v_cvt_pk_bf16_f32 %0, %1, %2" : "=v"(r) : "v"(lo), "v"(hi)); return r; }
; __device__ __forceinline__ float bf_lo(unsigned w) { return __uint_as_float(w << 16); }
; __device__ __forceinline__ float bf_hi(unsigned w) { return __uint_as_float(w & 0xffff0000u); }
; __device__ __forceinline__ void lru_item(const Frame& F, const bf16* XR, bf16* XGYL, const float* conv_w, const float* conv_b, const float* wa, const float* ba, const float* wx, const float* bx, const float* lam, int b, int hh, int j2) {
;     ...
;         const LAS unsigned char* xb = F.lds + LRU_XBUF + (chunk & 1) * LRU_XBUF_STRIDE + (16 * w + tl) * 256;
;         const int t = chunk * 128 + 16 * w + tl; const size_t row = (size_t)b * SEQ + t;
;         bf16* yp = XGYL + row * 4096 + chn;
;         const v4u gv0 = *(const v4u*)yp, gv1 = *(const v4u*)(yp + 32);
;         bf16x8 bfr[4]; float xcf[16];
; #pragma unroll
;         for (int i = 0; i < 16; ++i) xcf[i] = 0.f;
; #pragma unroll
;         for (int ks = 0; ks < 4; ++ks) { const int cl = 32 * ks + 8 * g; float a8[8];
;             { const f32x4 b0 = *(const LAS f32x4*)(tab + 512 + cl), b1 = *(const LAS f32x4*)(tab + 512 + cl + 4); a8[0] = b0[0]; a8[1] = b0[1]; a8[2] = b0[2]; a8[3] = b0[3]; a8[4] = b1[0]; a8[5] = b1[1]; a8[6] = b1[2]; a8[7] = b1[3]; }
; #pragma unroll
;             for (int k = 0; k < 4; ++k) { const int rr = 16 * w + tl + k; v4u xq = *(const LAS v4u*)(xb + k * 256 + (((4 * ks + g) ^ (rr & 15)) << 4));
;                 const bool inb = (chunk > 0) || (rr >= 3); xq.x = inb ? xq.x : 0u; xq.y = inb ? xq.y : 0u; xq.z = inb ? xq.z : 0u; xq.w = inb ? xq.w : 0u;
;                 const f32x4 w0 = *(const LAS f32x4*)(tab + k * 128 + cl), w1 = *(const LAS f32x4*)(tab + k * 128 + cl + 4);
;                 a8[0] += w0[0] * pg8::bf_lo(xq.x); a8[1] += w0[1] * pg8::bf_hi(xq.x); a8[2] += w0[2] * pg8::bf_lo(xq.y); a8[3] += w0[3] * pg8::bf_hi(xq.y);
;                 a8[4] += w1[0] * pg8::bf_lo(xq.z); a8[5] += w1[1] * pg8::bf_hi(xq.z); a8[6] += w1[2] * pg8::bf_lo(xq.w); a8[7] += w1[3] * pg8::bf_hi(xq.w); }
;             v4u u4; u4.x = pg8::cvt_pk_bf16(a8[0], a8[1]); u4.y = pg8::cvt_pk_bf16(a8[2], a8[3]); u4.z = pg8::cvt_pk_bf16(a8[4], a8[5]); u4.w = pg8::cvt_pk_bf16(a8[6], a8[7]); bfr[ks] = __builtin_bit_cast(bf16x8, u4);
.LBB0_346:
	s_add_i32 s44, s6, -1
	s_and_b32 s7, s44, 1
	s_mul_i32 s2, s7, 0x9000
	v_add_u32_e32 v28, s2, v134
	v_add_u32_e32 v0, v28, v116
	global_load_dwordx4 v[8:11], v[106:107], off offset:-64
	global_load_dwordx4 v[4:7], v[106:107], off
	ds_read_b128 v[16:19], v115 offset:2048
	ds_read_b128 v[12:15], v115 offset:2064
	ds_read_b128 v[20:23], v0 offset:45056
	s_cmp_lg_u32 s95, 0
	s_cselect_b64 s[2:3], -1, 0
	s_or_b64 vcc, s[12:13], s[2:3]
	s_or_b64 s[46:47], s[14:15], s[2:3]
	s_waitcnt lgkmcnt(0)
	v_cndmask_b32_e32 v0, 0, v20, vcc
	v_cndmask_b32_e32 v1, 0, v21, vcc
	v_cndmask_b32_e32 v2, 0, v22, vcc
	v_cndmask_b32_e32 v29, 0, v23, vcc
	ds_read_b128 v[20:23], v115
	ds_read_b128 v[24:27], v115 offset:16
	v_lshlrev_b32_e32 v30, 16, v0
	v_and_b32_e32 v0, 0xffff0000, v0
	s_waitcnt lgkmcnt(0)
	v_fma_f32 v17, v21, v0, v17
	v_lshlrev_b32_e32 v0, 16, v1
	v_fma_f32 v18, v22, v0, v18
	v_and_b32_e32 v0, 0xffff0000, v1
	v_fmac_f32_e32 v19, v23, v0
	v_lshlrev_b32_e32 v0, 16, v2
	v_fma_f32 v42, v24, v0, v12
	v_and_b32_e32 v0, 0xffff0000, v2
	v_fma_f32 v43, v25, v0, v13
	v_lshlrev_b32_e32 v0, 16, v29
	v_fma_f32 v14, v26, v0, v14
	v_and_b32_e32 v0, 0xffff0000, v29
	v_fmac_f32_e32 v15, v27, v0
	v_add_u32_e32 v0, v28, v117
	v_fma_f32 v16, v20, v30, v16
	ds_read_b128 v[20:23], v0 offset:45312
	s_waitcnt lgkmcnt(0)
	v_cndmask_b32_e64 v0, 0, v20, s[46:47]
	v_cndmask_b32_e64 v1, 0, v21, s[46:47]
	v_cndmask_b32_e64 v2, 0, v22, s[46:47]
	v_cndmask_b32_e64 v12, 0, v23, s[46:47]
	ds_read_b128 v[20:23], v115 offset:512
	ds_read_b128 v[24:27], v115 offset:528
	v_lshlrev_b32_e32 v13, 16, v0
	v_and_b32_e32 v0, 0xffff0000, v0
	s_waitcnt lgkmcnt(0)
	v_fmac_f32_e32 v17, v21, v0
	v_lshlrev_b32_e32 v0, 16, v1
	v_fmac_f32_e32 v18, v22, v0
	v_and_b32_e32 v0, 0xffff0000, v1
	v_fmac_f32_e32 v19, v23, v0
	v_lshlrev_b32_e32 v0, 16, v2
	v_fmac_f32_e32 v42, v24, v0
	v_and_b32_e32 v0, 0xffff0000, v2
	v_fmac_f32_e32 v43, v25, v0
	v_lshlrev_b32_e32 v0, 16, v12
	v_fmac_f32_e32 v14, v26, v0
	v_and_b32_e32 v0, 0xffff0000, v12
	v_fmac_f32_e32 v15, v27, v0
	v_add_u32_e32 v0, v28, v118
	v_fmac_f32_e32 v16, v20, v13
	ds_read_b128 v[20:23], v0 offset:45568
	v_or_b32_e32 v0, s44, v88
	v_cmp_eq_u32_e64 s[44:45], 0, v0
	v_add_u32_e32 v0, v28, v119
	s_waitcnt lgkmcnt(0)
	v_cndmask_b32_e64 v2, v20, 0, s[44:45]
	v_cndmask_b32_e64 v29, v21, 0, s[44:45]
	v_cndmask_b32_e64 v44, v22, 0, s[44:45]
	v_cndmask_b32_e64 v45, v23, 0, s[44:45]
	ds_read_b128 v[20:23], v115 offset:1024
	ds_read_b128 v[24:27], v115 offset:1040
	ds_read_b128 v[30:33], v0 offset:45824
	ds_read_b128 v[34:37], v115 offset:1536
	ds_read_b128 v[38:41], v115 offset:1552
	v_lshlrev_b32_e32 v0, 16, v2
	s_waitcnt lgkmcnt(0)
	v_lshlrev_b32_e32 v1, 16, v30
	v_mov_b32_e32 v12, v20
	v_mov_b32_e32 v13, v34
	v_pk_mul_f32 v[0:1], v[12:13], v[0:1]
	v_and_b32_e32 v13, 0xffff0000, v30
	v_and_b32_e32 v12, 0xffff0000, v2
	v_mov_b32_e32 v34, v21
	v_add_f32_e32 v0, v16, v0
	v_pk_mul_f32 v[12:13], v[34:35], v[12:13]
	v_add_f32_e32 v0, v0, v1
	v_add_f32_e32 v1, v17, v12
	v_add_f32_e32 v1, v1, v13
	v_lshlrev_b32_e32 v12, 16, v29
	v_lshlrev_b32_e32 v13, 16, v31
	v_mov_b32_e32 v16, v22
	v_mov_b32_e32 v17, v36
	v_pk_mul_f32 v[12:13], v[16:17], v[12:13]
	v_mov_b32_e32 v36, v23
	v_add_f32_e32 v2, v18, v12
	v_add_f32_e32 v2, v2, v13
	v_and_b32_e32 v13, 0xffff0000, v31
	v_and_b32_e32 v12, 0xffff0000, v29
	v_pk_mul_f32 v[12:13], v[36:37], v[12:13]
	v_mov_b32_e32 v16, v24
	v_add_f32_e32 v12, v19, v12
	v_add_f32_e32 v93, v12, v13
	v_lshlrev_b32_e32 v12, 16, v44
	v_lshlrev_b32_e32 v13, 16, v32
	v_mov_b32_e32 v17, v38
	v_pk_mul_f32 v[12:13], v[16:17], v[12:13]
	v_mov_b32_e32 v38, v25
	v_add_f32_e32 v12, v42, v12
	v_add_f32_e32 v95, v12, v13
	v_and_b32_e32 v13, 0xffff0000, v32
	v_and_b32_e32 v12, 0xffff0000, v44
	v_pk_mul_f32 v[12:13], v[38:39], v[12:13]
	v_mov_b32_e32 v16, v26
	v_add_f32_e32 v12, v43, v12
	v_add_f32_e32 v140, v12, v13
	v_lshlrev_b32_e32 v12, 16, v45
	v_lshlrev_b32_e32 v13, 16, v33
	v_mov_b32_e32 v17, v40
	v_pk_mul_f32 v[12:13], v[16:17], v[12:13]
	v_mov_b32_e32 v40, v27
	v_add_f32_e32 v12, v14, v12
	v_add_f32_e32 v141, v12, v13
	v_and_b32_e32 v13, 0xffff0000, v33
	v_and_b32_e32 v12, 0xffff0000, v45
	v_pk_mul_f32 v[12:13], v[40:41], v[12:13]
	v_add_u32_e32 v24, v28, v120
	v_add_f32_e32 v12, v15, v12
	v_add_f32_e32 v142, v12, v13
	v_cvt_pk_bf16_f32 v12, v0, v1
	v_cvt_pk_bf16_f32 v13, v2, v93
	v_cvt_pk_bf16_f32 v14, v95, v140
	v_cvt_pk_bf16_f32 v15, v141, v142
	ds_read_b128 v[20:23], v115 offset:2176
	ds_read_b128 v[16:19], v115 offset:2192
	ds_read_b128 v[24:27], v24 offset:45056
	s_waitcnt lgkmcnt(0)
	v_cndmask_b32_e32 v29, 0, v24, vcc
	v_cndmask_b32_e32 v34, 0, v25, vcc
	v_cndmask_b32_e32 v35, 0, v26, vcc
	v_cndmask_b32_e32 v36, 0, v27, vcc
	ds_read_b128 v[24:27], v115 offset:128
	ds_read_b128 v[30:33], v115 offset:144
	v_lshlrev_b32_e32 v37, 16, v29
	s_waitcnt lgkmcnt(0)
	v_fma_f32 v46, v24, v37, v20
	v_and_b32_e32 v20, 0xffff0000, v29
	v_fma_f32 v29, v25, v20, v21
	v_lshlrev_b32_e32 v20, 16, v34
	v_fma_f32 v22, v26, v20, v22
	v_and_b32_e32 v20, 0xffff0000, v34
	v_fmac_f32_e32 v23, v27, v20
	v_lshlrev_b32_e32 v20, 16, v35
	v_fma_f32 v47, v30, v20, v16
	v_and_b32_e32 v16, 0xffff0000, v35
	v_fma_f32 v48, v31, v16, v17
	v_lshlrev_b32_e32 v16, 16, v36
	v_fma_f32 v18, v32, v16, v18
	v_and_b32_e32 v16, 0xffff0000, v36
	v_fmac_f32_e32 v19, v33, v16
	v_add_u32_e32 v16, v28, v121
	ds_read_b128 v[24:27], v16 offset:45312
	s_waitcnt lgkmcnt(0)
	v_cndmask_b32_e64 v16, 0, v24, s[46:47]
	v_cndmask_b32_e64 v17, 0, v25, s[46:47]
	v_cndmask_b32_e64 v20, 0, v26, s[46:47]
	v_cndmask_b32_e64 v21, 0, v27, s[46:47]
	ds_read_b128 v[24:27], v115 offset:640
	ds_read_b128 v[30:33], v115 offset:656
	v_lshlrev_b32_e32 v34, 16, v16
	v_and_b32_e32 v16, 0xffff0000, v16
	s_waitcnt lgkmcnt(0)
; __device__ __forceinline__ unsigned cvt_pk_bf16(float lo, float hi) { unsigned r; asm volatile("v_cvt_pk_bf16_f32 %0, %1, %2" : "=v"(r) : "v"(lo), "v"(hi)); return r; }
; __device__ __forceinline__ float bf_lo(unsigned w) { return __uint_as_float(w << 16); }
; __device__ __forceinline__ float bf_hi(unsigned w) { return __uint_as_float(w & 0xffff0000u); }
; #define LAS __attribute__((address_space(3)))
; __device__ __forceinline__ void lru_item(const Frame& F, const bf16* XR, bf16* XGYL, const float* conv_w, const float* conv_b, const float* wa, const float* ba, const float* wx, const float* bx, const float* lam, int b, int hh, int j2) {
;     ...
;         for (int ks = 0; ks < 4; ++ks) { const int cl = 32 * ks + 8 * g; float a8[8];
;             { const f32x4 b0 = *(const LAS f32x4*)(tab + 512 + cl), b1 = *(const LAS f32x4*)(tab + 512 + cl + 4); a8[0] = b0[0]; a8[1] = b0[1]; a8[2] = b0[2]; a8[3] = b0[3]; a8[4] = b1[0]; a8[5] = b1[1]; a8[6] = b1[2]; a8[7] = b1[3]; }
; #pragma unroll
;             for (int k = 0; k < 4; ++k) { const int rr = 16 * w + tl + k; v4u xq = *(const LAS v4u*)(xb + k * 256 + (((4 * ks + g) ^ (rr & 15)) << 4));
;                 const bool inb = (chunk > 0) || (rr >= 3); xq.x = inb ? xq.x : 0u; xq.y = inb ? xq.y : 0u; xq.z = inb ? xq.z : 0u; xq.w = inb ? xq.w : 0u;
;                 const f32x4 w0 = *(const LAS f32x4*)(tab + k * 128 + cl), w1 = *(const LAS f32x4*)(tab + k * 128 + cl + 4);
;                 a8[0] += w0[0] * pg8::bf_lo(xq.x); a8[1] += w0[1] * pg8::bf_hi(xq.x); a8[2] += w0[2] * pg8::bf_lo(xq.y); a8[3] += w0[3] * pg8::bf_hi(xq.y);
;                 a8[4] += w1[0] * pg8::bf_lo(xq.z); a8[5] += w1[1] * pg8::bf_hi(xq.z); a8[6] += w1[2] * pg8::bf_lo(xq.w); a8[7] += w1[3] * pg8::bf_hi(xq.w); }
;             v4u u4; u4.x = pg8::cvt_pk_bf16(a8[0], a8[1]); u4.y = pg8::cvt_pk_bf16(a8[2], a8[3]); u4.z = pg8::cvt_pk_bf16(a8[4], a8[5]); u4.w = pg8::cvt_pk_bf16(a8[6], a8[7]); bfr[ks] = __builtin_bit_cast(bf16x8, u4);
	v_fmac_f32_e32 v29, v25, v16
	v_lshlrev_b32_e32 v16, 16, v17
	v_fmac_f32_e32 v22, v26, v16
	v_and_b32_e32 v16, 0xffff0000, v17
	v_fmac_f32_e32 v23, v27, v16
	v_lshlrev_b32_e32 v16, 16, v20
	v_fmac_f32_e32 v47, v30, v16
	v_and_b32_e32 v16, 0xffff0000, v20
	v_fmac_f32_e32 v48, v31, v16
	v_lshlrev_b32_e32 v16, 16, v21
	v_fmac_f32_e32 v18, v32, v16
	v_and_b32_e32 v16, 0xffff0000, v21
	v_fmac_f32_e32 v19, v33, v16
	v_add_u32_e32 v16, v28, v122
	v_fmac_f32_e32 v46, v24, v34
	ds_read_b128 v[24:27], v16 offset:45568
	v_add_u32_e32 v16, v28, v123
	s_waitcnt lgkmcnt(0)
	v_cndmask_b32_e64 v49, v24, 0, s[44:45]
	v_cndmask_b32_e64 v50, v25, 0, s[44:45]
	v_cndmask_b32_e64 v51, v26, 0, s[44:45]
	v_cndmask_b32_e64 v52, v27, 0, s[44:45]
	ds_read_b128 v[24:27], v115 offset:1152
	ds_read_b128 v[30:33], v115 offset:1168
	ds_read_b128 v[34:37], v16 offset:45824
	ds_read_b128 v[38:41], v115 offset:1664
	ds_read_b128 v[42:45], v115 offset:1680
	v_lshlrev_b32_e32 v16, 16, v49
	s_waitcnt lgkmcnt(0)
	v_lshlrev_b32_e32 v17, 16, v34
	v_mov_b32_e32 v20, v24
	v_mov_b32_e32 v21, v38
	v_pk_mul_f32 v[16:17], v[20:21], v[16:17]
	v_mov_b32_e32 v38, v25
	v_add_f32_e32 v16, v46, v16
	v_add_f32_e32 v144, v16, v17
	v_and_b32_e32 v17, 0xffff0000, v34
	v_and_b32_e32 v16, 0xffff0000, v49
	v_pk_mul_f32 v[16:17], v[38:39], v[16:17]
	v_mov_b32_e32 v20, v26
	v_add_f32_e32 v16, v29, v16
	v_add_f32_e32 v145, v16, v17
	v_lshlrev_b32_e32 v16, 16, v50
	v_lshlrev_b32_e32 v17, 16, v35
	v_mov_b32_e32 v21, v40
	v_pk_mul_f32 v[16:17], v[20:21], v[16:17]
	v_mov_b32_e32 v40, v27
	v_add_f32_e32 v16, v22, v16
	v_add_f32_e32 v146, v16, v17
	v_and_b32_e32 v17, 0xffff0000, v35
	v_and_b32_e32 v16, 0xffff0000, v50
	v_pk_mul_f32 v[16:17], v[40:41], v[16:17]
	v_mov_b32_e32 v20, v30
	v_add_f32_e32 v16, v23, v16
	v_add_f32_e32 v147, v16, v17
	v_lshlrev_b32_e32 v16, 16, v51
	v_lshlrev_b32_e32 v17, 16, v36
	v_mov_b32_e32 v21, v42
	v_pk_mul_f32 v[16:17], v[20:21], v[16:17]
	v_mov_b32_e32 v42, v31
	v_add_f32_e32 v16, v47, v16
	v_add_f32_e32 v148, v16, v17
	v_and_b32_e32 v17, 0xffff0000, v36
	v_and_b32_e32 v16, 0xffff0000, v51
	v_pk_mul_f32 v[16:17], v[42:43], v[16:17]
	v_mov_b32_e32 v20, v32
	v_add_f32_e32 v16, v48, v16
	v_add_f32_e32 v149, v16, v17
	v_lshlrev_b32_e32 v16, 16, v52
	v_lshlrev_b32_e32 v17, 16, v37
	v_mov_b32_e32 v21, v44
	v_pk_mul_f32 v[16:17], v[20:21], v[16:17]
	v_mov_b32_e32 v44, v33
	v_add_f32_e32 v16, v18, v16
	v_add_f32_e32 v150, v16, v17
	v_and_b32_e32 v17, 0xffff0000, v37
	v_and_b32_e32 v16, 0xffff0000, v52
	v_pk_mul_f32 v[16:17], v[44:45], v[16:17]
	v_add_u32_e32 v29, v28, v124
	v_add_f32_e32 v16, v19, v16
	v_add_f32_e32 v143, v16, v17
	v_cvt_pk_bf16_f32 v16, v144, v145
	v_cvt_pk_bf16_f32 v17, v146, v147
	v_cvt_pk_bf16_f32 v18, v148, v149
	v_cvt_pk_bf16_f32 v19, v150, v143
	ds_read_b128 v[24:27], v115 offset:2304
	ds_read_b128 v[20:23], v115 offset:2320
	ds_read_b128 v[30:33], v29 offset:45056
	s_waitcnt lgkmcnt(0)
	v_cndmask_b32_e32 v29, 0, v30, vcc
	v_cndmask_b32_e32 v38, 0, v31, vcc
	v_cndmask_b32_e32 v39, 0, v32, vcc
	v_cndmask_b32_e32 v40, 0, v33, vcc
	ds_read_b128 v[30:33], v115 offset:256
	ds_read_b128 v[34:37], v115 offset:272
	v_lshlrev_b32_e32 v41, 16, v29
	s_waitcnt lgkmcnt(0)
	v_fma_f32 v50, v30, v41, v24
	v_and_b32_e32 v24, 0xffff0000, v29
	v_fma_f32 v29, v31, v24, v25
	v_lshlrev_b32_e32 v24, 16, v38
	v_fma_f32 v26, v32, v24, v26
	v_and_b32_e32 v24, 0xffff0000, v38
	v_fmac_f32_e32 v27, v33, v24
	v_lshlrev_b32_e32 v24, 16, v39
	v_fma_f32 v51, v34, v24, v20
	v_and_b32_e32 v20, 0xffff0000, v39
	v_fma_f32 v52, v35, v20, v21
	v_lshlrev_b32_e32 v20, 16, v40
	v_fma_f32 v22, v36, v20, v22
	v_and_b32_e32 v20, 0xffff0000, v40
	v_fmac_f32_e32 v23, v37, v20
	v_add_u32_e32 v20, v28, v125
	ds_read_b128 v[30:33], v20 offset:45312
	s_waitcnt lgkmcnt(0)
	v_cndmask_b32_e64 v20, 0, v30, s[46:47]
	v_cndmask_b32_e64 v21, 0, v31, s[46:47]
	v_cndmask_b32_e64 v24, 0, v32, s[46:47]
	v_cndmask_b32_e64 v25, 0, v33, s[46:47]
	ds_read_b128 v[30:33], v115 offset:768
	ds_read_b128 v[34:37], v115 offset:784
	v_lshlrev_b32_e32 v38, 16, v20
	v_and_b32_e32 v20, 0xffff0000, v20
	s_waitcnt lgkmcnt(0)
	v_fmac_f32_e32 v29, v31, v20
	v_lshlrev_b32_e32 v20, 16, v21
	v_fmac_f32_e32 v26, v32, v20
	v_and_b32_e32 v20, 0xffff0000, v21
	v_fmac_f32_e32 v27, v33, v20
	v_lshlrev_b32_e32 v20, 16, v24
	v_fmac_f32_e32 v51, v34, v20
	v_and_b32_e32 v20, 0xffff0000, v24
	v_fmac_f32_e32 v52, v35, v20
	v_lshlrev_b32_e32 v20, 16, v25
	v_fmac_f32_e32 v22, v36, v20
	v_and_b32_e32 v20, 0xffff0000, v25
	v_fmac_f32_e32 v23, v37, v20
	v_add_u32_e32 v20, v28, v126
	v_fmac_f32_e32 v50, v30, v38
	ds_read_b128 v[30:33], v20 offset:45568
	v_add_u32_e32 v20, v28, v127
	s_waitcnt lgkmcnt(0)
	v_cndmask_b32_e64 v53, v30, 0, s[44:45]
	v_cndmask_b32_e64 v54, v31, 0, s[44:45]
	v_cndmask_b32_e64 v55, v32, 0, s[44:45]
	v_cndmask_b32_e64 v56, v33, 0, s[44:45]
	ds_read_b128 v[30:33], v115 offset:1280
	ds_read_b128 v[34:37], v115 offset:1296
	ds_read_b128 v[38:41], v20 offset:45824
	ds_read_b128 v[42:45], v115 offset:1792
	ds_read_b128 v[46:49], v115 offset:1808
	v_lshlrev_b32_e32 v20, 16, v53
	s_waitcnt lgkmcnt(0)
; __device__ __forceinline__ unsigned cvt_pk_bf16(float lo, float hi) { unsigned r; asm volatile("v_cvt_pk_bf16_f32 %0, %1, %2" : "=v"(r) : "v"(lo), "v"(hi)); return r; }
; __device__ __forceinline__ float bf_lo(unsigned w) { return __uint_as_float(w << 16); }
; #define LAS __attribute__((address_space(3)))
; __device__ __forceinline__ void lru_item(const Frame& F, const bf16* XR, bf16* XGYL, const float* conv_w, const float* conv_b, const float* wa, const float* ba, const float* wx, const float* bx, const float* lam, int b, int hh, int j2) {
;     ...
;         for (int ks = 0; ks < 4; ++ks) { const int cl = 32 * ks + 8 * g; float a8[8];
;             { const f32x4 b0 = *(const LAS f32x4*)(tab + 512 + cl), b1 = *(const LAS f32x4*)(tab + 512 + cl + 4); a8[0] = b0[0]; a8[1] = b0[1]; a8[2] = b0[2]; a8[3] = b0[3]; a8[4] = b1[0]; a8[5] = b1[1]; a8[6] = b1[2]; a8[7] = b1[3]; }
; #pragma unroll
;             for (int k = 0; k < 4; ++k) { const int rr = 16 * w + tl + k; v4u xq = *(const LAS v4u*)(xb + k * 256 + (((4 * ks + g) ^ (rr & 15)) << 4));
;                 const bool inb = (chunk > 0) || (rr >= 3); xq.x = inb ? xq.x : 0u; xq.y = inb ? xq.y : 0u; xq.z = inb ? xq.z : 0u; xq.w = inb ? xq.w : 0u;
;                 const f32x4 w0 = *(const LAS f32x4*)(tab + k * 128 + cl), w1 = *(const LAS f32x4*)(tab + k * 128 + cl + 4);
;                 a8[0] += w0[0] * pg8::bf_lo(xq.x); a8[1] += w0[1] * pg8::bf_hi(xq.x); a8[2] += w0[2] * pg8::bf_lo(xq.y); a8[3] += w0[3] * pg8::bf_hi(xq.y);
;                 a8[4] += w1[0] * pg8::bf_lo(xq.z); a8[5] += w1[1] * pg8::bf_hi(xq.z); a8[6] += w1[2] * pg8::bf_lo(xq.w); a8[7] += w1[3] * pg8::bf_hi(xq.w); }
;             v4u u4; u4.x = pg8::cvt_pk_bf16(a8[0], a8[1]); u4.y = pg8::cvt_pk_bf16(a8[2], a8[3]); u4.z = pg8::cvt_pk_bf16(a8[4], a8[5]); u4.w = pg8::cvt_pk_bf16(a8[6], a8[7]); bfr[ks] = __builtin_bit_cast(bf16x8, u4);
; #pragma unroll
;             for (int i = 0; i < 8; ++i) { xcf[i] = (ks == 2 * j2) ? a8[i] : xcf[i]; xcf[8 + i] = (ks == 2 * j2 + 1) ? a8[i] : xcf[8 + i]; } }
;         f32x4 pa[8];
; #pragma unroll
;         for (int T = 0; T < 8; ++T) { pa[T] = (f32x4){0.f, 0.f, 0.f, 0.f};
; #pragma unroll
;             for (int ks = 0; ks < 4; ++ks) { const bf16x8 wfr = *(const LAS bf16x8*)(wfl + ((T * 4 + ks) * 64 + lane) * 16); pa[T] = __builtin_amdgcn_mfma_f32_16x16x32_bf16(wfr, bfr[ks], pa[T], 0, 0, 0); } }
	v_lshlrev_b32_e32 v21, 16, v38
	v_mov_b32_e32 v24, v30
	v_mov_b32_e32 v25, v42
	v_pk_mul_f32 v[20:21], v[24:25], v[20:21]
	v_mov_b32_e32 v42, v31
	v_add_f32_e32 v20, v50, v20
	v_add_f32_e32 v151, v20, v21
	v_and_b32_e32 v21, 0xffff0000, v38
	v_and_b32_e32 v20, 0xffff0000, v53
	v_pk_mul_f32 v[20:21], v[42:43], v[20:21]
	v_mov_b32_e32 v24, v32
	v_add_f32_e32 v20, v29, v20
	v_add_f32_e32 v152, v20, v21
	v_lshlrev_b32_e32 v20, 16, v54
	v_lshlrev_b32_e32 v21, 16, v39
	v_mov_b32_e32 v25, v44
	v_pk_mul_f32 v[20:21], v[24:25], v[20:21]
	v_mov_b32_e32 v44, v33
	v_add_f32_e32 v20, v26, v20
	v_add_f32_e32 v153, v20, v21
	v_and_b32_e32 v21, 0xffff0000, v39
	v_and_b32_e32 v20, 0xffff0000, v54
	v_pk_mul_f32 v[20:21], v[44:45], v[20:21]
	v_mov_b32_e32 v24, v34
	v_add_f32_e32 v20, v27, v20
	v_add_f32_e32 v154, v20, v21
	v_lshlrev_b32_e32 v20, 16, v55
	v_lshlrev_b32_e32 v21, 16, v40
	v_mov_b32_e32 v25, v46
	v_pk_mul_f32 v[20:21], v[24:25], v[20:21]
	v_mov_b32_e32 v46, v35
	v_add_f32_e32 v20, v51, v20
	v_add_f32_e32 v155, v20, v21
	v_and_b32_e32 v21, 0xffff0000, v40
	v_and_b32_e32 v20, 0xffff0000, v55
	v_pk_mul_f32 v[20:21], v[46:47], v[20:21]
	v_mov_b32_e32 v24, v36
	v_add_f32_e32 v20, v52, v20
	v_add_f32_e32 v158, v20, v21
	v_lshlrev_b32_e32 v20, 16, v56
	v_lshlrev_b32_e32 v21, 16, v41
	v_mov_b32_e32 v25, v48
	v_pk_mul_f32 v[20:21], v[24:25], v[20:21]
	v_mov_b32_e32 v48, v37
	v_add_f32_e32 v20, v22, v20
	v_add_f32_e32 v159, v20, v21
	v_and_b32_e32 v21, 0xffff0000, v41
	v_and_b32_e32 v20, 0xffff0000, v56
	v_pk_mul_f32 v[20:21], v[48:49], v[20:21]
	v_add_u32_e32 v29, v28, v128
	v_add_f32_e32 v20, v23, v20
	v_add_f32_e32 v160, v20, v21
	v_cvt_pk_bf16_f32 v36, v151, v152
	v_cvt_pk_bf16_f32 v37, v153, v154
	v_cvt_pk_bf16_f32 v38, v155, v158
	v_cvt_pk_bf16_f32 v39, v159, v160
	ds_read_b128 v[24:27], v115 offset:2432
	ds_read_b128 v[20:23], v115 offset:2448
	ds_read_b128 v[30:33], v29 offset:45056
	s_waitcnt lgkmcnt(0)
	v_cndmask_b32_e32 v29, 0, v30, vcc
	v_cndmask_b32_e32 v34, 0, v31, vcc
	v_cndmask_b32_e32 v35, 0, v32, vcc
	v_cndmask_b32_e32 v44, 0, v33, vcc
	ds_read_b128 v[30:33], v115 offset:384
	ds_read_b128 v[40:43], v115 offset:400
	v_lshlrev_b32_e32 v45, 16, v29
	s_waitcnt lgkmcnt(0)
	v_fma_f32 v56, v30, v45, v24
	v_and_b32_e32 v24, 0xffff0000, v29
	v_fma_f32 v29, v31, v24, v25
	v_lshlrev_b32_e32 v24, 16, v34
	v_fma_f32 v26, v32, v24, v26
	v_and_b32_e32 v24, 0xffff0000, v34
	v_fmac_f32_e32 v27, v33, v24
	v_lshlrev_b32_e32 v24, 16, v35
	v_fma_f32 v34, v40, v24, v20
	v_and_b32_e32 v20, 0xffff0000, v35
	v_fma_f32 v35, v41, v20, v21
	v_lshlrev_b32_e32 v20, 16, v44
	v_fma_f32 v22, v42, v20, v22
	v_and_b32_e32 v20, 0xffff0000, v44
	v_fmac_f32_e32 v23, v43, v20
	v_add_u32_e32 v20, v28, v129
	ds_read_b128 v[30:33], v20 offset:45312
	s_waitcnt lgkmcnt(0)
	v_cndmask_b32_e64 v20, 0, v30, s[46:47]
	v_cndmask_b32_e64 v21, 0, v31, s[46:47]
	v_cndmask_b32_e64 v24, 0, v32, s[46:47]
	v_cndmask_b32_e64 v25, 0, v33, s[46:47]
	ds_read_b128 v[30:33], v115 offset:896
	ds_read_b128 v[40:43], v115 offset:912
	v_lshlrev_b32_e32 v44, 16, v20
	v_and_b32_e32 v20, 0xffff0000, v20
	s_waitcnt lgkmcnt(0)
	v_fmac_f32_e32 v29, v31, v20
	v_lshlrev_b32_e32 v20, 16, v21
	v_fmac_f32_e32 v26, v32, v20
	v_and_b32_e32 v20, 0xffff0000, v21
	v_fmac_f32_e32 v27, v33, v20
	v_lshlrev_b32_e32 v20, 16, v24
	v_fmac_f32_e32 v34, v40, v20
	v_and_b32_e32 v20, 0xffff0000, v24
	v_fmac_f32_e32 v35, v41, v20
	v_lshlrev_b32_e32 v20, 16, v25
	v_fmac_f32_e32 v22, v42, v20
	v_and_b32_e32 v20, 0xffff0000, v25
	v_fmac_f32_e32 v23, v43, v20
	v_add_u32_e32 v20, v28, v130
	v_fmac_f32_e32 v56, v30, v44
	ds_read_b128 v[30:33], v20 offset:45568
	v_add_u32_e32 v20, v28, v131
	s_waitcnt lgkmcnt(0)
	v_cndmask_b32_e64 v57, v30, 0, s[44:45]
	v_cndmask_b32_e64 v58, v31, 0, s[44:45]
	v_cndmask_b32_e64 v59, v32, 0, s[44:45]
	v_cndmask_b32_e64 v60, v33, 0, s[44:45]
	ds_read_b128 v[30:33], v115 offset:1408
	ds_read_b128 v[40:43], v115 offset:1424
	ds_read_b128 v[44:47], v20 offset:45824
	ds_read_b128 v[48:51], v115 offset:1920
	ds_read_b128 v[52:55], v115 offset:1936
	v_lshlrev_b32_e32 v20, 16, v57
	s_waitcnt lgkmcnt(0)
	v_lshlrev_b32_e32 v21, 16, v44
	v_mov_b32_e32 v24, v30
	v_mov_b32_e32 v25, v48
	v_pk_mul_f32 v[20:21], v[24:25], v[20:21]
	v_mov_b32_e32 v48, v31
	v_add_f32_e32 v20, v56, v20
	v_add_f32_e32 v162, v20, v21
	v_and_b32_e32 v21, 0xffff0000, v44
	v_and_b32_e32 v20, 0xffff0000, v57
	v_pk_mul_f32 v[20:21], v[48:49], v[20:21]
	v_mov_b32_e32 v24, v32
	v_add_f32_e32 v20, v29, v20
	v_add_f32_e32 v163, v20, v21
	v_lshlrev_b32_e32 v20, 16, v58
	v_lshlrev_b32_e32 v21, 16, v45
	v_mov_b32_e32 v25, v50
	v_pk_mul_f32 v[20:21], v[24:25], v[20:21]
	v_mov_b32_e32 v50, v33
	v_add_f32_e32 v20, v26, v20
	v_add_f32_e32 v164, v20, v21
	v_and_b32_e32 v21, 0xffff0000, v45
	v_and_b32_e32 v20, 0xffff0000, v58
	v_pk_mul_f32 v[20:21], v[50:51], v[20:21]
	v_mov_b32_e32 v24, v40
	v_add_f32_e32 v20, v27, v20
	v_add_f32_e32 v165, v20, v21
	v_lshlrev_b32_e32 v20, 16, v59
	v_lshlrev_b32_e32 v21, 16, v46
	v_mov_b32_e32 v25, v52
	v_pk_mul_f32 v[20:21], v[24:25], v[20:21]
	v_mov_b32_e32 v52, v41
	v_add_f32_e32 v20, v34, v20
	v_add_f32_e32 v166, v20, v21
	v_and_b32_e32 v21, 0xffff0000, v46
	v_and_b32_e32 v20, 0xffff0000, v59
	v_pk_mul_f32 v[20:21], v[52:53], v[20:21]
	v_mov_b32_e32 v24, v42
	v_add_f32_e32 v20, v35, v20
	v_add_f32_e32 v167, v20, v21
	v_lshlrev_b32_e32 v20, 16, v60
	v_lshlrev_b32_e32 v21, 16, v47
	v_mov_b32_e32 v25, v54
	v_pk_mul_f32 v[20:21], v[24:25], v[20:21]
	v_mov_b32_e32 v54, v43
	v_add_f32_e32 v20, v22, v20
	v_add_f32_e32 v168, v20, v21
	v_and_b32_e32 v21, 0xffff0000, v47
	v_and_b32_e32 v20, 0xffff0000, v60
	v_pk_mul_f32 v[20:21], v[54:55], v[20:21]
	v_add_u32_e32 v60, 0, v108
	v_add_f32_e32 v20, v23, v20
	v_add_f32_e32 v161, v20, v21
	v_cvt_pk_bf16_f32 v52, v162, v163
	v_cvt_pk_bf16_f32 v53, v164, v165
	v_cvt_pk_bf16_f32 v54, v166, v167
	v_cvt_pk_bf16_f32 v55, v168, v161
	ds_read_b128 v[20:23], v60 offset:12288
	ds_read_b128 v[24:27], v60 offset:13312
	s_waitcnt lgkmcnt(0)
; __device__ __forceinline__ float fsigmoid(float x) { return __builtin_amdgcn_rcpf(1.0f + __builtin_amdgcn_exp2f(-1.4426950408889634f * x)); }
; #define LAS __attribute__((address_space(3)))
; __device__ __forceinline__ void lru_item(const Frame& F, const bf16* XR, bf16* XGYL, const float* conv_w, const float* conv_b, const float* wa, const float* ba, const float* wx, const float* bx, const float* lam, int b, int hh, int j2) {
;     ...
;         f32x4 pa[8];
; #pragma unroll
;         for (int T = 0; T < 8; ++T) { pa[T] = (f32x4){0.f, 0.f, 0.f, 0.f};
; #pragma unroll
;             for (int ks = 0; ks < 4; ++ks) { const bf16x8 wfr = *(const LAS bf16x8*)(wfl + ((T * 4 + ks) * 64 + lane) * 16); pa[T] = __builtin_amdgcn_mfma_f32_16x16x32_bf16(wfr, bfr[ks], pa[T], 0, 0, 0); } }
;         float av[16], uv[16];
; #pragma unroll
;         for (int s2 = 0; s2 < 2; ++s2) {
;             const f32x4 ba0 = *(const LAS f32x4*)(ctab + 32 * s2 + 8 * g), ba1 = *(const LAS f32x4*)(ctab + 32 * s2 + 8 * g + 4);
;             const f32x4 bx0 = *(const LAS f32x4*)(ctab + 64 + 32 * s2 + 8 * g), bx1 = *(const LAS f32x4*)(ctab + 64 + 32 * s2 + 8 * g + 4);
;             const f32x4 sp0 = *(const LAS f32x4*)(ctab + 128 + 32 * s2 + 8 * g), sp1 = *(const LAS f32x4*)(ctab + 128 + 32 * s2 + 8 * g + 4);
; #pragma unroll
;             for (int i = 0; i < 8; ++i) { const float bai = (i < 4) ? ba0[i & 3] : ba1[i & 3], bxi = (i < 4) ? bx0[i & 3] : bx1[i & 3], spi = (i < 4) ? sp0[i & 3] : sp1[i & 3];
;                 const float rp = pa[s2 * 2 + (i >> 2)][i & 3] + bai, xp = pa[4 + s2 * 2 + (i >> 2)][i & 3] + bxi;
;                 const float rr = pg8::fsigmoid(rp), ig = pg8::fsigmoid(xp), la = -spi * rr, x2 = 2.0f * la;
;                 const float a = __builtin_amdgcn_exp2f(LOG2E * la);
;                 const float em1 = (x2 > -0.3f) ? x2 * (1.0f + x2 * (0.5f + x2 * (0.16666667f + x2 * (0.041666668f + x2 * 0.0083333333f)))) : (a * a - 1.0f);
;                 av[8 * s2 + i] = a; uv[8 * s2 + i] = __builtin_amdgcn_sqrtf(-em1) * ig * xcf[8 * s2 + i]; } }
	v_mfma_f32_16x16x32_bf16 v[20:23], v[20:23], v[12:15], 0
	ds_read_b128 v[32:35], v60 offset:33792
	ds_read_b128 v[56:59], v60 offset:37888
	v_mfma_f32_16x16x32_bf16 v[20:23], v[24:27], v[16:19], v[20:23]
	ds_read_b128 v[24:27], v60 offset:14336
	s_waitcnt lgkmcnt(0)
	v_mfma_f32_16x16x32_bf16 v[20:23], v[24:27], v[36:39], v[20:23]
	ds_read_b128 v[24:27], v60 offset:15360
	s_waitcnt lgkmcnt(0)
	v_mfma_f32_16x16x32_bf16 v[48:51], v[24:27], v[52:55], v[20:23]
	s_nop 4
	ds_read_b128 v[20:23], v60 offset:16384
	ds_read_b128 v[24:27], v60 offset:17408
	s_waitcnt lgkmcnt(0)
	v_mfma_f32_16x16x32_bf16 v[20:23], v[20:23], v[12:15], 0
	v_mfma_f32_16x16x32_bf16 v[20:23], v[24:27], v[16:19], v[20:23]
	ds_read_b128 v[24:27], v60 offset:18432
	s_waitcnt lgkmcnt(0)
	v_mfma_f32_16x16x32_bf16 v[20:23], v[24:27], v[36:39], v[20:23]
	ds_read_b128 v[24:27], v60 offset:19456
	s_waitcnt lgkmcnt(0)
	v_mfma_f32_16x16x32_bf16 v[44:47], v[24:27], v[52:55], v[20:23]
	s_nop 4
	ds_read_b128 v[20:23], v60 offset:20480
	ds_read_b128 v[24:27], v60 offset:21504
	s_waitcnt lgkmcnt(0)
	v_mfma_f32_16x16x32_bf16 v[20:23], v[20:23], v[12:15], 0
	v_mfma_f32_16x16x32_bf16 v[20:23], v[24:27], v[16:19], v[20:23]
	ds_read_b128 v[24:27], v60 offset:22528
	s_waitcnt lgkmcnt(0)
	v_mfma_f32_16x16x32_bf16 v[20:23], v[24:27], v[36:39], v[20:23]
	ds_read_b128 v[24:27], v60 offset:23552
	s_waitcnt lgkmcnt(0)
	v_mfma_f32_16x16x32_bf16 v[40:43], v[24:27], v[52:55], v[20:23]
	s_nop 4
	ds_read_b128 v[20:23], v60 offset:24576
	ds_read_b128 v[24:27], v60 offset:25600
	s_waitcnt lgkmcnt(0)
	v_mfma_f32_16x16x32_bf16 v[20:23], v[20:23], v[12:15], 0
	v_mfma_f32_16x16x32_bf16 v[20:23], v[24:27], v[16:19], v[20:23]
	ds_read_b128 v[24:27], v60 offset:26624
	s_waitcnt lgkmcnt(0)
	v_mfma_f32_16x16x32_bf16 v[20:23], v[24:27], v[36:39], v[20:23]
	ds_read_b128 v[24:27], v60 offset:27648
	s_waitcnt lgkmcnt(0)
	v_mfma_f32_16x16x32_bf16 v[28:31], v[24:27], v[52:55], v[20:23]
	s_nop 4
	ds_read_b128 v[20:23], v60 offset:28672
	ds_read_b128 v[24:27], v60 offset:29696
	s_waitcnt lgkmcnt(0)
	v_mfma_f32_16x16x32_bf16 v[20:23], v[20:23], v[12:15], 0
	v_mfma_f32_16x16x32_bf16 v[20:23], v[24:27], v[16:19], v[20:23]
	ds_read_b128 v[24:27], v60 offset:30720
	s_waitcnt lgkmcnt(0)
	v_mfma_f32_16x16x32_bf16 v[20:23], v[24:27], v[36:39], v[20:23]
	ds_read_b128 v[24:27], v60 offset:31744
	s_waitcnt lgkmcnt(0)
	v_mfma_f32_16x16x32_bf16 v[20:23], v[24:27], v[52:55], v[20:23]
	ds_read_b128 v[24:27], v60 offset:32768
	s_waitcnt lgkmcnt(0)
	v_mfma_f32_16x16x32_bf16 v[24:27], v[24:27], v[12:15], 0
	v_mfma_f32_16x16x32_bf16 v[24:27], v[32:35], v[16:19], v[24:27]
	ds_read_b128 v[32:35], v60 offset:34816
	s_waitcnt lgkmcnt(0)
	v_mfma_f32_16x16x32_bf16 v[24:27], v[32:35], v[36:39], v[24:27]
	ds_read_b128 v[32:35], v60 offset:35840
	s_waitcnt lgkmcnt(0)
	v_mfma_f32_16x16x32_bf16 v[24:27], v[32:35], v[52:55], v[24:27]
	ds_read_b128 v[32:35], v60 offset:36864
	s_waitcnt lgkmcnt(0)
	v_mfma_f32_16x16x32_bf16 v[32:35], v[32:35], v[12:15], 0
	v_mfma_f32_16x16x32_bf16 v[32:35], v[56:59], v[16:19], v[32:35]
	ds_read_b128 v[56:59], v60 offset:38912
	s_waitcnt lgkmcnt(0)
	v_mfma_f32_16x16x32_bf16 v[32:35], v[56:59], v[36:39], v[32:35]
	ds_read_b128 v[56:59], v60 offset:39936
	s_waitcnt lgkmcnt(0)
	v_mfma_f32_16x16x32_bf16 v[32:35], v[56:59], v[52:55], v[32:35]
	ds_read_b128 v[56:59], v60 offset:40960
	s_waitcnt lgkmcnt(0)
	v_mfma_f32_16x16x32_bf16 v[12:15], v[56:59], v[12:15], 0
	ds_read_b128 v[56:59], v60 offset:41984
	s_waitcnt lgkmcnt(0)
	v_mfma_f32_16x16x32_bf16 v[12:15], v[56:59], v[16:19], v[12:15]
	ds_read_b128 v[16:19], v60 offset:43008
	s_waitcnt lgkmcnt(0)
	v_mfma_f32_16x16x32_bf16 v[12:15], v[16:19], v[36:39], v[12:15]
	ds_read_b128 v[16:19], v60 offset:44032
	s_waitcnt lgkmcnt(0)
	v_mfma_f32_16x16x32_bf16 v[16:19], v[16:19], v[52:55], v[12:15]
	ds_read_b128 v[60:63], v115 offset:2560
	ds_read_b128 v[56:59], v115 offset:2576
	s_nop 2
	ds_read_b128 v[12:15], v115 offset:2816
	ds_read_b128 v[36:39], v115 offset:2832
	ds_read_b128 v[64:67], v115 offset:3072
	ds_read_b128 v[52:55], v115 offset:3088
	s_waitcnt lgkmcnt(0)
	v_add_f32_e32 v48, v48, v60
	v_mul_f32_e32 v48, 0xbfb8aa3b, v48
	v_exp_f32_e32 v48, v48
	s_nop 0
	v_add_f32_e32 v48, 1.0, v48
	v_rcp_f32_e32 v48, v48
	s_nop 0
	v_mul_f32_e64 v60, v48, -v64
	v_add_f32_e32 v48, v60, v60
	v_mul_f32_e32 v60, 0x3fb8aa3b, v60
	v_exp_f32_e32 v169, v60
	v_cmp_nlt_f32_e32 vcc, s92, v48
	s_and_saveexec_b64 s[2:3], vcc
	s_xor_b64 s[2:3], exec, s[2:3]
	v_fma_f32 v171, v169, v169, -1.0
	s_andn2_saveexec_b64 s[2:3], s[2:3]
	v_fmamk_f32 v60, v48, 0x3c088888, v136
	v_fmaak_f32 v60, v48, v60, 0x3e2aaaab
	v_fma_f32 v60, v48, v60, 0.5
	v_fma_f32 v60, v48, v60, 1.0
	v_mul_f32_e32 v171, v48, v60
	s_or_b64 exec, exec, s[2:3]
	v_add_f32_e32 v48, v49, v61
	v_mul_f32_e32 v48, 0xbfb8aa3b, v48
	v_exp_f32_e32 v48, v48
	s_nop 0
	v_add_f32_e32 v48, 1.0, v48
	v_rcp_f32_e32 v48, v48
	s_nop 0
	v_mul_f32_e64 v48, v48, -v65
	v_mul_f32_e32 v49, 0x3fb8aa3b, v48
	v_exp_f32_e32 v170, v49
	v_add_f32_e32 v48, v48, v48
	v_cmp_nlt_f32_e32 vcc, s92, v48
	s_and_saveexec_b64 s[2:3], vcc
	s_xor_b64 s[2:3], exec, s[2:3]
	v_fma_f32 v176, v170, v170, -1.0
	s_andn2_saveexec_b64 s[2:3], s[2:3]
	v_fmamk_f32 v49, v48, 0x3c088888, v136
	v_fmaak_f32 v49, v48, v49, 0x3e2aaaab
	v_fma_f32 v49, v48, v49, 0.5
	v_fma_f32 v49, v48, v49, 1.0
	v_mul_f32_e32 v176, v48, v49
	s_or_b64 exec, exec, s[2:3]
	v_add_f32_e32 v48, v50, v62
	v_mul_f32_e32 v48, 0xbfb8aa3b, v48
	v_exp_f32_e32 v48, v48
	s_nop 0
	v_add_f32_e32 v48, 1.0, v48
	v_rcp_f32_e32 v48, v48
	s_nop 0
	v_mul_f32_e64 v48, v48, -v66
	v_mul_f32_e32 v49, 0x3fb8aa3b, v48
	v_exp_f32_e32 v172, v49
; __device__ __forceinline__ float fsigmoid(float x) { return __builtin_amdgcn_rcpf(1.0f + __builtin_amdgcn_exp2f(-1.4426950408889634f * x)); }
; #define LAS __attribute__((address_space(3)))
; __device__ __forceinline__ void lru_item(const Frame& F, const bf16* XR, bf16* XGYL, const float* conv_w, const float* conv_b, const float* wa, const float* ba, const float* wx, const float* bx, const float* lam, int b, int hh, int j2) {
;     ...
;         for (int s2 = 0; s2 < 2; ++s2) {
;             const f32x4 ba0 = *(const LAS f32x4*)(ctab + 32 * s2 + 8 * g), ba1 = *(const LAS f32x4*)(ctab + 32 * s2 + 8 * g + 4);
;             const f32x4 bx0 = *(const LAS f32x4*)(ctab + 64 + 32 * s2 + 8 * g), bx1 = *(const LAS f32x4*)(ctab + 64 + 32 * s2 + 8 * g + 4);
;             const f32x4 sp0 = *(const LAS f32x4*)(ctab + 128 + 32 * s2 + 8 * g), sp1 = *(const LAS f32x4*)(ctab + 128 + 32 * s2 + 8 * g + 4);
; #pragma unroll
;             for (int i = 0; i < 8; ++i) { const float bai = (i < 4) ? ba0[i & 3] : ba1[i & 3], bxi = (i < 4) ? bx0[i & 3] : bx1[i & 3], spi = (i < 4) ? sp0[i & 3] : sp1[i & 3];
;                 const float rp = pa[s2 * 2 + (i >> 2)][i & 3] + bai, xp = pa[4 + s2 * 2 + (i >> 2)][i & 3] + bxi;
;                 const float rr = pg8::fsigmoid(rp), ig = pg8::fsigmoid(xp), la = -spi * rr, x2 = 2.0f * la;
;                 const float a = __builtin_amdgcn_exp2f(LOG2E * la);
;                 const float em1 = (x2 > -0.3f) ? x2 * (1.0f + x2 * (0.5f + x2 * (0.16666667f + x2 * (0.041666668f + x2 * 0.0083333333f)))) : (a * a - 1.0f);
;                 av[8 * s2 + i] = a; uv[8 * s2 + i] = __builtin_amdgcn_sqrtf(-em1) * ig * xcf[8 * s2 + i]; } }
	v_add_f32_e32 v48, v48, v48
	v_cmp_nlt_f32_e32 vcc, s92, v48
	s_and_saveexec_b64 s[2:3], vcc
	s_xor_b64 s[2:3], exec, s[2:3]
	v_fma_f32 v179, v172, v172, -1.0
	s_andn2_saveexec_b64 s[2:3], s[2:3]
	v_fmamk_f32 v49, v48, 0x3c088888, v136
	v_fmaak_f32 v49, v48, v49, 0x3e2aaaab
	v_fma_f32 v49, v48, v49, 0.5
	v_fma_f32 v49, v48, v49, 1.0
	v_mul_f32_e32 v179, v48, v49
	s_or_b64 exec, exec, s[2:3]
	v_add_f32_e32 v48, v51, v63
	v_mul_f32_e32 v48, 0xbfb8aa3b, v48
	v_exp_f32_e32 v48, v48
	s_nop 0
	v_add_f32_e32 v48, 1.0, v48
	v_rcp_f32_e32 v48, v48
	s_nop 0
	v_mul_f32_e64 v48, v48, -v67
	v_mul_f32_e32 v49, 0x3fb8aa3b, v48
	v_exp_f32_e32 v173, v49
	v_add_f32_e32 v48, v48, v48
	v_cmp_nlt_f32_e32 vcc, s92, v48
	s_and_saveexec_b64 s[2:3], vcc
	s_xor_b64 s[2:3], exec, s[2:3]
	v_fma_f32 v180, v173, v173, -1.0
	s_andn2_saveexec_b64 s[2:3], s[2:3]
	v_fmamk_f32 v49, v48, 0x3c088888, v136
	v_fmaak_f32 v49, v48, v49, 0x3e2aaaab
	v_fma_f32 v49, v48, v49, 0.5
	v_fma_f32 v49, v48, v49, 1.0
	v_mul_f32_e32 v180, v48, v49
	s_or_b64 exec, exec, s[2:3]
	v_add_f32_e32 v44, v44, v56
	v_mul_f32_e32 v44, 0xbfb8aa3b, v44
	v_exp_f32_e32 v44, v44
	s_nop 0
	v_add_f32_e32 v44, 1.0, v44
	v_rcp_f32_e32 v44, v44
	s_nop 0
	v_mul_f32_e64 v44, v44, -v52
	v_mul_f32_e32 v48, 0x3fb8aa3b, v44
	v_exp_f32_e32 v174, v48
	v_add_f32_e32 v44, v44, v44
	v_cmp_nlt_f32_e32 vcc, s92, v44
	s_and_saveexec_b64 s[2:3], vcc
	s_xor_b64 s[2:3], exec, s[2:3]
	v_fma_f32 v181, v174, v174, -1.0
	s_andn2_saveexec_b64 s[2:3], s[2:3]
	v_fmamk_f32 v48, v44, 0x3c088888, v136
	v_fmaak_f32 v48, v44, v48, 0x3e2aaaab
	v_fma_f32 v48, v44, v48, 0.5
	v_fma_f32 v48, v44, v48, 1.0
	v_mul_f32_e32 v181, v44, v48
	s_or_b64 exec, exec, s[2:3]
	v_add_f32_e32 v44, v45, v57
	v_mul_f32_e32 v44, 0xbfb8aa3b, v44
	v_exp_f32_e32 v44, v44
	s_nop 0
	v_add_f32_e32 v44, 1.0, v44
	v_rcp_f32_e32 v44, v44
	s_nop 0
	v_mul_f32_e64 v44, v44, -v53
	v_mul_f32_e32 v45, 0x3fb8aa3b, v44
	v_exp_f32_e32 v175, v45
	v_add_f32_e32 v44, v44, v44
	v_cmp_nlt_f32_e32 vcc, s92, v44
	s_and_saveexec_b64 s[2:3], vcc
	s_xor_b64 s[2:3], exec, s[2:3]
	v_fma_f32 v182, v175, v175, -1.0
	s_andn2_saveexec_b64 s[2:3], s[2:3]
	v_fmamk_f32 v45, v44, 0x3c088888, v136
	v_fmaak_f32 v45, v44, v45, 0x3e2aaaab
	v_fma_f32 v45, v44, v45, 0.5
	v_fma_f32 v45, v44, v45, 1.0
	v_mul_f32_e32 v182, v44, v45
	s_or_b64 exec, exec, s[2:3]
	v_add_f32_e32 v44, v46, v58
	v_mul_f32_e32 v44, 0xbfb8aa3b, v44
	v_exp_f32_e32 v44, v44
	s_nop 0
	v_add_f32_e32 v44, 1.0, v44
	v_rcp_f32_e32 v44, v44
	s_nop 0
	v_mul_f32_e64 v44, v44, -v54
	v_mul_f32_e32 v45, 0x3fb8aa3b, v44
	v_exp_f32_e32 v177, v45
	v_add_f32_e32 v44, v44, v44
	v_cmp_nlt_f32_e32 vcc, s92, v44
	s_and_saveexec_b64 s[2:3], vcc
	s_xor_b64 s[2:3], exec, s[2:3]
	v_fma_f32 v183, v177, v177, -1.0
	s_andn2_saveexec_b64 s[2:3], s[2:3]
	v_fmamk_f32 v45, v44, 0x3c088888, v136
	v_fmaak_f32 v45, v44, v45, 0x3e2aaaab
	v_fma_f32 v45, v44, v45, 0.5
	v_fma_f32 v45, v44, v45, 1.0
	v_mul_f32_e32 v183, v44, v45
	s_or_b64 exec, exec, s[2:3]
	v_add_f32_e32 v44, v47, v59
	v_mul_f32_e32 v44, 0xbfb8aa3b, v44
	v_exp_f32_e32 v44, v44
	s_nop 0
	v_add_f32_e32 v44, 1.0, v44
	v_rcp_f32_e32 v44, v44
	s_nop 0
	v_mul_f32_e64 v44, v44, -v55
	v_mul_f32_e32 v45, 0x3fb8aa3b, v44
	v_exp_f32_e32 v178, v45
	v_add_f32_e32 v44, v44, v44
	v_cmp_nlt_f32_e32 vcc, s92, v44
	s_and_saveexec_b64 s[2:3], vcc
	s_xor_b64 s[2:3], exec, s[2:3]
	v_fma_f32 v184, v178, v178, -1.0
	s_andn2_saveexec_b64 s[2:3], s[2:3]
	v_fmamk_f32 v45, v44, 0x3c088888, v136
	v_fmaak_f32 v45, v44, v45, 0x3e2aaaab
	v_fma_f32 v45, v44, v45, 0.5
	v_fma_f32 v45, v44, v45, 1.0
	v_mul_f32_e32 v184, v44, v45
	s_or_b64 exec, exec, s[2:3]
	ds_read_b128 v[60:63], v115 offset:2688
	ds_read_b128 v[52:55], v115 offset:2704
	ds_read_b128 v[64:67], v115 offset:3200
	ds_read_b128 v[44:47], v115 offset:2944
	ds_read_b128 v[48:51], v115 offset:2960
	ds_read_b128 v[56:59], v115 offset:3216
	s_waitcnt lgkmcnt(0)
	v_add_f32_e32 v40, v40, v60
	v_mul_f32_e32 v40, 0xbfb8aa3b, v40
	v_exp_f32_e32 v40, v40
	s_nop 0
	v_add_f32_e32 v40, 1.0, v40
	v_rcp_f32_e32 v40, v40
	s_nop 0
	v_mul_f32_e64 v60, v40, -v64
	v_mul_f32_e32 v40, 0x3fb8aa3b, v60
	v_exp_f32_e32 v40, v40
	v_add_f32_e32 v60, v60, v60
	v_cmp_nlt_f32_e32 vcc, s92, v60
	s_and_saveexec_b64 s[2:3], vcc
	s_xor_b64 s[2:3], exec, s[2:3]
	v_fma_f32 v64, v40, v40, -1.0
	s_andn2_saveexec_b64 s[2:3], s[2:3]
	v_fmamk_f32 v64, v60, 0x3c088888, v136
	v_fmaak_f32 v64, v60, v64, 0x3e2aaaab
	v_fma_f32 v64, v60, v64, 0.5
	v_fma_f32 v64, v60, v64, 1.0
	v_mul_f32_e32 v64, v60, v64
	s_or_b64 exec, exec, s[2:3]
	v_add_f32_e32 v41, v41, v61
	v_mul_f32_e32 v41, 0xbfb8aa3b, v41
	v_exp_f32_e32 v41, v41
	s_nop 0
	v_add_f32_e32 v41, 1.0, v41
	v_rcp_f32_e32 v41, v41
	s_nop 0
	v_mul_f32_e64 v41, v41, -v65
	v_mul_f32_e32 v60, 0x3fb8aa3b, v41
	v_exp_f32_e32 v60, v60
	v_add_f32_e32 v61, v41, v41
	v_cmp_nlt_f32_e32 vcc, s92, v61
	s_and_saveexec_b64 s[2:3], vcc
	s_xor_b64 s[2:3], exec, s[2:3]
	v_fma_f32 v41, v60, v60, -1.0
	s_andn2_saveexec_b64 s[2:3], s[2:3]
	v_fmamk_f32 v41, v61, 0x3c088888, v136
	v_fmaak_f32 v41, v61, v41, 0x3e2aaaab
	v_fma_f32 v41, v61, v41, 0.5
	v_fma_f32 v41, v61, v41, 1.0
	v_mul_f32_e32 v41, v61, v41
	s_or_b64 exec, exec, s[2:3]
	v_add_f32_e32 v42, v42, v62
	v_mul_f32_e32 v42, 0xbfb8aa3b, v42
	v_exp_f32_e32 v42, v42
	s_nop 0
	v_add_f32_e32 v42, 1.0, v42
	v_rcp_f32_e32 v42, v42
	s_nop 0
	v_mul_f32_e64 v42, v42, -v66
	v_mul_f32_e32 v61, 0x3fb8aa3b, v42
	v_exp_f32_e32 v61, v61
	v_add_f32_e32 v62, v42, v42
	v_cmp_nlt_f32_e32 vcc, s92, v62
	s_and_saveexec_b64 s[2:3], vcc
	s_xor_b64 s[2:3], exec, s[2:3]
	v_fma_f32 v42, v61, v61, -1.0
	s_andn2_saveexec_b64 s[2:3], s[2:3]
	v_fmamk_f32 v42, v62, 0x3c088888, v136
; __device__ __forceinline__ float fsigmoid(float x) { return __builtin_amdgcn_rcpf(1.0f + __builtin_amdgcn_exp2f(-1.4426950408889634f * x)); }
; #define LAS __attribute__((address_space(3)))
; __device__ __forceinline__ void lru_item(const Frame& F, const bf16* XR, bf16* XGYL, const float* conv_w, const float* conv_b, const float* wa, const float* ba, const float* wx, const float* bx, const float* lam, int b, int hh, int j2) {
;     ...
;         for (int s2 = 0; s2 < 2; ++s2) {
;             const f32x4 ba0 = *(const LAS f32x4*)(ctab + 32 * s2 + 8 * g), ba1 = *(const LAS f32x4*)(ctab + 32 * s2 + 8 * g + 4);
;             const f32x4 bx0 = *(const LAS f32x4*)(ctab + 64 + 32 * s2 + 8 * g), bx1 = *(const LAS f32x4*)(ctab + 64 + 32 * s2 + 8 * g + 4);
;             const f32x4 sp0 = *(const LAS f32x4*)(ctab + 128 + 32 * s2 + 8 * g), sp1 = *(const LAS f32x4*)(ctab + 128 + 32 * s2 + 8 * g + 4);
; #pragma unroll
;             for (int i = 0; i < 8; ++i) { const float bai = (i < 4) ? ba0[i & 3] : ba1[i & 3], bxi = (i < 4) ? bx0[i & 3] : bx1[i & 3], spi = (i < 4) ? sp0[i & 3] : sp1[i & 3];
;                 const float rp = pa[s2 * 2 + (i >> 2)][i & 3] + bai, xp = pa[4 + s2 * 2 + (i >> 2)][i & 3] + bxi;
;                 const float rr = pg8::fsigmoid(rp), ig = pg8::fsigmoid(xp), la = -spi * rr, x2 = 2.0f * la;
;                 const float a = __builtin_amdgcn_exp2f(LOG2E * la);
;                 const float em1 = (x2 > -0.3f) ? x2 * (1.0f + x2 * (0.5f + x2 * (0.16666667f + x2 * (0.041666668f + x2 * 0.0083333333f)))) : (a * a - 1.0f);
;                 av[8 * s2 + i] = a; uv[8 * s2 + i] = __builtin_amdgcn_sqrtf(-em1) * ig * xcf[8 * s2 + i]; } }
	v_fmaak_f32 v42, v62, v42, 0x3e2aaaab
	v_fma_f32 v42, v62, v42, 0.5
	v_fma_f32 v42, v62, v42, 1.0
	v_mul_f32_e32 v42, v62, v42
	s_or_b64 exec, exec, s[2:3]
	v_add_f32_e32 v43, v43, v63
	v_mul_f32_e32 v43, 0xbfb8aa3b, v43
	v_exp_f32_e32 v43, v43
	s_nop 0
	v_add_f32_e32 v43, 1.0, v43
	v_rcp_f32_e32 v43, v43
	s_nop 0
	v_mul_f32_e64 v43, v43, -v67
	v_mul_f32_e32 v62, 0x3fb8aa3b, v43
	v_exp_f32_e32 v62, v62
	v_add_f32_e32 v63, v43, v43
	v_cmp_nlt_f32_e32 vcc, s92, v63
	s_and_saveexec_b64 s[2:3], vcc
	s_xor_b64 s[2:3], exec, s[2:3]
	v_fma_f32 v43, v62, v62, -1.0
	s_andn2_saveexec_b64 s[2:3], s[2:3]
	v_fmamk_f32 v43, v63, 0x3c088888, v136
	v_fmaak_f32 v43, v63, v43, 0x3e2aaaab
	v_fma_f32 v43, v63, v43, 0.5
	v_fma_f32 v43, v63, v43, 1.0
	v_mul_f32_e32 v43, v63, v43
	s_or_b64 exec, exec, s[2:3]
	v_add_f32_e32 v28, v28, v52
	v_mul_f32_e32 v28, 0xbfb8aa3b, v28
	v_exp_f32_e32 v28, v28
	s_nop 0
	v_add_f32_e32 v28, 1.0, v28
	v_rcp_f32_e32 v28, v28
	s_nop 0
	v_mul_f32_e64 v52, v28, -v56
	v_mul_f32_e32 v28, 0x3fb8aa3b, v52
	v_exp_f32_e32 v28, v28
	v_add_f32_e32 v52, v52, v52
	v_cmp_nlt_f32_e32 vcc, s92, v52
	s_and_saveexec_b64 s[2:3], vcc
	s_xor_b64 s[2:3], exec, s[2:3]
	v_fma_f32 v56, v28, v28, -1.0
	s_andn2_saveexec_b64 s[2:3], s[2:3]
	v_fmamk_f32 v56, v52, 0x3c088888, v136
	v_fmaak_f32 v56, v52, v56, 0x3e2aaaab
	v_fma_f32 v56, v52, v56, 0.5
	v_fma_f32 v56, v52, v56, 1.0
	v_mul_f32_e32 v56, v52, v56
	s_or_b64 exec, exec, s[2:3]
	v_add_f32_e32 v29, v29, v53
	v_mul_f32_e32 v29, 0xbfb8aa3b, v29
	v_exp_f32_e32 v29, v29
	s_nop 0
	v_add_f32_e32 v29, 1.0, v29
	v_rcp_f32_e32 v29, v29
	s_nop 0
	v_mul_f32_e64 v29, v29, -v57
	v_mul_f32_e32 v52, 0x3fb8aa3b, v29
	v_exp_f32_e32 v52, v52
	v_add_f32_e32 v53, v29, v29
	v_cmp_nlt_f32_e32 vcc, s92, v53
	s_and_saveexec_b64 s[2:3], vcc
	s_xor_b64 s[2:3], exec, s[2:3]
	v_fma_f32 v29, v52, v52, -1.0
	s_andn2_saveexec_b64 s[2:3], s[2:3]
	v_fmamk_f32 v29, v53, 0x3c088888, v136
	v_fmaak_f32 v29, v53, v29, 0x3e2aaaab
	v_fma_f32 v29, v53, v29, 0.5
	v_fma_f32 v29, v53, v29, 1.0
	v_mul_f32_e32 v29, v53, v29
	s_or_b64 exec, exec, s[2:3]
	v_add_f32_e32 v30, v30, v54
	v_mul_f32_e32 v30, 0xbfb8aa3b, v30
	v_exp_f32_e32 v30, v30
	s_nop 0
	v_add_f32_e32 v30, 1.0, v30
	v_rcp_f32_e32 v30, v30
	s_nop 0
	v_mul_f32_e64 v30, v30, -v58
	v_mul_f32_e32 v53, 0x3fb8aa3b, v30
	v_exp_f32_e32 v53, v53
	v_add_f32_e32 v30, v30, v30
	v_cmp_nlt_f32_e32 vcc, s92, v30
	s_and_saveexec_b64 s[2:3], vcc
	s_xor_b64 s[2:3], exec, s[2:3]
	v_fma_f32 v57, v53, v53, -1.0
	s_andn2_saveexec_b64 s[2:3], s[2:3]
	v_fmamk_f32 v54, v30, 0x3c088888, v136
	v_fmaak_f32 v54, v30, v54, 0x3e2aaaab
	v_fma_f32 v54, v30, v54, 0.5
	v_fma_f32 v54, v30, v54, 1.0
	v_mul_f32_e32 v57, v30, v54
	s_or_b64 exec, exec, s[2:3]
	v_add_f32_e32 v30, v31, v55
	v_mul_f32_e32 v30, 0xbfb8aa3b, v30
	v_exp_f32_e32 v30, v30
	s_nop 0
	v_add_f32_e32 v30, 1.0, v30
	v_rcp_f32_e32 v30, v30
	s_nop 0
	v_mul_f32_e64 v30, v30, -v59
	v_mul_f32_e32 v31, 0x3fb8aa3b, v30
	v_exp_f32_e32 v54, v31
	v_add_f32_e32 v31, v30, v30
	v_cmp_nlt_f32_e32 vcc, s92, v31
	s_and_saveexec_b64 s[2:3], vcc
	s_xor_b64 s[2:3], exec, s[2:3]
	v_fma_f32 v30, v54, v54, -1.0
	s_andn2_saveexec_b64 s[2:3], s[2:3]
	v_fmamk_f32 v30, v31, 0x3c088888, v136
	v_fmaak_f32 v30, v31, v30, 0x3e2aaaab
	v_fma_f32 v30, v31, v30, 0.5
	v_fma_f32 v30, v31, v30, 1.0
	v_mul_f32_e32 v30, v31, v30
	s_or_b64 exec, exec, s[2:3]
	v_add_f32_e32 v18, v18, v50
	v_mul_f32_e32 v18, 0xbfb8aa3b, v18
	v_exp_f32_e32 v18, v18
	v_add_f32_e32 v19, v19, v51
	v_add_f32_e32 v17, v17, v49
	v_mul_f32_e32 v19, 0xbfb8aa3b, v19
	v_add_f32_e32 v18, 1.0, v18
	v_mul_f32_e32 v17, 0xbfb8aa3b, v17
	v_sqrt_f32_e64 v50, -v57
	v_rcp_f32_e32 v18, v18
	v_exp_f32_e32 v19, v19
	v_exp_f32_e32 v49, v17
	v_add_f32_e32 v16, v16, v48
	v_mul_f32_e32 v16, 0xbfb8aa3b, v16
	v_mul_f32_e32 v17, v18, v50
	v_add_f32_e32 v18, 1.0, v19
	v_add_f32_e32 v19, 1.0, v49
	v_exp_f32_e32 v16, v16
	v_rcp_f32_e32 v19, v19
	v_sqrt_f32_e64 v29, -v29
	v_add_f32_e32 v35, v35, v47
	v_add_f32_e32 v16, 1.0, v16
	v_mul_f32_e32 v35, 0xbfb8aa3b, v35
	v_mul_f32_e32 v19, v19, v29
	v_rcp_f32_e32 v16, v16
	v_sqrt_f32_e64 v29, -v56
	v_exp_f32_e32 v35, v35
	v_add_f32_e32 v33, v33, v45
	v_mul_f32_e32 v33, 0xbfb8aa3b, v33
	v_mul_f32_e32 v16, v16, v29
	v_add_f32_e32 v29, 1.0, v35
	v_rcp_f32_e32 v35, v29
	v_add_f32_e32 v29, v34, v46
	v_mul_f32_e32 v29, 0xbfb8aa3b, v29
	v_exp_f32_e32 v34, v29
	v_sqrt_f32_e64 v43, -v43
	v_exp_f32_e32 v33, v33
	v_cndmask_b32_e64 v31, v168, v150, s[42:43]
	v_add_f32_e32 v34, 1.0, v34
	v_rcp_f32_e32 v34, v34
	v_sqrt_f32_e64 v42, -v42
	v_mul_f32_e32 v17, v31, v17
	v_cndmask_b32_e64 v31, v167, v149, s[42:43]
	v_add_f32_e32 v32, v32, v44
	v_mul_f32_e32 v31, v31, v19
	v_cndmask_b32_e64 v19, v166, v148, s[42:43]
	v_mul_f32_e32 v32, 0xbfb8aa3b, v32
	v_mul_f32_e32 v29, v19, v16
	v_cndmask_b32_e64 v16, v165, v147, s[42:43]
	v_mul_f32_e32 v19, v35, v43
	v_add_f32_e32 v33, 1.0, v33
	v_exp_f32_e32 v32, v32
	v_mul_f32_e32 v35, v16, v19
	v_mul_f32_e32 v19, v34, v42
	v_rcp_f32_e32 v34, v33
	v_sqrt_f32_e64 v41, -v41
	v_add_f32_e32 v27, v27, v39
	v_mul_f32_e32 v27, 0xbfb8aa3b, v27
	v_cndmask_b32_e64 v16, v164, v146, s[42:43]
	v_add_f32_e32 v32, 1.0, v32
	v_exp_f32_e32 v27, v27
	v_mul_f32_e32 v33, v16, v19
	v_mul_f32_e32 v19, v34, v41
	v_rcp_f32_e32 v32, v32
	v_sqrt_f32_e64 v34, -v64
	v_add_f32_e32 v26, v26, v38
	v_mul_f32_e32 v26, 0xbfb8aa3b, v26
	v_cndmask_b32_e64 v16, v163, v145, s[42:43]
	v_add_f32_e32 v27, 1.0, v27
	v_exp_f32_e32 v26, v26
	v_mul_f32_e32 v41, v16, v19
	v_mul_f32_e32 v19, v32, v34
	v_rcp_f32_e32 v27, v27
	v_sqrt_f32_e64 v32, -v184
	v_add_f32_e32 v25, v25, v37
	v_mul_f32_e32 v25, 0xbfb8aa3b, v25
; #define LAS __attribute__((address_space(3)))
; __device__ __forceinline__ void lru_item(const Frame& F, const bf16* XR, bf16* XGYL, const float* conv_w, const float* conv_b, const float* wa, const float* ba, const float* wx, const float* bx, const float* lam, int b, int hh, int j2) {
;     ...
; #pragma unroll
;         for (int i = 0; i < 16; ++i) {
;             { const float ap = row_shr<1>(1.0f, av[i]), up = row_shr<1>(0.0f, uv[i]); uv[i] = fmaf(av[i], up, uv[i]); av[i] *= ap; }
;             { const float ap = row_shr<2>(1.0f, av[i]), up = row_shr<2>(0.0f, uv[i]); uv[i] = fmaf(av[i], up, uv[i]); av[i] *= ap; }
;             { const float ap = row_shr<4>(1.0f, av[i]), up = row_shr<4>(0.0f, uv[i]); uv[i] = fmaf(av[i], up, uv[i]); av[i] *= ap; }
;             { const float ap = row_shr<8>(1.0f, av[i]), up = row_shr<8>(0.0f, uv[i]); uv[i] = fmaf(av[i], up, uv[i]); av[i] *= ap; } }
;         LAS float* tb = tot + (chunk & 1) * 1024;
;         if (tl == 15) {
; #pragma unroll
;             for (int i = 0; i < 16; i += 2) *(LAS f32x4*)(tb + (w * 64 + g * 16 + i) * 2) = (f32x4){av[i], uv[i], av[i + 1], uv[i + 1]}; }
	v_cndmask_b32_e64 v16, v162, v144, s[42:43]
	v_add_f32_e32 v26, 1.0, v26
	v_exp_f32_e32 v25, v25
	v_mul_f32_e32 v39, v16, v19
	v_mul_f32_e32 v19, v27, v32
	v_rcp_f32_e32 v26, v26
	v_sqrt_f32_e64 v32, -v183
	v_add_f32_e32 v24, v24, v36
	v_mul_f32_e32 v24, 0xbfb8aa3b, v24
	v_cndmask_b32_e64 v16, v160, v142, s[42:43]
	v_add_f32_e32 v25, 1.0, v25
	v_exp_f32_e32 v24, v24
	v_mul_f32_e32 v27, v16, v19
	v_mul_f32_e32 v19, v26, v32
	v_rcp_f32_e32 v26, v25
	v_sqrt_f32_e64 v32, -v182
	v_add_f32_e32 v15, v23, v15
	v_mul_f32_e32 v15, 0xbfb8aa3b, v15
	v_add_f32_e32 v14, v22, v14
	v_cndmask_b32_e64 v16, v159, v141, s[42:43]
	v_add_f32_e32 v24, 1.0, v24
	v_exp_f32_e32 v15, v15
	v_mul_f32_e32 v14, 0xbfb8aa3b, v14
	v_mul_f32_e32 v25, v16, v19
	v_mul_f32_e32 v19, v26, v32
	v_rcp_f32_e32 v24, v24
	v_sqrt_f32_e64 v26, -v181
	v_exp_f32_e32 v14, v14
	v_add_f32_e32 v13, v21, v13
	v_cndmask_b32_e64 v16, v158, v140, s[42:43]
	v_add_f32_e32 v15, 1.0, v15
	v_mul_f32_e32 v13, 0xbfb8aa3b, v13
	v_mul_f32_e32 v45, v16, v19
	v_cndmask_b32_e64 v16, v155, v95, s[42:43]
	v_mul_f32_e32 v19, v24, v26
	v_rcp_f32_e32 v15, v15
	v_sqrt_f32_e64 v23, -v180
	v_add_f32_e32 v14, 1.0, v14
	v_exp_f32_e32 v13, v13
	v_mul_f32_e32 v43, v16, v19
	v_rcp_f32_e32 v14, v14
	v_sqrt_f32_e64 v19, -v179
	v_add_f32_e32 v12, v20, v12
	v_mul_f32_e32 v12, 0xbfb8aa3b, v12
	v_cndmask_b32_e64 v16, v154, v93, s[42:43]
	v_mul_f32_e32 v15, v15, v23
	v_add_f32_e32 v13, 1.0, v13
	v_exp_f32_e32 v12, v12
	v_mul_f32_e32 v15, v16, v15
	v_mul_f32_e32 v14, v14, v19
	v_rcp_f32_e32 v16, v13
	v_sqrt_f32_e64 v19, -v176
	v_cndmask_b32_e64 v2, v153, v2, s[42:43]
	v_add_f32_e32 v12, 1.0, v12
	v_mul_f32_e32 v13, v2, v14
	v_cndmask_b32_e64 v1, v152, v1, s[42:43]
	v_mul_f32_e32 v2, v16, v19
	v_rcp_f32_e32 v12, v12
	v_sqrt_f32_e64 v14, -v171
	v_rcp_f32_e32 v18, v18
	v_mul_f32_e32 v23, v1, v2
	v_sqrt_f32_e64 v1, -v30
	v_cndmask_b32_e64 v0, v151, v0, s[42:43]
	v_mul_f32_e32 v2, v12, v14
	v_mul_f32_e32 v21, v0, v2
	v_cndmask_b32_e64 v0, v161, v143, s[42:43]
	v_mul_f32_e32 v1, v18, v1
	v_mul_f32_e32 v19, v0, v1
	s_lshl_b32 s2, s7, 12
	s_add_i32 s7, s2, 0
	v_mov_b32_e32 v20, v169
	v_mov_b32_e32 v22, v170
	v_mov_b32_e32 v12, v172
	v_mov_b32_e32 v14, v173
	v_mov_b32_e32 v42, v174
	v_mov_b32_e32 v44, v175
	v_mov_b32_e32 v24, v177
	v_mov_b32_e32 v26, v178
	v_mov_b32_e32 v38, v40
	v_mov_b32_e32 v40, v60
	v_mov_b32_e32 v32, v61
	v_mov_b32_e32 v34, v62
	v_mov_b32_e32 v28, v28
	v_mov_b32_e32 v30, v52
	v_mov_b32_e32 v16, v53
	v_mov_b32_e32 v18, v54
	v_fmac_f32_dpp v21, v21, v20 row_shr:1 row_mask:0xf bank_mask:0xf
	v_fmac_f32_dpp v23, v23, v22 row_shr:1 row_mask:0xf bank_mask:0xf
	v_fmac_f32_dpp v13, v13, v12 row_shr:1 row_mask:0xf bank_mask:0xf
	v_fmac_f32_dpp v15, v15, v14 row_shr:1 row_mask:0xf bank_mask:0xf
	v_fmac_f32_dpp v43, v43, v42 row_shr:1 row_mask:0xf bank_mask:0xf
	v_fmac_f32_dpp v45, v45, v44 row_shr:1 row_mask:0xf bank_mask:0xf
	v_fmac_f32_dpp v25, v25, v24 row_shr:1 row_mask:0xf bank_mask:0xf
	v_fmac_f32_dpp v27, v27, v26 row_shr:1 row_mask:0xf bank_mask:0xf
	v_fmac_f32_dpp v39, v39, v38 row_shr:1 row_mask:0xf bank_mask:0xf
	v_fmac_f32_dpp v41, v41, v40 row_shr:1 row_mask:0xf bank_mask:0xf
	v_fmac_f32_dpp v33, v33, v32 row_shr:1 row_mask:0xf bank_mask:0xf
	v_fmac_f32_dpp v35, v35, v34 row_shr:1 row_mask:0xf bank_mask:0xf
	v_fmac_f32_dpp v29, v29, v28 row_shr:1 row_mask:0xf bank_mask:0xf
	v_fmac_f32_dpp v31, v31, v30 row_shr:1 row_mask:0xf bank_mask:0xf
	v_fmac_f32_dpp v17, v17, v16 row_shr:1 row_mask:0xf bank_mask:0xf
	v_fmac_f32_dpp v19, v19, v18 row_shr:1 row_mask:0xf bank_mask:0xf
	v_mul_f32_dpp v20, v20, v20 row_shr:1 row_mask:0xf bank_mask:0xf
	v_mul_f32_dpp v22, v22, v22 row_shr:1 row_mask:0xf bank_mask:0xf
	v_mul_f32_dpp v12, v12, v12 row_shr:1 row_mask:0xf bank_mask:0xf
	v_mul_f32_dpp v14, v14, v14 row_shr:1 row_mask:0xf bank_mask:0xf
	v_mul_f32_dpp v42, v42, v42 row_shr:1 row_mask:0xf bank_mask:0xf
	v_mul_f32_dpp v44, v44, v44 row_shr:1 row_mask:0xf bank_mask:0xf
	v_mul_f32_dpp v24, v24, v24 row_shr:1 row_mask:0xf bank_mask:0xf
	v_mul_f32_dpp v26, v26, v26 row_shr:1 row_mask:0xf bank_mask:0xf
	v_mul_f32_dpp v38, v38, v38 row_shr:1 row_mask:0xf bank_mask:0xf
	v_mul_f32_dpp v40, v40, v40 row_shr:1 row_mask:0xf bank_mask:0xf
	v_mul_f32_dpp v32, v32, v32 row_shr:1 row_mask:0xf bank_mask:0xf
	v_mul_f32_dpp v34, v34, v34 row_shr:1 row_mask:0xf bank_mask:0xf
	v_mul_f32_dpp v28, v28, v28 row_shr:1 row_mask:0xf bank_mask:0xf
	v_mul_f32_dpp v30, v30, v30 row_shr:1 row_mask:0xf bank_mask:0xf
	v_mul_f32_dpp v16, v16, v16 row_shr:1 row_mask:0xf bank_mask:0xf
	v_mul_f32_dpp v18, v18, v18 row_shr:1 row_mask:0xf bank_mask:0xf
	v_fmac_f32_dpp v21, v21, v20 row_shr:2 row_mask:0xf bank_mask:0xf
	v_fmac_f32_dpp v23, v23, v22 row_shr:2 row_mask:0xf bank_mask:0xf
	v_fmac_f32_dpp v13, v13, v12 row_shr:2 row_mask:0xf bank_mask:0xf
	v_fmac_f32_dpp v15, v15, v14 row_shr:2 row_mask:0xf bank_mask:0xf
	v_fmac_f32_dpp v43, v43, v42 row_shr:2 row_mask:0xf bank_mask:0xf
	v_fmac_f32_dpp v45, v45, v44 row_shr:2 row_mask:0xf bank_mask:0xf
	v_fmac_f32_dpp v25, v25, v24 row_shr:2 row_mask:0xf bank_mask:0xf
	v_fmac_f32_dpp v27, v27, v26 row_shr:2 row_mask:0xf bank_mask:0xf
	v_fmac_f32_dpp v39, v39, v38 row_shr:2 row_mask:0xf bank_mask:0xf
	v_fmac_f32_dpp v41, v41, v40 row_shr:2 row_mask:0xf bank_mask:0xf
	v_fmac_f32_dpp v33, v33, v32 row_shr:2 row_mask:0xf bank_mask:0xf
	v_fmac_f32_dpp v35, v35, v34 row_shr:2 row_mask:0xf bank_mask:0xf
	v_fmac_f32_dpp v29, v29, v28 row_shr:2 row_mask:0xf bank_mask:0xf
	v_fmac_f32_dpp v31, v31, v30 row_shr:2 row_mask:0xf bank_mask:0xf
	v_fmac_f32_dpp v17, v17, v16 row_shr:2 row_mask:0xf bank_mask:0xf
; #define LAS __attribute__((address_space(3)))
; __device__ __forceinline__ void lru_item(const Frame& F, const bf16* XR, bf16* XGYL, const float* conv_w, const float* conv_b, const float* wa, const float* ba, const float* wx, const float* bx, const float* lam, int b, int hh, int j2) {
;     ...
; #pragma unroll
;         for (int i = 0; i < 16; ++i) {
;             { const float ap = row_shr<1>(1.0f, av[i]), up = row_shr<1>(0.0f, uv[i]); uv[i] = fmaf(av[i], up, uv[i]); av[i] *= ap; }
;             { const float ap = row_shr<2>(1.0f, av[i]), up = row_shr<2>(0.0f, uv[i]); uv[i] = fmaf(av[i], up, uv[i]); av[i] *= ap; }
;             { const float ap = row_shr<4>(1.0f, av[i]), up = row_shr<4>(0.0f, uv[i]); uv[i] = fmaf(av[i], up, uv[i]); av[i] *= ap; }
;             { const float ap = row_shr<8>(1.0f, av[i]), up = row_shr<8>(0.0f, uv[i]); uv[i] = fmaf(av[i], up, uv[i]); av[i] *= ap; } }
;         LAS float* tb = tot + (chunk & 1) * 1024;
;         if (tl == 15) {
; #pragma unroll
;             for (int i = 0; i < 16; i += 2) *(LAS f32x4*)(tb + (w * 64 + g * 16 + i) * 2) = (f32x4){av[i], uv[i], av[i + 1], uv[i + 1]}; }
	v_fmac_f32_dpp v19, v19, v18 row_shr:2 row_mask:0xf bank_mask:0xf
	v_mul_f32_dpp v20, v20, v20 row_shr:2 row_mask:0xf bank_mask:0xf
	v_mul_f32_dpp v22, v22, v22 row_shr:2 row_mask:0xf bank_mask:0xf
	v_mul_f32_dpp v12, v12, v12 row_shr:2 row_mask:0xf bank_mask:0xf
	v_mul_f32_dpp v14, v14, v14 row_shr:2 row_mask:0xf bank_mask:0xf
	v_mul_f32_dpp v42, v42, v42 row_shr:2 row_mask:0xf bank_mask:0xf
	v_mul_f32_dpp v44, v44, v44 row_shr:2 row_mask:0xf bank_mask:0xf
	v_mul_f32_dpp v24, v24, v24 row_shr:2 row_mask:0xf bank_mask:0xf
	v_mul_f32_dpp v26, v26, v26 row_shr:2 row_mask:0xf bank_mask:0xf
	v_mul_f32_dpp v38, v38, v38 row_shr:2 row_mask:0xf bank_mask:0xf
	v_mul_f32_dpp v40, v40, v40 row_shr:2 row_mask:0xf bank_mask:0xf
	v_mul_f32_dpp v32, v32, v32 row_shr:2 row_mask:0xf bank_mask:0xf
	v_mul_f32_dpp v34, v34, v34 row_shr:2 row_mask:0xf bank_mask:0xf
	v_mul_f32_dpp v28, v28, v28 row_shr:2 row_mask:0xf bank_mask:0xf
	v_mul_f32_dpp v30, v30, v30 row_shr:2 row_mask:0xf bank_mask:0xf
	v_mul_f32_dpp v16, v16, v16 row_shr:2 row_mask:0xf bank_mask:0xf
	v_mul_f32_dpp v18, v18, v18 row_shr:2 row_mask:0xf bank_mask:0xf
	v_fmac_f32_dpp v21, v21, v20 row_shr:4 row_mask:0xf bank_mask:0xf
	v_fmac_f32_dpp v23, v23, v22 row_shr:4 row_mask:0xf bank_mask:0xf
	v_fmac_f32_dpp v13, v13, v12 row_shr:4 row_mask:0xf bank_mask:0xf
	v_fmac_f32_dpp v15, v15, v14 row_shr:4 row_mask:0xf bank_mask:0xf
	v_fmac_f32_dpp v43, v43, v42 row_shr:4 row_mask:0xf bank_mask:0xf
	v_fmac_f32_dpp v45, v45, v44 row_shr:4 row_mask:0xf bank_mask:0xf
	v_fmac_f32_dpp v25, v25, v24 row_shr:4 row_mask:0xf bank_mask:0xf
	v_fmac_f32_dpp v27, v27, v26 row_shr:4 row_mask:0xf bank_mask:0xf
	v_fmac_f32_dpp v39, v39, v38 row_shr:4 row_mask:0xf bank_mask:0xf
	v_fmac_f32_dpp v41, v41, v40 row_shr:4 row_mask:0xf bank_mask:0xf
	v_fmac_f32_dpp v33, v33, v32 row_shr:4 row_mask:0xf bank_mask:0xf
	v_fmac_f32_dpp v35, v35, v34 row_shr:4 row_mask:0xf bank_mask:0xf
	v_fmac_f32_dpp v29, v29, v28 row_shr:4 row_mask:0xf bank_mask:0xf
	v_fmac_f32_dpp v31, v31, v30 row_shr:4 row_mask:0xf bank_mask:0xf
	v_fmac_f32_dpp v17, v17, v16 row_shr:4 row_mask:0xf bank_mask:0xf
	v_fmac_f32_dpp v19, v19, v18 row_shr:4 row_mask:0xf bank_mask:0xf
	v_mul_f32_dpp v20, v20, v20 row_shr:4 row_mask:0xf bank_mask:0xf
	v_mul_f32_dpp v22, v22, v22 row_shr:4 row_mask:0xf bank_mask:0xf
	v_mul_f32_dpp v12, v12, v12 row_shr:4 row_mask:0xf bank_mask:0xf
	v_mul_f32_dpp v14, v14, v14 row_shr:4 row_mask:0xf bank_mask:0xf
	v_mul_f32_dpp v42, v42, v42 row_shr:4 row_mask:0xf bank_mask:0xf
	v_mul_f32_dpp v44, v44, v44 row_shr:4 row_mask:0xf bank_mask:0xf
	v_mul_f32_dpp v24, v24, v24 row_shr:4 row_mask:0xf bank_mask:0xf
	v_mul_f32_dpp v26, v26, v26 row_shr:4 row_mask:0xf bank_mask:0xf
	v_mul_f32_dpp v38, v38, v38 row_shr:4 row_mask:0xf bank_mask:0xf
	v_mul_f32_dpp v40, v40, v40 row_shr:4 row_mask:0xf bank_mask:0xf
	v_mul_f32_dpp v32, v32, v32 row_shr:4 row_mask:0xf bank_mask:0xf
	v_mul_f32_dpp v34, v34, v34 row_shr:4 row_mask:0xf bank_mask:0xf
	v_mul_f32_dpp v28, v28, v28 row_shr:4 row_mask:0xf bank_mask:0xf
	v_mul_f32_dpp v30, v30, v30 row_shr:4 row_mask:0xf bank_mask:0xf
	v_mul_f32_dpp v16, v16, v16 row_shr:4 row_mask:0xf bank_mask:0xf
	v_mul_f32_dpp v18, v18, v18 row_shr:4 row_mask:0xf bank_mask:0xf
	v_fmac_f32_dpp v21, v21, v20 row_shr:8 row_mask:0xf bank_mask:0xf
	v_fmac_f32_dpp v23, v23, v22 row_shr:8 row_mask:0xf bank_mask:0xf
	v_fmac_f32_dpp v13, v13, v12 row_shr:8 row_mask:0xf bank_mask:0xf
	v_fmac_f32_dpp v15, v15, v14 row_shr:8 row_mask:0xf bank_mask:0xf
	v_fmac_f32_dpp v43, v43, v42 row_shr:8 row_mask:0xf bank_mask:0xf
	v_fmac_f32_dpp v45, v45, v44 row_shr:8 row_mask:0xf bank_mask:0xf
	v_fmac_f32_dpp v25, v25, v24 row_shr:8 row_mask:0xf bank_mask:0xf
	v_fmac_f32_dpp v27, v27, v26 row_shr:8 row_mask:0xf bank_mask:0xf
	v_fmac_f32_dpp v39, v39, v38 row_shr:8 row_mask:0xf bank_mask:0xf
	v_fmac_f32_dpp v41, v41, v40 row_shr:8 row_mask:0xf bank_mask:0xf
	v_fmac_f32_dpp v33, v33, v32 row_shr:8 row_mask:0xf bank_mask:0xf
	v_fmac_f32_dpp v35, v35, v34 row_shr:8 row_mask:0xf bank_mask:0xf
	v_fmac_f32_dpp v29, v29, v28 row_shr:8 row_mask:0xf bank_mask:0xf
	v_fmac_f32_dpp v31, v31, v30 row_shr:8 row_mask:0xf bank_mask:0xf
	v_fmac_f32_dpp v17, v17, v16 row_shr:8 row_mask:0xf bank_mask:0xf
	v_fmac_f32_dpp v19, v19, v18 row_shr:8 row_mask:0xf bank_mask:0xf
	v_mul_f32_dpp v20, v20, v20 row_shr:8 row_mask:0xf bank_mask:0xf
	v_mul_f32_dpp v22, v22, v22 row_shr:8 row_mask:0xf bank_mask:0xf
	v_mul_f32_dpp v12, v12, v12 row_shr:8 row_mask:0xf bank_mask:0xf
	v_mul_f32_dpp v14, v14, v14 row_shr:8 row_mask:0xf bank_mask:0xf
	v_mul_f32_dpp v42, v42, v42 row_shr:8 row_mask:0xf bank_mask:0xf
	v_mul_f32_dpp v44, v44, v44 row_shr:8 row_mask:0xf bank_mask:0xf
	v_mul_f32_dpp v24, v24, v24 row_shr:8 row_mask:0xf bank_mask:0xf
	v_mul_f32_dpp v26, v26, v26 row_shr:8 row_mask:0xf bank_mask:0xf
	v_mul_f32_dpp v38, v38, v38 row_shr:8 row_mask:0xf bank_mask:0xf
	v_mul_f32_dpp v40, v40, v40 row_shr:8 row_mask:0xf bank_mask:0xf
	v_mul_f32_dpp v32, v32, v32 row_shr:8 row_mask:0xf bank_mask:0xf
	v_mul_f32_dpp v34, v34, v34 row_shr:8 row_mask:0xf bank_mask:0xf
	v_mul_f32_dpp v28, v28, v28 row_shr:8 row_mask:0xf bank_mask:0xf
	v_mul_f32_dpp v30, v30, v30 row_shr:8 row_mask:0xf bank_mask:0xf
	v_mul_f32_dpp v16, v16, v16 row_shr:8 row_mask:0xf bank_mask:0xf
	v_mul_f32_dpp v18, v18, v18 row_shr:8 row_mask:0xf bank_mask:0xf
	s_nop 1
	s_and_saveexec_b64 s[2:3], s[10:11]
	s_cbranch_execz .LBB0_338
	v_add_u32_e32 v0, s7, v132
	ds_write_b128 v0, v[20:23] offset:4096
	ds_write_b128 v0, v[12:15] offset:4112
	ds_write_b128 v0, v[42:45] offset:4128
	ds_write_b128 v0, v[24:27] offset:4144
	ds_write_b128 v0, v[38:41] offset:4160
	ds_write_b128 v0, v[32:35] offset:4176
	ds_write_b128 v0, v[28:31] offset:4192
	ds_write_b128 v0, v[16:19] offset:4208
	s_branch .LBB0_338

; #define PG8_STAGE(bufoff, gbase, voff) do { _Pragma("unroll") for (int _i = 0; _i < 2; ++_i) \
;         __builtin_amdgcn_global_load_lds((const unsigned*)((const char*)(gbase) + (voff)[_i]), (PG8_LAS unsigned*)(lds + (bufoff) + ldsw + _i * 8192), 16, 0, 0); } while (0)
; #define PG8_LDA(dst, b, h) do { _Pragma("unroll") for (int m = 0; m < 4; ++m) _Pragma("unroll") for (int k = 0; k < 2; ++k) dst[m][k] = *(const PG8_LAS bf16x8*)(lds + PG8_SA(b, h) + aoff + m * 2048 + k * 1024); } while (0)
; #define PG8_LDB(dst, b, h) do { _Pragma("unroll") for (int n = 0; n < 2; ++n) _Pragma("unroll") for (int k = 0; k < 2; ++k) dst[n][k] = *(const PG8_LAS bf16x8*)(lds + PG8_SB(b, h) + boff + n * 2048 + k * 1024); } while (0)
; #define PG8_MMA(ai, bj, At, Bt) do { __builtin_amdgcn_s_setprio(1); _Pragma("unroll") for (int m = 0; m < 4; ++m) _Pragma("unroll") for (int n = 0; n < 2; ++n) _Pragma("unroll") for (int k = 0; k < 2; ++k) \
;         acc[ai][bj][m][n] = __builtin_amdgcn_mfma_f32_16x16x32_bf16(Bt[n][k], At[m][k], acc[ai][bj][m][n], 0, 0, 0); __builtin_amdgcn_s_setprio(0); } while (0)
; #define PG8_WAIT_V(n) asm volatile("s_waitcnt vmcnt(" #n ")" ::: "memory")
; #define PG8_WAIT_L(n) asm volatile("s_waitcnt lgkmcnt(" #n ")" ::: "memory")
; #define PG8_BAR __builtin_amdgcn_s_barrier()
; #define PG8_SCHED __builtin_amdgcn_sched_barrier(0)
; template <class Epi, class Sched, bool ALIGN_EPI = false, bool SP2 = false>
; __device__ __forceinline__ void gemm_phase(PG8_LAS unsigned char* lds, const Gemm g, const Sched& S, const Epi& E) {
;     ...
;             PG8_LDB(B0, 0, 0); PG8_LDB(B1, 0, 1); PG8_SCHED; PG8_LDA(At, 0, 0); PG8_STAGE(PG8_SA(1, 1), a1 + hstepA, voffA);
;             PG8_WAIT_V(8); PG8_WAIT_L(0); PG8_BAR; PG8_MMA(0, 0, At, B0); PG8_MMA(0, 1, At, B1); PG8_BAR; PG8_SCHED;
;             PG8_LDA(At, 0, 1); PG8_STAGE(PG8_SB(0, 0), b2, voffB); PG8_STAGE(PG8_SB(0, 1), b2 + hstepB, voffB); PG8_STAGE(PG8_SA(0, 0), a2, voffA);
;             PG8_WAIT_V(8); PG8_WAIT_L(0); PG8_BAR; PG8_MMA(1, 0, At, B0); PG8_MMA(1, 1, At, B1); PG8_BAR; PG8_SCHED;
.LBB0_632:
	ds_read_b128 v[144:147], v163
	ds_read_b128 v[166:169], v163 offset:1024
	ds_read_b128 v[170:173], v163 offset:2048
	ds_read_b128 v[174:177], v163 offset:3072
	ds_read_b128 v[178:181], v164
	ds_read_b128 v[182:185], v164 offset:1024
	ds_read_b128 v[186:189], v164 offset:2048
	ds_read_b128 v[190:193], v164 offset:3072
	s_add_u32 s46, s44, 0xfff00080
	s_addc_u32 s47, s45, -1
	s_cmp_eq_u32 s70, 28
	s_cselect_b32 s49, s37, s47
	s_cselect_b32 s48, s66, s46
	s_cselect_b32 s47, s35, s69
	s_cselect_b32 s46, s67, s68
	v_lshl_add_u64 v[148:149], s[44:45], 0, v[136:137]
	s_add_i32 m0, s43, 0xc000
	ds_read_b128 v[194:197], v165
	ds_read_b128 v[198:201], v165 offset:1024
	ds_read_b128 v[202:205], v165 offset:2048
	ds_read_b128 v[206:209], v165 offset:3072
	ds_read_b128 v[210:213], v165 offset:4096
	ds_read_b128 v[214:217], v165 offset:5120
	ds_read_b128 v[218:221], v165 offset:6144
	ds_read_b128 v[222:225], v165 offset:7168
	global_load_lds_dwordx4 v[148:149], off
	v_lshl_add_u64 v[148:149], s[44:45], 0, v[138:139]
	s_add_i32 m0, s43, 0xe000
	s_nop 0
	global_load_lds_dwordx4 v[148:149], off
	s_waitcnt vmcnt(8)
	s_waitcnt lgkmcnt(0)
	s_barrier
	s_setprio 1
	s_waitcnt lgkmcnt(0)
	v_mfma_f32_16x16x32_bf16 v[124:127], v[144:147], v[194:197], v[124:127]
	v_mfma_f32_16x16x32_bf16 v[120:123], v[170:173], v[194:197], v[120:123]
	v_mfma_f32_16x16x32_bf16 v[108:111], v[144:147], v[202:205], v[108:111]
	v_mfma_f32_16x16x32_bf16 v[104:107], v[170:173], v[202:205], v[104:107]
	v_mfma_f32_16x16x32_bf16 v[92:95], v[144:147], v[210:213], v[92:95]
	v_mfma_f32_16x16x32_bf16 v[88:91], v[170:173], v[210:213], v[88:91]
	v_mfma_f32_16x16x32_bf16 v[76:79], v[144:147], v[218:221], v[76:79]
	v_mfma_f32_16x16x32_bf16 v[72:75], v[170:173], v[218:221], v[72:75]
	v_mfma_f32_16x16x32_bf16 v[124:127], v[166:169], v[198:201], v[124:127]
	v_mfma_f32_16x16x32_bf16 v[120:123], v[174:177], v[198:201], v[120:123]
	v_mfma_f32_16x16x32_bf16 v[108:111], v[166:169], v[206:209], v[108:111]
	v_mfma_f32_16x16x32_bf16 v[104:107], v[174:177], v[206:209], v[104:107]
	v_mfma_f32_16x16x32_bf16 v[92:95], v[166:169], v[214:217], v[92:95]
	v_mfma_f32_16x16x32_bf16 v[88:91], v[174:177], v[214:217], v[88:91]
	v_mfma_f32_16x16x32_bf16 v[76:79], v[166:169], v[222:225], v[76:79]
	v_mfma_f32_16x16x32_bf16 v[72:75], v[174:177], v[222:225], v[72:75]
	v_mfma_f32_16x16x32_bf16 v[116:119], v[178:181], v[194:197], v[116:119]
	v_mfma_f32_16x16x32_bf16 v[112:115], v[186:189], v[194:197], v[112:115]
	v_mfma_f32_16x16x32_bf16 v[100:103], v[178:181], v[202:205], v[100:103]
	v_mfma_f32_16x16x32_bf16 v[96:99], v[186:189], v[202:205], v[96:99]
	v_mfma_f32_16x16x32_bf16 v[84:87], v[178:181], v[210:213], v[84:87]
	v_mfma_f32_16x16x32_bf16 v[80:83], v[186:189], v[210:213], v[80:83]
	v_mfma_f32_16x16x32_bf16 v[68:71], v[178:181], v[218:221], v[68:71]
	v_mfma_f32_16x16x32_bf16 v[64:67], v[186:189], v[218:221], v[64:67]
	v_mfma_f32_16x16x32_bf16 v[116:119], v[182:185], v[198:201], v[116:119]
	v_mfma_f32_16x16x32_bf16 v[112:115], v[190:193], v[198:201], v[112:115]
	v_mfma_f32_16x16x32_bf16 v[100:103], v[182:185], v[206:209], v[100:103]
	v_mfma_f32_16x16x32_bf16 v[96:99], v[190:193], v[206:209], v[96:99]
	v_mfma_f32_16x16x32_bf16 v[84:87], v[182:185], v[214:217], v[84:87]
	v_mfma_f32_16x16x32_bf16 v[80:83], v[190:193], v[214:217], v[80:83]
	v_mfma_f32_16x16x32_bf16 v[68:71], v[182:185], v[222:225], v[68:71]
	v_mfma_f32_16x16x32_bf16 v[64:67], v[190:193], v[222:225], v[64:67]
	s_setprio 0
	s_barrier
	s_add_i32 s71, s63, s55
	v_lshl_add_u64 v[148:149], s[46:47], 0, v[130:131]
	s_mov_b32 m0, s71
	ds_read_b128 v[194:197], v165 offset:16384
	ds_read_b128 v[198:201], v165 offset:17408
	ds_read_b128 v[202:205], v165 offset:18432
	ds_read_b128 v[206:209], v165 offset:19456
	ds_read_b128 v[210:213], v165 offset:20480
	ds_read_b128 v[214:217], v165 offset:21504
	ds_read_b128 v[218:221], v165 offset:22528
	ds_read_b128 v[222:225], v165 offset:23552
	global_load_lds_dwordx4 v[148:149], off
	s_add_i32 m0, s71, 0x2000
	s_add_u32 s72, s46, 0x80000
	v_lshl_add_u64 v[226:227], s[46:47], 0, v[134:135]
	s_addc_u32 s73, s47, 0
	s_add_i32 s71, s64, s55
	global_load_lds_dwordx4 v[226:227], off
	v_lshl_add_u64 v[228:229], s[72:73], 0, v[130:131]
	s_mov_b32 m0, s71
	v_lshl_add_u64 v[230:231], s[48:49], 0, v[132:133]
	global_load_lds_dwordx4 v[228:229], off
	v_lshl_add_u64 v[228:229], s[72:73], 0, v[134:135]
	s_add_i32 m0, s71, 0x2000
	s_nop 0
	global_load_lds_dwordx4 v[228:229], off
	v_lshl_add_u64 v[228:229], s[48:49], 0, v[128:129]
	s_mov_b32 m0, s43
	s_nop 0
	global_load_lds_dwordx4 v[228:229], off
	s_mov_b32 m0, s56
	s_nop 0
	global_load_lds_dwordx4 v[230:231], off
	s_waitcnt vmcnt(8)
	s_waitcnt lgkmcnt(0)
	s_barrier
; #define PG8_STAGE(bufoff, gbase, voff) do { _Pragma("unroll") for (int _i = 0; _i < 2; ++_i) \
;         __builtin_amdgcn_global_load_lds((const unsigned*)((const char*)(gbase) + (voff)[_i]), (PG8_LAS unsigned*)(lds + (bufoff) + ldsw + _i * 8192), 16, 0, 0); } while (0)
; #define PG8_LDA(dst, b, h) do { _Pragma("unroll") for (int m = 0; m < 4; ++m) _Pragma("unroll") for (int k = 0; k < 2; ++k) dst[m][k] = *(const PG8_LAS bf16x8*)(lds + PG8_SA(b, h) + aoff + m * 2048 + k * 1024); } while (0)
; #define PG8_LDB(dst, b, h) do { _Pragma("unroll") for (int n = 0; n < 2; ++n) _Pragma("unroll") for (int k = 0; k < 2; ++k) dst[n][k] = *(const PG8_LAS bf16x8*)(lds + PG8_SB(b, h) + boff + n * 2048 + k * 1024); } while (0)
; #define PG8_MMA(ai, bj, At, Bt) do { __builtin_amdgcn_s_setprio(1); _Pragma("unroll") for (int m = 0; m < 4; ++m) _Pragma("unroll") for (int n = 0; n < 2; ++n) _Pragma("unroll") for (int k = 0; k < 2; ++k) \
;         acc[ai][bj][m][n] = __builtin_amdgcn_mfma_f32_16x16x32_bf16(Bt[n][k], At[m][k], acc[ai][bj][m][n], 0, 0, 0); __builtin_amdgcn_s_setprio(0); } while (0)
; #define PG8_WAIT_V(n) asm volatile("s_waitcnt vmcnt(" #n ")" ::: "memory")
; #define PG8_WAIT_L(n) asm volatile("s_waitcnt lgkmcnt(" #n ")" ::: "memory")
; #define PG8_BAR __builtin_amdgcn_s_barrier()
; #define PG8_SCHED __builtin_amdgcn_sched_barrier(0)
; template <class Epi, class Sched, bool ALIGN_EPI = false, bool SP2 = false>
; __device__ __forceinline__ void gemm_phase(PG8_LAS unsigned char* lds, const Gemm g, const Sched& S, const Epi& E) {
;     ...
;             PG8_WAIT_V(8); PG8_WAIT_L(0); PG8_BAR; PG8_MMA(1, 0, At, B0); PG8_MMA(1, 1, At, B1); PG8_BAR; PG8_SCHED;
;             PG8_LDB(B0, 1, 0); PG8_LDB(B1, 1, 1); PG8_SCHED; PG8_LDA(At, 1, 0); PG8_STAGE(PG8_SA(0, 1), a2 + hstepA, voffA);
;             PG8_WAIT_V(8); PG8_WAIT_L(0); PG8_BAR; PG8_MMA(0, 0, At, B0); PG8_MMA(0, 1, At, B1); PG8_BAR; PG8_SCHED;
	s_setprio 1
	s_waitcnt lgkmcnt(0)
	v_mfma_f32_16x16x32_bf16 v[60:63], v[144:147], v[194:197], v[60:63]
	v_mfma_f32_16x16x32_bf16 v[56:59], v[170:173], v[194:197], v[56:59]
	v_mfma_f32_16x16x32_bf16 v[44:47], v[144:147], v[202:205], v[44:47]
	v_mfma_f32_16x16x32_bf16 v[40:43], v[170:173], v[202:205], v[40:43]
	v_mfma_f32_16x16x32_bf16 v[28:31], v[144:147], v[210:213], v[28:31]
	v_mfma_f32_16x16x32_bf16 v[24:27], v[170:173], v[210:213], v[24:27]
	v_mfma_f32_16x16x32_bf16 v[12:15], v[144:147], v[218:221], v[12:15]
	v_mfma_f32_16x16x32_bf16 v[8:11], v[170:173], v[218:221], v[8:11]
	v_mfma_f32_16x16x32_bf16 v[60:63], v[166:169], v[198:201], v[60:63]
	v_mfma_f32_16x16x32_bf16 v[56:59], v[174:177], v[198:201], v[56:59]
	v_mfma_f32_16x16x32_bf16 v[44:47], v[166:169], v[206:209], v[44:47]
	v_mfma_f32_16x16x32_bf16 v[40:43], v[174:177], v[206:209], v[40:43]
	v_mfma_f32_16x16x32_bf16 v[28:31], v[166:169], v[214:217], v[28:31]
	v_mfma_f32_16x16x32_bf16 v[24:27], v[174:177], v[214:217], v[24:27]
	v_mfma_f32_16x16x32_bf16 v[12:15], v[166:169], v[222:225], v[12:15]
	v_mfma_f32_16x16x32_bf16 v[8:11], v[174:177], v[222:225], v[8:11]
	v_mfma_f32_16x16x32_bf16 v[52:55], v[178:181], v[194:197], v[52:55]
	v_mfma_f32_16x16x32_bf16 v[48:51], v[186:189], v[194:197], v[48:51]
	v_mfma_f32_16x16x32_bf16 v[36:39], v[178:181], v[202:205], v[36:39]
	v_mfma_f32_16x16x32_bf16 v[32:35], v[186:189], v[202:205], v[32:35]
	v_mfma_f32_16x16x32_bf16 v[20:23], v[178:181], v[210:213], v[20:23]
	v_mfma_f32_16x16x32_bf16 v[16:19], v[186:189], v[210:213], v[16:19]
	v_mfma_f32_16x16x32_bf16 v[4:7], v[178:181], v[218:221], v[4:7]
	v_mfma_f32_16x16x32_bf16 v[0:3], v[186:189], v[218:221], v[0:3]
	v_mfma_f32_16x16x32_bf16 v[52:55], v[182:185], v[198:201], v[52:55]
	v_mfma_f32_16x16x32_bf16 v[48:51], v[190:193], v[198:201], v[48:51]
	v_mfma_f32_16x16x32_bf16 v[36:39], v[182:185], v[206:209], v[36:39]
	v_mfma_f32_16x16x32_bf16 v[32:35], v[190:193], v[206:209], v[32:35]
	v_mfma_f32_16x16x32_bf16 v[20:23], v[182:185], v[214:217], v[20:23]
	v_mfma_f32_16x16x32_bf16 v[16:19], v[190:193], v[214:217], v[16:19]
	v_mfma_f32_16x16x32_bf16 v[4:7], v[182:185], v[222:225], v[4:7]
	v_mfma_f32_16x16x32_bf16 v[0:3], v[190:193], v[222:225], v[0:3]
	s_setprio 0
	s_barrier
	s_add_i32 s71, 0, 0x18000
	s_add_i32 s72, 0, 0x1c000
	v_add_u32_e32 v174, s71, v161
	v_add_u32_e32 v190, s72, v161
	ds_read_b128 v[144:147], v174
	ds_read_b128 v[166:169], v174 offset:1024
	ds_read_b128 v[170:173], v174 offset:2048
	ds_read_b128 v[174:177], v174 offset:3072
	ds_read_b128 v[178:181], v190
	ds_read_b128 v[182:185], v190 offset:1024
	ds_read_b128 v[186:189], v190 offset:2048
	ds_read_b128 v[190:193], v190 offset:3072
	s_add_u32 s48, s48, 0x100000
	s_addc_u32 s49, s49, 0
	s_mov_b32 m0, s57
	v_lshl_add_u64 v[232:233], s[48:49], 0, v[128:129]
	ds_read_b128 v[194:197], v165 offset:32768
	ds_read_b128 v[198:201], v165 offset:33792
	ds_read_b128 v[202:205], v165 offset:34816
	ds_read_b128 v[206:209], v165 offset:35840
	ds_read_b128 v[210:213], v165 offset:36864
	ds_read_b128 v[214:217], v165 offset:37888
	ds_read_b128 v[218:221], v165 offset:38912
	ds_read_b128 v[222:225], v165 offset:39936
	global_load_lds_dwordx4 v[232:233], off
	v_lshl_add_u64 v[232:233], s[48:49], 0, v[132:133]
	s_mov_b32 m0, s58
	s_nop 0
	global_load_lds_dwordx4 v[232:233], off
	s_waitcnt vmcnt(8)
	s_waitcnt lgkmcnt(0)
	s_barrier
	s_setprio 1
	s_waitcnt lgkmcnt(0)
	v_mfma_f32_16x16x32_bf16 v[124:127], v[144:147], v[194:197], v[124:127]
	v_mfma_f32_16x16x32_bf16 v[120:123], v[170:173], v[194:197], v[120:123]
	v_mfma_f32_16x16x32_bf16 v[108:111], v[144:147], v[202:205], v[108:111]
	v_mfma_f32_16x16x32_bf16 v[104:107], v[170:173], v[202:205], v[104:107]
	v_mfma_f32_16x16x32_bf16 v[92:95], v[144:147], v[210:213], v[92:95]
	v_mfma_f32_16x16x32_bf16 v[88:91], v[170:173], v[210:213], v[88:91]
	v_mfma_f32_16x16x32_bf16 v[76:79], v[144:147], v[218:221], v[76:79]
	v_mfma_f32_16x16x32_bf16 v[72:75], v[170:173], v[218:221], v[72:75]
	v_mfma_f32_16x16x32_bf16 v[124:127], v[166:169], v[198:201], v[124:127]
	v_mfma_f32_16x16x32_bf16 v[120:123], v[174:177], v[198:201], v[120:123]
	v_mfma_f32_16x16x32_bf16 v[108:111], v[166:169], v[206:209], v[108:111]
	v_mfma_f32_16x16x32_bf16 v[104:107], v[174:177], v[206:209], v[104:107]
	v_mfma_f32_16x16x32_bf16 v[92:95], v[166:169], v[214:217], v[92:95]
	v_mfma_f32_16x16x32_bf16 v[88:91], v[174:177], v[214:217], v[88:91]
	v_mfma_f32_16x16x32_bf16 v[76:79], v[166:169], v[222:225], v[76:79]
	v_mfma_f32_16x16x32_bf16 v[72:75], v[174:177], v[222:225], v[72:75]
	v_mfma_f32_16x16x32_bf16 v[116:119], v[178:181], v[194:197], v[116:119]
	v_mfma_f32_16x16x32_bf16 v[112:115], v[186:189], v[194:197], v[112:115]
	v_mfma_f32_16x16x32_bf16 v[100:103], v[178:181], v[202:205], v[100:103]
	v_mfma_f32_16x16x32_bf16 v[96:99], v[186:189], v[202:205], v[96:99]
	v_mfma_f32_16x16x32_bf16 v[84:87], v[178:181], v[210:213], v[84:87]
	v_mfma_f32_16x16x32_bf16 v[80:83], v[186:189], v[210:213], v[80:83]
	v_mfma_f32_16x16x32_bf16 v[68:71], v[178:181], v[218:221], v[68:71]
	v_mfma_f32_16x16x32_bf16 v[64:67], v[186:189], v[218:221], v[64:67]
	v_mfma_f32_16x16x32_bf16 v[116:119], v[182:185], v[198:201], v[116:119]
	v_mfma_f32_16x16x32_bf16 v[112:115], v[190:193], v[198:201], v[112:115]
	v_mfma_f32_16x16x32_bf16 v[100:103], v[182:185], v[206:209], v[100:103]
	v_mfma_f32_16x16x32_bf16 v[96:99], v[190:193], v[206:209], v[96:99]
	v_mfma_f32_16x16x32_bf16 v[84:87], v[182:185], v[214:217], v[84:87]
	v_mfma_f32_16x16x32_bf16 v[80:83], v[190:193], v[214:217], v[80:83]
	v_mfma_f32_16x16x32_bf16 v[68:71], v[182:185], v[222:225], v[68:71]
	v_mfma_f32_16x16x32_bf16 v[64:67], v[190:193], v[222:225], v[64:67]
	s_setprio 0
	s_barrier
; #define PG8_STAGE(bufoff, gbase, voff) do { _Pragma("unroll") for (int _i = 0; _i < 2; ++_i) \
;         __builtin_amdgcn_global_load_lds((const unsigned*)((const char*)(gbase) + (voff)[_i]), (PG8_LAS unsigned*)(lds + (bufoff) + ldsw + _i * 8192), 16, 0, 0); } while (0)
; #define PG8_LDA(dst, b, h) do { _Pragma("unroll") for (int m = 0; m < 4; ++m) _Pragma("unroll") for (int k = 0; k < 2; ++k) dst[m][k] = *(const PG8_LAS bf16x8*)(lds + PG8_SA(b, h) + aoff + m * 2048 + k * 1024); } while (0)
; #define PG8_MMA(ai, bj, At, Bt) do { __builtin_amdgcn_s_setprio(1); _Pragma("unroll") for (int m = 0; m < 4; ++m) _Pragma("unroll") for (int n = 0; n < 2; ++n) _Pragma("unroll") for (int k = 0; k < 2; ++k) \
;         acc[ai][bj][m][n] = __builtin_amdgcn_mfma_f32_16x16x32_bf16(Bt[n][k], At[m][k], acc[ai][bj][m][n], 0, 0, 0); __builtin_amdgcn_s_setprio(0); } while (0)
; #define PG8_WAIT_V(n) asm volatile("s_waitcnt vmcnt(" #n ")" ::: "memory")
; #define PG8_WAIT_L(n) asm volatile("s_waitcnt lgkmcnt(" #n ")" ::: "memory")
; #define PG8_BAR __builtin_amdgcn_s_barrier()
; #define PG8_SCHED __builtin_amdgcn_sched_barrier(0)
; template <class Epi, class Sched, bool ALIGN_EPI = false, bool SP2 = false>
; __device__ __forceinline__ void gemm_phase(PG8_LAS unsigned char* lds, const Gemm g, const Sched& S, const Epi& E) {
;     ...
;         for (int t = 0; t < nt; t += 2) {
;     ...
;             PG8_LDA(At, 1, 1); PG8_STAGE(PG8_SB(1, 0), b3, voffB); PG8_STAGE(PG8_SB(1, 1), b3 + hstepB, voffB); PG8_STAGE(PG8_SA(1, 0), a3, voffA);
;             PG8_WAIT_V(8); PG8_WAIT_L(0); PG8_BAR; PG8_MMA(1, 0, At, B0); PG8_MMA(1, 1, At, B1); PG8_BAR; PG8_SCHED;
	s_add_i32 s48, s71, s55
	v_lshl_add_u64 v[148:149], v[148:149], 0, s[14:15]
	s_mov_b32 m0, s48
	ds_read_b128 v[194:197], v165 offset:49152
	ds_read_b128 v[198:201], v165 offset:50176
	ds_read_b128 v[202:205], v165 offset:51200
	ds_read_b128 v[206:209], v165 offset:52224
	ds_read_b128 v[210:213], v165 offset:53248
	ds_read_b128 v[214:217], v165 offset:54272
	ds_read_b128 v[218:221], v165 offset:55296
	ds_read_b128 v[222:225], v165 offset:56320
	global_load_lds_dwordx4 v[148:149], off
	s_add_i32 m0, s48, 0x2000
	s_add_u32 s46, s46, 0x80080
	v_lshl_add_u64 v[148:149], v[226:227], 0, s[14:15]
	s_addc_u32 s47, s47, 0
	s_add_i32 s48, s72, s55
	global_load_lds_dwordx4 v[148:149], off
	v_lshl_add_u64 v[148:149], s[46:47], 0, v[130:131]
	s_mov_b32 m0, s48
	s_nop 0
	global_load_lds_dwordx4 v[148:149], off
	v_lshl_add_u64 v[148:149], s[46:47], 0, v[134:135]
	s_add_i32 m0, s48, 0x2000
	s_nop 0
	global_load_lds_dwordx4 v[148:149], off
	v_lshl_add_u64 v[148:149], v[228:229], 0, s[14:15]
	s_mov_b32 m0, s60
	s_nop 0
	global_load_lds_dwordx4 v[148:149], off
	v_lshl_add_u64 v[148:149], v[230:231], 0, s[14:15]
	s_mov_b32 m0, s61
	s_nop 0
	global_load_lds_dwordx4 v[148:149], off
	s_waitcnt vmcnt(8)
	s_waitcnt lgkmcnt(0)
	s_barrier
	s_setprio 1
	s_waitcnt lgkmcnt(0)
	v_mfma_f32_16x16x32_bf16 v[60:63], v[144:147], v[194:197], v[60:63]
	v_mfma_f32_16x16x32_bf16 v[56:59], v[170:173], v[194:197], v[56:59]
	v_mfma_f32_16x16x32_bf16 v[44:47], v[144:147], v[202:205], v[44:47]
	v_mfma_f32_16x16x32_bf16 v[40:43], v[170:173], v[202:205], v[40:43]
	v_mfma_f32_16x16x32_bf16 v[28:31], v[144:147], v[210:213], v[28:31]
	v_mfma_f32_16x16x32_bf16 v[24:27], v[170:173], v[210:213], v[24:27]
	v_mfma_f32_16x16x32_bf16 v[12:15], v[144:147], v[218:221], v[12:15]
	v_mfma_f32_16x16x32_bf16 v[8:11], v[170:173], v[218:221], v[8:11]
	v_mfma_f32_16x16x32_bf16 v[60:63], v[166:169], v[198:201], v[60:63]
	v_mfma_f32_16x16x32_bf16 v[56:59], v[174:177], v[198:201], v[56:59]
	v_mfma_f32_16x16x32_bf16 v[44:47], v[166:169], v[206:209], v[44:47]
	v_mfma_f32_16x16x32_bf16 v[40:43], v[174:177], v[206:209], v[40:43]
	v_mfma_f32_16x16x32_bf16 v[28:31], v[166:169], v[214:217], v[28:31]
	v_mfma_f32_16x16x32_bf16 v[24:27], v[174:177], v[214:217], v[24:27]
	v_mfma_f32_16x16x32_bf16 v[12:15], v[166:169], v[222:225], v[12:15]
	v_mfma_f32_16x16x32_bf16 v[8:11], v[174:177], v[222:225], v[8:11]
	v_mfma_f32_16x16x32_bf16 v[52:55], v[178:181], v[194:197], v[52:55]
	v_mfma_f32_16x16x32_bf16 v[48:51], v[186:189], v[194:197], v[48:51]
	v_mfma_f32_16x16x32_bf16 v[36:39], v[178:181], v[202:205], v[36:39]
	v_mfma_f32_16x16x32_bf16 v[32:35], v[186:189], v[202:205], v[32:35]
	v_mfma_f32_16x16x32_bf16 v[20:23], v[178:181], v[210:213], v[20:23]
	v_mfma_f32_16x16x32_bf16 v[16:19], v[186:189], v[210:213], v[16:19]
	v_mfma_f32_16x16x32_bf16 v[4:7], v[178:181], v[218:221], v[4:7]
	v_mfma_f32_16x16x32_bf16 v[0:3], v[186:189], v[218:221], v[0:3]
	v_mfma_f32_16x16x32_bf16 v[52:55], v[182:185], v[198:201], v[52:55]
	v_mfma_f32_16x16x32_bf16 v[48:51], v[190:193], v[198:201], v[48:51]
	v_mfma_f32_16x16x32_bf16 v[36:39], v[182:185], v[206:209], v[36:39]
	v_mfma_f32_16x16x32_bf16 v[32:35], v[190:193], v[206:209], v[32:35]
	v_mfma_f32_16x16x32_bf16 v[20:23], v[182:185], v[214:217], v[20:23]
	v_mfma_f32_16x16x32_bf16 v[16:19], v[190:193], v[214:217], v[16:19]
	v_mfma_f32_16x16x32_bf16 v[4:7], v[182:185], v[222:225], v[4:7]
	v_mfma_f32_16x16x32_bf16 v[0:3], v[190:193], v[222:225], v[0:3]
	s_setprio 0
	s_barrier
	s_add_i32 s70, s70, 2
	s_add_u32 s44, s44, 0x100
	s_addc_u32 s45, s45, 0
	s_add_u32 s68, s68, 0x100
	s_addc_u32 s69, s69, 0
	s_cmp_gt_u32 s70, 29
	s_cbranch_scc0 .LBB0_632
	s_and_b64 vcc, exec, s[16:17]
	s_cbranch_vccz .LBB0_635
	s_barrier

; #define PG8_STAGE(bufoff, gbase, voff) do { _Pragma("unroll") for (int _i = 0; _i < 2; ++_i) \
;         __builtin_amdgcn_global_load_lds((const unsigned*)((const char*)(gbase) + (voff)[_i]), (PG8_LAS unsigned*)(lds + (bufoff) + ldsw + _i * 8192), 16, 0, 0); } while (0)
; #define PG8_LDA(dst, b, h) do { _Pragma("unroll") for (int m = 0; m < 4; ++m) _Pragma("unroll") for (int k = 0; k < 2; ++k) dst[m][k] = *(const PG8_LAS bf16x8*)(lds + PG8_SA(b, h) + aoff + m * 2048 + k * 1024); } while (0)
; #define PG8_LDB(dst, b, h) do { _Pragma("unroll") for (int n = 0; n < 2; ++n) _Pragma("unroll") for (int k = 0; k < 2; ++k) dst[n][k] = *(const PG8_LAS bf16x8*)(lds + PG8_SB(b, h) + boff + n * 2048 + k * 1024); } while (0)
; #define PG8_MMA(ai, bj, At, Bt) do { __builtin_amdgcn_s_setprio(1); _Pragma("unroll") for (int m = 0; m < 4; ++m) _Pragma("unroll") for (int n = 0; n < 2; ++n) _Pragma("unroll") for (int k = 0; k < 2; ++k) \
;         acc[ai][bj][m][n] = __builtin_amdgcn_mfma_f32_16x16x32_bf16(Bt[n][k], At[m][k], acc[ai][bj][m][n], 0, 0, 0); __builtin_amdgcn_s_setprio(0); } while (0)
; #define PG8_WAIT_V(n) asm volatile("s_waitcnt vmcnt(" #n ")" ::: "memory")
; #define PG8_WAIT_L(n) asm volatile("s_waitcnt lgkmcnt(" #n ")" ::: "memory")
; #define PG8_BAR __builtin_amdgcn_s_barrier()
; #define PG8_SCHED __builtin_amdgcn_sched_barrier(0)
; template <class Epi, class Sched, bool ALIGN_EPI = false, bool SP2 = false>
; __device__ __forceinline__ void gemm_phase(PG8_LAS unsigned char* lds, const Gemm g, const Sched& S, const Epi& E) {
;     ...
;             PG8_LDB(B0, 0, 0); PG8_LDB(B1, 0, 1); PG8_SCHED; PG8_LDA(At, 0, 0); PG8_STAGE(PG8_SA(1, 1), a1 + hstepA, voffA);
;             PG8_WAIT_V(8); PG8_WAIT_L(0); PG8_BAR; PG8_MMA(0, 0, At, B0); PG8_MMA(0, 1, At, B1); PG8_BAR; PG8_SCHED;
;             PG8_LDA(At, 0, 1); PG8_STAGE(PG8_SB(0, 0), b2, voffB); PG8_STAGE(PG8_SB(0, 1), b2 + hstepB, voffB); PG8_STAGE(PG8_SA(0, 0), a2, voffA);
;             PG8_WAIT_V(8); PG8_WAIT_L(0); PG8_BAR; PG8_MMA(1, 0, At, B0); PG8_MMA(1, 1, At, B1); PG8_BAR; PG8_SCHED;
.LBB0_656:
	ds_read_b128 v[144:147], v150
	ds_read_b128 v[162:165], v150 offset:1024
	ds_read_b128 v[166:169], v150 offset:2048
	ds_read_b128 v[170:173], v150 offset:3072
	ds_read_b128 v[174:177], v151
	ds_read_b128 v[178:181], v151 offset:1024
	ds_read_b128 v[182:185], v151 offset:2048
	ds_read_b128 v[186:189], v151 offset:3072
	s_add_u32 s44, s42, 0xfff00080
	s_addc_u32 s45, s43, -1
	s_cmp_eq_u32 s68, 28
	s_cselect_b32 s47, s37, s45
	s_cselect_b32 s46, s64, s44
	s_cselect_b32 s45, s35, s67
	s_cselect_b32 s44, s65, s66
	v_lshl_add_u64 v[148:149], s[42:43], 0, v[136:137]
	s_add_i32 m0, s3, 0xc000
	ds_read_b128 v[190:193], v152
	ds_read_b128 v[194:197], v152 offset:1024
	ds_read_b128 v[198:201], v152 offset:2048
	ds_read_b128 v[202:205], v152 offset:3072
	ds_read_b128 v[206:209], v152 offset:4096
	ds_read_b128 v[210:213], v152 offset:5120
	ds_read_b128 v[214:217], v152 offset:6144
	ds_read_b128 v[218:221], v152 offset:7168
	global_load_lds_dwordx4 v[148:149], off
	v_lshl_add_u64 v[148:149], s[42:43], 0, v[138:139]
	s_add_i32 m0, s3, 0xe000
	s_nop 0
	global_load_lds_dwordx4 v[148:149], off
	s_waitcnt vmcnt(8)
	s_waitcnt lgkmcnt(0)
	s_barrier
	s_setprio 1
	s_waitcnt lgkmcnt(0)
	v_mfma_f32_16x16x32_bf16 v[124:127], v[144:147], v[190:193], v[124:127]
	v_mfma_f32_16x16x32_bf16 v[120:123], v[166:169], v[190:193], v[120:123]
	v_mfma_f32_16x16x32_bf16 v[108:111], v[144:147], v[198:201], v[108:111]
	v_mfma_f32_16x16x32_bf16 v[104:107], v[166:169], v[198:201], v[104:107]
	v_mfma_f32_16x16x32_bf16 v[92:95], v[144:147], v[206:209], v[92:95]
	v_mfma_f32_16x16x32_bf16 v[88:91], v[166:169], v[206:209], v[88:91]
	v_mfma_f32_16x16x32_bf16 v[76:79], v[144:147], v[214:217], v[76:79]
	v_mfma_f32_16x16x32_bf16 v[72:75], v[166:169], v[214:217], v[72:75]
	v_mfma_f32_16x16x32_bf16 v[124:127], v[162:165], v[194:197], v[124:127]
	v_mfma_f32_16x16x32_bf16 v[120:123], v[170:173], v[194:197], v[120:123]
	v_mfma_f32_16x16x32_bf16 v[108:111], v[162:165], v[202:205], v[108:111]
	v_mfma_f32_16x16x32_bf16 v[104:107], v[170:173], v[202:205], v[104:107]
	v_mfma_f32_16x16x32_bf16 v[92:95], v[162:165], v[210:213], v[92:95]
	v_mfma_f32_16x16x32_bf16 v[88:91], v[170:173], v[210:213], v[88:91]
	v_mfma_f32_16x16x32_bf16 v[76:79], v[162:165], v[218:221], v[76:79]
	v_mfma_f32_16x16x32_bf16 v[72:75], v[170:173], v[218:221], v[72:75]
	v_mfma_f32_16x16x32_bf16 v[116:119], v[174:177], v[190:193], v[116:119]
	v_mfma_f32_16x16x32_bf16 v[112:115], v[182:185], v[190:193], v[112:115]
	v_mfma_f32_16x16x32_bf16 v[100:103], v[174:177], v[198:201], v[100:103]
	v_mfma_f32_16x16x32_bf16 v[96:99], v[182:185], v[198:201], v[96:99]
	v_mfma_f32_16x16x32_bf16 v[84:87], v[174:177], v[206:209], v[84:87]
	v_mfma_f32_16x16x32_bf16 v[80:83], v[182:185], v[206:209], v[80:83]
	v_mfma_f32_16x16x32_bf16 v[68:71], v[174:177], v[214:217], v[68:71]
	v_mfma_f32_16x16x32_bf16 v[64:67], v[182:185], v[214:217], v[64:67]
	v_mfma_f32_16x16x32_bf16 v[116:119], v[178:181], v[194:197], v[116:119]
	v_mfma_f32_16x16x32_bf16 v[112:115], v[186:189], v[194:197], v[112:115]
	v_mfma_f32_16x16x32_bf16 v[100:103], v[178:181], v[202:205], v[100:103]
	v_mfma_f32_16x16x32_bf16 v[96:99], v[186:189], v[202:205], v[96:99]
	v_mfma_f32_16x16x32_bf16 v[84:87], v[178:181], v[210:213], v[84:87]
	v_mfma_f32_16x16x32_bf16 v[80:83], v[186:189], v[210:213], v[80:83]
	v_mfma_f32_16x16x32_bf16 v[68:71], v[178:181], v[218:221], v[68:71]
	v_mfma_f32_16x16x32_bf16 v[64:67], v[186:189], v[218:221], v[64:67]
	s_setprio 0
	s_barrier
	s_add_i32 s69, s61, s51
	v_lshl_add_u64 v[148:149], s[44:45], 0, v[130:131]
	s_mov_b32 m0, s69
	ds_read_b128 v[190:193], v152 offset:16384
	ds_read_b128 v[194:197], v152 offset:17408
	ds_read_b128 v[198:201], v152 offset:18432
	ds_read_b128 v[202:205], v152 offset:19456
	ds_read_b128 v[206:209], v152 offset:20480
	ds_read_b128 v[210:213], v152 offset:21504
	ds_read_b128 v[214:217], v152 offset:22528
	ds_read_b128 v[218:221], v152 offset:23552
	global_load_lds_dwordx4 v[148:149], off
	s_add_i32 m0, s69, 0x2000
	s_add_u32 s70, s44, 0x80000
	v_lshl_add_u64 v[158:159], s[44:45], 0, v[134:135]
	s_addc_u32 s71, s45, 0
	s_add_i32 s69, s62, s51
	global_load_lds_dwordx4 v[158:159], off
	v_lshl_add_u64 v[222:223], s[70:71], 0, v[130:131]
	s_mov_b32 m0, s69
	v_lshl_add_u64 v[224:225], s[46:47], 0, v[132:133]
	global_load_lds_dwordx4 v[222:223], off
	v_lshl_add_u64 v[222:223], s[70:71], 0, v[134:135]
	s_add_i32 m0, s69, 0x2000
	s_nop 0
	global_load_lds_dwordx4 v[222:223], off
	v_lshl_add_u64 v[222:223], s[46:47], 0, v[128:129]
	s_mov_b32 m0, s3
	s_nop 0
	global_load_lds_dwordx4 v[222:223], off
	s_mov_b32 m0, s54
	s_nop 0
	global_load_lds_dwordx4 v[224:225], off
	s_waitcnt vmcnt(8)
	s_waitcnt lgkmcnt(0)
	s_barrier
; #define PG8_STAGE(bufoff, gbase, voff) do { _Pragma("unroll") for (int _i = 0; _i < 2; ++_i) \
;         __builtin_amdgcn_global_load_lds((const unsigned*)((const char*)(gbase) + (voff)[_i]), (PG8_LAS unsigned*)(lds + (bufoff) + ldsw + _i * 8192), 16, 0, 0); } while (0)
; #define PG8_LDA(dst, b, h) do { _Pragma("unroll") for (int m = 0; m < 4; ++m) _Pragma("unroll") for (int k = 0; k < 2; ++k) dst[m][k] = *(const PG8_LAS bf16x8*)(lds + PG8_SA(b, h) + aoff + m * 2048 + k * 1024); } while (0)
; #define PG8_LDB(dst, b, h) do { _Pragma("unroll") for (int n = 0; n < 2; ++n) _Pragma("unroll") for (int k = 0; k < 2; ++k) dst[n][k] = *(const PG8_LAS bf16x8*)(lds + PG8_SB(b, h) + boff + n * 2048 + k * 1024); } while (0)
; #define PG8_MMA(ai, bj, At, Bt) do { __builtin_amdgcn_s_setprio(1); _Pragma("unroll") for (int m = 0; m < 4; ++m) _Pragma("unroll") for (int n = 0; n < 2; ++n) _Pragma("unroll") for (int k = 0; k < 2; ++k) \
;         acc[ai][bj][m][n] = __builtin_amdgcn_mfma_f32_16x16x32_bf16(Bt[n][k], At[m][k], acc[ai][bj][m][n], 0, 0, 0); __builtin_amdgcn_s_setprio(0); } while (0)
; #define PG8_WAIT_V(n) asm volatile("s_waitcnt vmcnt(" #n ")" ::: "memory")
; #define PG8_WAIT_L(n) asm volatile("s_waitcnt lgkmcnt(" #n ")" ::: "memory")
; #define PG8_BAR __builtin_amdgcn_s_barrier()
; #define PG8_SCHED __builtin_amdgcn_sched_barrier(0)
; template <class Epi, class Sched, bool ALIGN_EPI = false, bool SP2 = false>
; __device__ __forceinline__ void gemm_phase(PG8_LAS unsigned char* lds, const Gemm g, const Sched& S, const Epi& E) {
;     ...
;             PG8_WAIT_V(8); PG8_WAIT_L(0); PG8_BAR; PG8_MMA(1, 0, At, B0); PG8_MMA(1, 1, At, B1); PG8_BAR; PG8_SCHED;
;             PG8_LDB(B0, 1, 0); PG8_LDB(B1, 1, 1); PG8_SCHED; PG8_LDA(At, 1, 0); PG8_STAGE(PG8_SA(0, 1), a2 + hstepA, voffA);
;             PG8_WAIT_V(8); PG8_WAIT_L(0); PG8_BAR; PG8_MMA(0, 0, At, B0); PG8_MMA(0, 1, At, B1); PG8_BAR; PG8_SCHED;
	s_setprio 1
	s_waitcnt lgkmcnt(0)
	v_mfma_f32_16x16x32_bf16 v[60:63], v[144:147], v[190:193], v[60:63]
	v_mfma_f32_16x16x32_bf16 v[56:59], v[166:169], v[190:193], v[56:59]
	v_mfma_f32_16x16x32_bf16 v[44:47], v[144:147], v[198:201], v[44:47]
	v_mfma_f32_16x16x32_bf16 v[40:43], v[166:169], v[198:201], v[40:43]
	v_mfma_f32_16x16x32_bf16 v[28:31], v[144:147], v[206:209], v[28:31]
	v_mfma_f32_16x16x32_bf16 v[24:27], v[166:169], v[206:209], v[24:27]
	v_mfma_f32_16x16x32_bf16 v[12:15], v[144:147], v[214:217], v[12:15]
	v_mfma_f32_16x16x32_bf16 v[8:11], v[166:169], v[214:217], v[8:11]
	v_mfma_f32_16x16x32_bf16 v[60:63], v[162:165], v[194:197], v[60:63]
	v_mfma_f32_16x16x32_bf16 v[56:59], v[170:173], v[194:197], v[56:59]
	v_mfma_f32_16x16x32_bf16 v[44:47], v[162:165], v[202:205], v[44:47]
	v_mfma_f32_16x16x32_bf16 v[40:43], v[170:173], v[202:205], v[40:43]
	v_mfma_f32_16x16x32_bf16 v[28:31], v[162:165], v[210:213], v[28:31]
	v_mfma_f32_16x16x32_bf16 v[24:27], v[170:173], v[210:213], v[24:27]
	v_mfma_f32_16x16x32_bf16 v[12:15], v[162:165], v[218:221], v[12:15]
	v_mfma_f32_16x16x32_bf16 v[8:11], v[170:173], v[218:221], v[8:11]
	v_mfma_f32_16x16x32_bf16 v[52:55], v[174:177], v[190:193], v[52:55]
	v_mfma_f32_16x16x32_bf16 v[48:51], v[182:185], v[190:193], v[48:51]
	v_mfma_f32_16x16x32_bf16 v[36:39], v[174:177], v[198:201], v[36:39]
	v_mfma_f32_16x16x32_bf16 v[32:35], v[182:185], v[198:201], v[32:35]
	v_mfma_f32_16x16x32_bf16 v[20:23], v[174:177], v[206:209], v[20:23]
	v_mfma_f32_16x16x32_bf16 v[16:19], v[182:185], v[206:209], v[16:19]
	v_mfma_f32_16x16x32_bf16 v[4:7], v[174:177], v[214:217], v[4:7]
	v_mfma_f32_16x16x32_bf16 v[0:3], v[182:185], v[214:217], v[0:3]
	v_mfma_f32_16x16x32_bf16 v[52:55], v[178:181], v[194:197], v[52:55]
	v_mfma_f32_16x16x32_bf16 v[48:51], v[186:189], v[194:197], v[48:51]
	v_mfma_f32_16x16x32_bf16 v[36:39], v[178:181], v[202:205], v[36:39]
	v_mfma_f32_16x16x32_bf16 v[32:35], v[186:189], v[202:205], v[32:35]
	v_mfma_f32_16x16x32_bf16 v[20:23], v[178:181], v[210:213], v[20:23]
	v_mfma_f32_16x16x32_bf16 v[16:19], v[186:189], v[210:213], v[16:19]
	v_mfma_f32_16x16x32_bf16 v[4:7], v[178:181], v[218:221], v[4:7]
	v_mfma_f32_16x16x32_bf16 v[0:3], v[186:189], v[218:221], v[0:3]
	s_setprio 0
	s_barrier
	s_add_i32 s69, 0, 0x18000
	v_add_u32_e32 v154, s69, v155
	s_add_i32 s70, 0, 0x1c000
	ds_read_b128 v[144:147], v154
	ds_read_b128 v[162:165], v154 offset:1024
	ds_read_b128 v[166:169], v154 offset:2048
	ds_read_b128 v[170:173], v154 offset:3072
	v_add_u32_e32 v154, s70, v155
	ds_read_b128 v[174:177], v154
	ds_read_b128 v[178:181], v154 offset:1024
	ds_read_b128 v[182:185], v154 offset:2048
	ds_read_b128 v[186:189], v154 offset:3072
	s_add_u32 s46, s46, 0x100000
	s_addc_u32 s47, s47, 0
	s_mov_b32 m0, s55
	v_lshl_add_u64 v[226:227], s[46:47], 0, v[128:129]
	ds_read_b128 v[190:193], v152 offset:32768
	ds_read_b128 v[194:197], v152 offset:33792
	ds_read_b128 v[198:201], v152 offset:34816
	ds_read_b128 v[202:205], v152 offset:35840
	ds_read_b128 v[206:209], v152 offset:36864
	ds_read_b128 v[210:213], v152 offset:37888
	ds_read_b128 v[214:217], v152 offset:38912
	ds_read_b128 v[218:221], v152 offset:39936
	global_load_lds_dwordx4 v[226:227], off
	v_lshl_add_u64 v[226:227], s[46:47], 0, v[132:133]
	s_mov_b32 m0, s56
	s_nop 0
	global_load_lds_dwordx4 v[226:227], off
	s_waitcnt vmcnt(8)
	s_waitcnt lgkmcnt(0)
	s_barrier
	s_setprio 1
	s_waitcnt lgkmcnt(0)
	v_mfma_f32_16x16x32_bf16 v[124:127], v[144:147], v[190:193], v[124:127]
	v_mfma_f32_16x16x32_bf16 v[120:123], v[166:169], v[190:193], v[120:123]
	v_mfma_f32_16x16x32_bf16 v[108:111], v[144:147], v[198:201], v[108:111]
	v_mfma_f32_16x16x32_bf16 v[104:107], v[166:169], v[198:201], v[104:107]
	v_mfma_f32_16x16x32_bf16 v[92:95], v[144:147], v[206:209], v[92:95]
	v_mfma_f32_16x16x32_bf16 v[88:91], v[166:169], v[206:209], v[88:91]
	v_mfma_f32_16x16x32_bf16 v[76:79], v[144:147], v[214:217], v[76:79]
	v_mfma_f32_16x16x32_bf16 v[72:75], v[166:169], v[214:217], v[72:75]
	v_mfma_f32_16x16x32_bf16 v[124:127], v[162:165], v[194:197], v[124:127]
	v_mfma_f32_16x16x32_bf16 v[120:123], v[170:173], v[194:197], v[120:123]
	v_mfma_f32_16x16x32_bf16 v[108:111], v[162:165], v[202:205], v[108:111]
	v_mfma_f32_16x16x32_bf16 v[104:107], v[170:173], v[202:205], v[104:107]
	v_mfma_f32_16x16x32_bf16 v[92:95], v[162:165], v[210:213], v[92:95]
	v_mfma_f32_16x16x32_bf16 v[88:91], v[170:173], v[210:213], v[88:91]
	v_mfma_f32_16x16x32_bf16 v[76:79], v[162:165], v[218:221], v[76:79]
	v_mfma_f32_16x16x32_bf16 v[72:75], v[170:173], v[218:221], v[72:75]
	v_mfma_f32_16x16x32_bf16 v[116:119], v[174:177], v[190:193], v[116:119]
	v_mfma_f32_16x16x32_bf16 v[112:115], v[182:185], v[190:193], v[112:115]
	v_mfma_f32_16x16x32_bf16 v[100:103], v[174:177], v[198:201], v[100:103]
	v_mfma_f32_16x16x32_bf16 v[96:99], v[182:185], v[198:201], v[96:99]
	v_mfma_f32_16x16x32_bf16 v[84:87], v[174:177], v[206:209], v[84:87]
	v_mfma_f32_16x16x32_bf16 v[80:83], v[182:185], v[206:209], v[80:83]
	v_mfma_f32_16x16x32_bf16 v[68:71], v[174:177], v[214:217], v[68:71]
	v_mfma_f32_16x16x32_bf16 v[64:67], v[182:185], v[214:217], v[64:67]
	v_mfma_f32_16x16x32_bf16 v[116:119], v[178:181], v[194:197], v[116:119]
	v_mfma_f32_16x16x32_bf16 v[112:115], v[186:189], v[194:197], v[112:115]
	v_mfma_f32_16x16x32_bf16 v[100:103], v[178:181], v[202:205], v[100:103]
	v_mfma_f32_16x16x32_bf16 v[96:99], v[186:189], v[202:205], v[96:99]
	v_mfma_f32_16x16x32_bf16 v[84:87], v[178:181], v[210:213], v[84:87]
	v_mfma_f32_16x16x32_bf16 v[80:83], v[186:189], v[210:213], v[80:83]
	v_mfma_f32_16x16x32_bf16 v[68:71], v[178:181], v[218:221], v[68:71]
	v_mfma_f32_16x16x32_bf16 v[64:67], v[186:189], v[218:221], v[64:67]
	s_setprio 0
	s_barrier
; #define PG8_STAGE(bufoff, gbase, voff) do { _Pragma("unroll") for (int _i = 0; _i < 2; ++_i) \
;         __builtin_amdgcn_global_load_lds((const unsigned*)((const char*)(gbase) + (voff)[_i]), (PG8_LAS unsigned*)(lds + (bufoff) + ldsw + _i * 8192), 16, 0, 0); } while (0)
; #define PG8_LDA(dst, b, h) do { _Pragma("unroll") for (int m = 0; m < 4; ++m) _Pragma("unroll") for (int k = 0; k < 2; ++k) dst[m][k] = *(const PG8_LAS bf16x8*)(lds + PG8_SA(b, h) + aoff + m * 2048 + k * 1024); } while (0)
; #define PG8_MMA(ai, bj, At, Bt) do { __builtin_amdgcn_s_setprio(1); _Pragma("unroll") for (int m = 0; m < 4; ++m) _Pragma("unroll") for (int n = 0; n < 2; ++n) _Pragma("unroll") for (int k = 0; k < 2; ++k) \
;         acc[ai][bj][m][n] = __builtin_amdgcn_mfma_f32_16x16x32_bf16(Bt[n][k], At[m][k], acc[ai][bj][m][n], 0, 0, 0); __builtin_amdgcn_s_setprio(0); } while (0)
; #define PG8_WAIT_V(n) asm volatile("s_waitcnt vmcnt(" #n ")" ::: "memory")
; #define PG8_WAIT_L(n) asm volatile("s_waitcnt lgkmcnt(" #n ")" ::: "memory")
; #define PG8_BAR __builtin_amdgcn_s_barrier()
; #define PG8_SCHED __builtin_amdgcn_sched_barrier(0)
; template <class Epi, class Sched, bool ALIGN_EPI = false, bool SP2 = false>
; __device__ __forceinline__ void gemm_phase(PG8_LAS unsigned char* lds, const Gemm g, const Sched& S, const Epi& E) {
;     ...
;         for (int t = 0; t < nt; t += 2) {
;     ...
;             PG8_LDA(At, 1, 1); PG8_STAGE(PG8_SB(1, 0), b3, voffB); PG8_STAGE(PG8_SB(1, 1), b3 + hstepB, voffB); PG8_STAGE(PG8_SA(1, 0), a3, voffA);
;             PG8_WAIT_V(8); PG8_WAIT_L(0); PG8_BAR; PG8_MMA(1, 0, At, B0); PG8_MMA(1, 1, At, B1); PG8_BAR; PG8_SCHED;
	s_add_i32 s46, s69, s51
	v_lshl_add_u64 v[148:149], v[148:149], 0, s[14:15]
	s_mov_b32 m0, s46
	ds_read_b128 v[190:193], v152 offset:49152
	ds_read_b128 v[194:197], v152 offset:50176
	ds_read_b128 v[198:201], v152 offset:51200
	ds_read_b128 v[202:205], v152 offset:52224
	ds_read_b128 v[206:209], v152 offset:53248
	ds_read_b128 v[210:213], v152 offset:54272
	ds_read_b128 v[214:217], v152 offset:55296
	ds_read_b128 v[218:221], v152 offset:56320
	global_load_lds_dwordx4 v[148:149], off
	s_add_i32 m0, s46, 0x2000
	s_add_u32 s44, s44, 0x80080
	v_lshl_add_u64 v[148:149], v[158:159], 0, s[14:15]
	s_addc_u32 s45, s45, 0
	s_add_i32 s46, s70, s51
	global_load_lds_dwordx4 v[148:149], off
	v_lshl_add_u64 v[148:149], s[44:45], 0, v[130:131]
	s_mov_b32 m0, s46
	s_nop 0
	global_load_lds_dwordx4 v[148:149], off
	v_lshl_add_u64 v[148:149], s[44:45], 0, v[134:135]
	s_add_i32 m0, s46, 0x2000
	s_nop 0
	global_load_lds_dwordx4 v[148:149], off
	v_lshl_add_u64 v[148:149], v[222:223], 0, s[14:15]
	s_mov_b32 m0, s58
	s_nop 0
	global_load_lds_dwordx4 v[148:149], off
	v_lshl_add_u64 v[148:149], v[224:225], 0, s[14:15]
	s_mov_b32 m0, s59
	s_nop 0
	global_load_lds_dwordx4 v[148:149], off
	s_waitcnt vmcnt(8)
	s_waitcnt lgkmcnt(0)
	s_barrier
	s_setprio 1
	s_waitcnt lgkmcnt(0)
	v_mfma_f32_16x16x32_bf16 v[60:63], v[144:147], v[190:193], v[60:63]
	v_mfma_f32_16x16x32_bf16 v[56:59], v[166:169], v[190:193], v[56:59]
	v_mfma_f32_16x16x32_bf16 v[44:47], v[144:147], v[198:201], v[44:47]
	v_mfma_f32_16x16x32_bf16 v[40:43], v[166:169], v[198:201], v[40:43]
	v_mfma_f32_16x16x32_bf16 v[28:31], v[144:147], v[206:209], v[28:31]
	v_mfma_f32_16x16x32_bf16 v[24:27], v[166:169], v[206:209], v[24:27]
	v_mfma_f32_16x16x32_bf16 v[12:15], v[144:147], v[214:217], v[12:15]
	v_mfma_f32_16x16x32_bf16 v[8:11], v[166:169], v[214:217], v[8:11]
	v_mfma_f32_16x16x32_bf16 v[60:63], v[162:165], v[194:197], v[60:63]
	v_mfma_f32_16x16x32_bf16 v[56:59], v[170:173], v[194:197], v[56:59]
	v_mfma_f32_16x16x32_bf16 v[44:47], v[162:165], v[202:205], v[44:47]
	v_mfma_f32_16x16x32_bf16 v[40:43], v[170:173], v[202:205], v[40:43]
	v_mfma_f32_16x16x32_bf16 v[28:31], v[162:165], v[210:213], v[28:31]
	v_mfma_f32_16x16x32_bf16 v[24:27], v[170:173], v[210:213], v[24:27]
	v_mfma_f32_16x16x32_bf16 v[12:15], v[162:165], v[218:221], v[12:15]
	v_mfma_f32_16x16x32_bf16 v[8:11], v[170:173], v[218:221], v[8:11]
	v_mfma_f32_16x16x32_bf16 v[52:55], v[174:177], v[190:193], v[52:55]
	v_mfma_f32_16x16x32_bf16 v[48:51], v[182:185], v[190:193], v[48:51]
	v_mfma_f32_16x16x32_bf16 v[36:39], v[174:177], v[198:201], v[36:39]
	v_mfma_f32_16x16x32_bf16 v[32:35], v[182:185], v[198:201], v[32:35]
	v_mfma_f32_16x16x32_bf16 v[20:23], v[174:177], v[206:209], v[20:23]
	v_mfma_f32_16x16x32_bf16 v[16:19], v[182:185], v[206:209], v[16:19]
	v_mfma_f32_16x16x32_bf16 v[4:7], v[174:177], v[214:217], v[4:7]
	v_mfma_f32_16x16x32_bf16 v[0:3], v[182:185], v[214:217], v[0:3]
	v_mfma_f32_16x16x32_bf16 v[52:55], v[178:181], v[194:197], v[52:55]
	v_mfma_f32_16x16x32_bf16 v[48:51], v[186:189], v[194:197], v[48:51]
	v_mfma_f32_16x16x32_bf16 v[36:39], v[178:181], v[202:205], v[36:39]
	v_mfma_f32_16x16x32_bf16 v[32:35], v[186:189], v[202:205], v[32:35]
	v_mfma_f32_16x16x32_bf16 v[20:23], v[178:181], v[210:213], v[20:23]
	v_mfma_f32_16x16x32_bf16 v[16:19], v[186:189], v[210:213], v[16:19]
	v_mfma_f32_16x16x32_bf16 v[4:7], v[178:181], v[218:221], v[4:7]
	v_mfma_f32_16x16x32_bf16 v[0:3], v[186:189], v[218:221], v[0:3]
	s_setprio 0
	s_barrier
	s_add_i32 s68, s68, 2
	s_add_u32 s42, s42, 0x100
	s_addc_u32 s43, s43, 0
	s_add_u32 s66, s66, 0x100
	s_addc_u32 s67, s67, 0
	s_cmp_gt_u32 s68, 29
	s_cbranch_scc0 .LBB0_656
	s_and_b64 vcc, exec, s[16:17]
	s_cbranch_vccz .LBB0_659
	s_barrier

; #define PG8_STAGE(bufoff, gbase, voff) do { _Pragma("unroll") for (int _i = 0; _i < 2; ++_i) \
;         __builtin_amdgcn_global_load_lds((const unsigned*)((const char*)(gbase) + (voff)[_i]), (PG8_LAS unsigned*)(lds + (bufoff) + ldsw + _i * 8192), 16, 0, 0); } while (0)
; #define PG8_LDA(dst, b, h) do { _Pragma("unroll") for (int m = 0; m < 4; ++m) _Pragma("unroll") for (int k = 0; k < 2; ++k) dst[m][k] = *(const PG8_LAS bf16x8*)(lds + PG8_SA(b, h) + aoff + m * 2048 + k * 1024); } while (0)
; #define PG8_LDB(dst, b, h) do { _Pragma("unroll") for (int n = 0; n < 2; ++n) _Pragma("unroll") for (int k = 0; k < 2; ++k) dst[n][k] = *(const PG8_LAS bf16x8*)(lds + PG8_SB(b, h) + boff + n * 2048 + k * 1024); } while (0)
; #define PG8_MMA(ai, bj, At, Bt) do { __builtin_amdgcn_s_setprio(1); _Pragma("unroll") for (int m = 0; m < 4; ++m) _Pragma("unroll") for (int n = 0; n < 2; ++n) _Pragma("unroll") for (int k = 0; k < 2; ++k) \
;         acc[ai][bj][m][n] = __builtin_amdgcn_mfma_f32_16x16x32_bf16(Bt[n][k], At[m][k], acc[ai][bj][m][n], 0, 0, 0); __builtin_amdgcn_s_setprio(0); } while (0)
; #define PG8_WAIT_V(n) asm volatile("s_waitcnt vmcnt(" #n ")" ::: "memory")
; #define PG8_WAIT_L(n) asm volatile("s_waitcnt lgkmcnt(" #n ")" ::: "memory")
; #define PG8_BAR __builtin_amdgcn_s_barrier()
; #define PG8_SCHED __builtin_amdgcn_sched_barrier(0)
; template <class Epi, class Sched, bool ALIGN_EPI = false, bool SP2 = false>
; __device__ __forceinline__ void gemm_phase(PG8_LAS unsigned char* lds, const Gemm g, const Sched& S, const Epi& E) {
;     ...
;             PG8_LDB(B0, 0, 0); PG8_LDB(B1, 0, 1); PG8_SCHED; PG8_LDA(At, 0, 0); PG8_STAGE(PG8_SA(1, 1), a1 + hstepA, voffA);
;             PG8_WAIT_V(8); PG8_WAIT_L(0); PG8_BAR; PG8_MMA(0, 0, At, B0); PG8_MMA(0, 1, At, B1); PG8_BAR; PG8_SCHED;
;             PG8_LDA(At, 0, 1); PG8_STAGE(PG8_SB(0, 0), b2, voffB); PG8_STAGE(PG8_SB(0, 1), b2 + hstepB, voffB); PG8_STAGE(PG8_SA(0, 0), a2, voffA);
;             PG8_WAIT_V(8); PG8_WAIT_L(0); PG8_BAR; PG8_MMA(1, 0, At, B0); PG8_MMA(1, 1, At, B1); PG8_BAR; PG8_SCHED;
.LBB0_733:
	ds_read_b128 v[140:143], v149
	ds_read_b128 v[158:161], v149 offset:1024
	ds_read_b128 v[162:165], v149 offset:2048
	ds_read_b128 v[166:169], v149 offset:3072
	ds_read_b128 v[170:173], v150
	ds_read_b128 v[174:177], v150 offset:1024
	ds_read_b128 v[178:181], v150 offset:2048
	ds_read_b128 v[182:185], v150 offset:3072
	s_add_u32 s30, s28, 0xfff80080
	s_addc_u32 s31, s29, -1
	s_cmp_eq_u32 s56, 28
	s_cselect_b32 s35, s3, s31
	s_cselect_b32 s34, s21, s30
	s_cselect_b32 s31, s19, s55
	s_cselect_b32 s30, s51, s54
	v_lshl_add_u64 v[144:145], s[28:29], 0, v[132:133]
	s_add_i32 m0, s27, 0xc000
	ds_read_b128 v[186:189], v151
	ds_read_b128 v[190:193], v151 offset:1024
	ds_read_b128 v[194:197], v151 offset:2048
	ds_read_b128 v[198:201], v151 offset:3072
	ds_read_b128 v[202:205], v151 offset:4096
	ds_read_b128 v[206:209], v151 offset:5120
	ds_read_b128 v[210:213], v151 offset:6144
	ds_read_b128 v[214:217], v151 offset:7168
	global_load_lds_dwordx4 v[144:145], off
	v_lshl_add_u64 v[144:145], s[28:29], 0, v[134:135]
	s_add_i32 m0, s27, 0xe000
	s_nop 0
	global_load_lds_dwordx4 v[144:145], off
	s_waitcnt vmcnt(8)
	s_waitcnt lgkmcnt(0)
	s_barrier
	s_setprio 1
	s_waitcnt lgkmcnt(0)
	v_mfma_f32_16x16x32_bf16 v[124:127], v[140:143], v[186:189], v[124:127]
	v_mfma_f32_16x16x32_bf16 v[120:123], v[162:165], v[186:189], v[120:123]
	v_mfma_f32_16x16x32_bf16 v[108:111], v[140:143], v[194:197], v[108:111]
	v_mfma_f32_16x16x32_bf16 v[104:107], v[162:165], v[194:197], v[104:107]
	v_mfma_f32_16x16x32_bf16 v[92:95], v[140:143], v[202:205], v[92:95]
	v_mfma_f32_16x16x32_bf16 v[88:91], v[162:165], v[202:205], v[88:91]
	v_mfma_f32_16x16x32_bf16 v[76:79], v[140:143], v[210:213], v[76:79]
	v_mfma_f32_16x16x32_bf16 v[72:75], v[162:165], v[210:213], v[72:75]
	v_mfma_f32_16x16x32_bf16 v[124:127], v[158:161], v[190:193], v[124:127]
	v_mfma_f32_16x16x32_bf16 v[120:123], v[166:169], v[190:193], v[120:123]
	v_mfma_f32_16x16x32_bf16 v[108:111], v[158:161], v[198:201], v[108:111]
	v_mfma_f32_16x16x32_bf16 v[104:107], v[166:169], v[198:201], v[104:107]
	v_mfma_f32_16x16x32_bf16 v[92:95], v[158:161], v[206:209], v[92:95]
	v_mfma_f32_16x16x32_bf16 v[88:91], v[166:169], v[206:209], v[88:91]
	v_mfma_f32_16x16x32_bf16 v[76:79], v[158:161], v[214:217], v[76:79]
	v_mfma_f32_16x16x32_bf16 v[72:75], v[166:169], v[214:217], v[72:75]
	v_mfma_f32_16x16x32_bf16 v[116:119], v[170:173], v[186:189], v[116:119]
	v_mfma_f32_16x16x32_bf16 v[112:115], v[178:181], v[186:189], v[112:115]
	v_mfma_f32_16x16x32_bf16 v[100:103], v[170:173], v[194:197], v[100:103]
	v_mfma_f32_16x16x32_bf16 v[96:99], v[178:181], v[194:197], v[96:99]
	v_mfma_f32_16x16x32_bf16 v[84:87], v[170:173], v[202:205], v[84:87]
	v_mfma_f32_16x16x32_bf16 v[80:83], v[178:181], v[202:205], v[80:83]
	v_mfma_f32_16x16x32_bf16 v[68:71], v[170:173], v[210:213], v[68:71]
	v_mfma_f32_16x16x32_bf16 v[64:67], v[178:181], v[210:213], v[64:67]
	v_mfma_f32_16x16x32_bf16 v[116:119], v[174:177], v[190:193], v[116:119]
	v_mfma_f32_16x16x32_bf16 v[112:115], v[182:185], v[190:193], v[112:115]
	v_mfma_f32_16x16x32_bf16 v[100:103], v[174:177], v[198:201], v[100:103]
	v_mfma_f32_16x16x32_bf16 v[96:99], v[182:185], v[198:201], v[96:99]
	v_mfma_f32_16x16x32_bf16 v[84:87], v[174:177], v[206:209], v[84:87]
	v_mfma_f32_16x16x32_bf16 v[80:83], v[182:185], v[206:209], v[80:83]
	v_mfma_f32_16x16x32_bf16 v[68:71], v[174:177], v[214:217], v[68:71]
	v_mfma_f32_16x16x32_bf16 v[64:67], v[182:185], v[214:217], v[64:67]
	s_setprio 0
	s_barrier
	s_add_i32 s57, s49, s40
	v_lshl_add_u64 v[144:145], s[30:31], 0, v[128:129]
	s_mov_b32 m0, s57
	ds_read_b128 v[186:189], v151 offset:16384
	ds_read_b128 v[190:193], v151 offset:17408
	ds_read_b128 v[194:197], v151 offset:18432
	ds_read_b128 v[198:201], v151 offset:19456
	ds_read_b128 v[202:205], v151 offset:20480
	ds_read_b128 v[206:209], v151 offset:21504
	ds_read_b128 v[210:213], v151 offset:22528
	ds_read_b128 v[214:217], v151 offset:23552
	global_load_lds_dwordx4 v[144:145], off
	s_add_i32 m0, s57, 0x2000
	s_add_u32 s58, s30, 0x80000
	v_lshl_add_u64 v[154:155], s[30:31], 0, v[130:131]
	s_addc_u32 s59, s31, 0
	s_add_i32 s57, s50, s40
	global_load_lds_dwordx4 v[154:155], off
	v_lshl_add_u64 v[218:219], s[58:59], 0, v[128:129]
	s_mov_b32 m0, s57
	v_lshl_add_u64 v[220:221], s[34:35], 0, v[130:131]
	global_load_lds_dwordx4 v[218:219], off
	v_lshl_add_u64 v[218:219], s[58:59], 0, v[130:131]
	s_add_i32 m0, s57, 0x2000
	s_nop 0
	global_load_lds_dwordx4 v[218:219], off
	v_lshl_add_u64 v[218:219], s[34:35], 0, v[128:129]
	s_mov_b32 m0, s27
	s_nop 0
	global_load_lds_dwordx4 v[218:219], off
	s_mov_b32 m0, s41
	s_nop 0
	global_load_lds_dwordx4 v[220:221], off
	s_waitcnt vmcnt(8)
	s_waitcnt lgkmcnt(0)
	s_barrier
; #define PG8_STAGE(bufoff, gbase, voff) do { _Pragma("unroll") for (int _i = 0; _i < 2; ++_i) \
;         __builtin_amdgcn_global_load_lds((const unsigned*)((const char*)(gbase) + (voff)[_i]), (PG8_LAS unsigned*)(lds + (bufoff) + ldsw + _i * 8192), 16, 0, 0); } while (0)
; #define PG8_LDA(dst, b, h) do { _Pragma("unroll") for (int m = 0; m < 4; ++m) _Pragma("unroll") for (int k = 0; k < 2; ++k) dst[m][k] = *(const PG8_LAS bf16x8*)(lds + PG8_SA(b, h) + aoff + m * 2048 + k * 1024); } while (0)
; #define PG8_LDB(dst, b, h) do { _Pragma("unroll") for (int n = 0; n < 2; ++n) _Pragma("unroll") for (int k = 0; k < 2; ++k) dst[n][k] = *(const PG8_LAS bf16x8*)(lds + PG8_SB(b, h) + boff + n * 2048 + k * 1024); } while (0)
; #define PG8_MMA(ai, bj, At, Bt) do { __builtin_amdgcn_s_setprio(1); _Pragma("unroll") for (int m = 0; m < 4; ++m) _Pragma("unroll") for (int n = 0; n < 2; ++n) _Pragma("unroll") for (int k = 0; k < 2; ++k) \
;         acc[ai][bj][m][n] = __builtin_amdgcn_mfma_f32_16x16x32_bf16(Bt[n][k], At[m][k], acc[ai][bj][m][n], 0, 0, 0); __builtin_amdgcn_s_setprio(0); } while (0)
; #define PG8_WAIT_V(n) asm volatile("s_waitcnt vmcnt(" #n ")" ::: "memory")
; #define PG8_WAIT_L(n) asm volatile("s_waitcnt lgkmcnt(" #n ")" ::: "memory")
; #define PG8_BAR __builtin_amdgcn_s_barrier()
; #define PG8_SCHED __builtin_amdgcn_sched_barrier(0)
; template <class Epi, class Sched, bool ALIGN_EPI = false, bool SP2 = false>
; __device__ __forceinline__ void gemm_phase(PG8_LAS unsigned char* lds, const Gemm g, const Sched& S, const Epi& E) {
;     ...
;             PG8_WAIT_V(8); PG8_WAIT_L(0); PG8_BAR; PG8_MMA(1, 0, At, B0); PG8_MMA(1, 1, At, B1); PG8_BAR; PG8_SCHED;
;             PG8_LDB(B0, 1, 0); PG8_LDB(B1, 1, 1); PG8_SCHED; PG8_LDA(At, 1, 0); PG8_STAGE(PG8_SA(0, 1), a2 + hstepA, voffA);
;             PG8_WAIT_V(8); PG8_WAIT_L(0); PG8_BAR; PG8_MMA(0, 0, At, B0); PG8_MMA(0, 1, At, B1); PG8_BAR; PG8_SCHED;
	s_setprio 1
	s_waitcnt lgkmcnt(0)
	v_mfma_f32_16x16x32_bf16 v[60:63], v[140:143], v[186:189], v[60:63]
	v_mfma_f32_16x16x32_bf16 v[56:59], v[162:165], v[186:189], v[56:59]
	v_mfma_f32_16x16x32_bf16 v[44:47], v[140:143], v[194:197], v[44:47]
	v_mfma_f32_16x16x32_bf16 v[40:43], v[162:165], v[194:197], v[40:43]
	v_mfma_f32_16x16x32_bf16 v[28:31], v[140:143], v[202:205], v[28:31]
	v_mfma_f32_16x16x32_bf16 v[24:27], v[162:165], v[202:205], v[24:27]
	v_mfma_f32_16x16x32_bf16 v[12:15], v[140:143], v[210:213], v[12:15]
	v_mfma_f32_16x16x32_bf16 v[8:11], v[162:165], v[210:213], v[8:11]
	v_mfma_f32_16x16x32_bf16 v[60:63], v[158:161], v[190:193], v[60:63]
	v_mfma_f32_16x16x32_bf16 v[56:59], v[166:169], v[190:193], v[56:59]
	v_mfma_f32_16x16x32_bf16 v[44:47], v[158:161], v[198:201], v[44:47]
	v_mfma_f32_16x16x32_bf16 v[40:43], v[166:169], v[198:201], v[40:43]
	v_mfma_f32_16x16x32_bf16 v[28:31], v[158:161], v[206:209], v[28:31]
	v_mfma_f32_16x16x32_bf16 v[24:27], v[166:169], v[206:209], v[24:27]
	v_mfma_f32_16x16x32_bf16 v[12:15], v[158:161], v[214:217], v[12:15]
	v_mfma_f32_16x16x32_bf16 v[8:11], v[166:169], v[214:217], v[8:11]
	v_mfma_f32_16x16x32_bf16 v[52:55], v[170:173], v[186:189], v[52:55]
	v_mfma_f32_16x16x32_bf16 v[48:51], v[178:181], v[186:189], v[48:51]
	v_mfma_f32_16x16x32_bf16 v[36:39], v[170:173], v[194:197], v[36:39]
	v_mfma_f32_16x16x32_bf16 v[32:35], v[178:181], v[194:197], v[32:35]
	v_mfma_f32_16x16x32_bf16 v[20:23], v[170:173], v[202:205], v[20:23]
	v_mfma_f32_16x16x32_bf16 v[16:19], v[178:181], v[202:205], v[16:19]
	v_mfma_f32_16x16x32_bf16 v[4:7], v[170:173], v[210:213], v[4:7]
	v_mfma_f32_16x16x32_bf16 v[0:3], v[178:181], v[210:213], v[0:3]
	v_mfma_f32_16x16x32_bf16 v[52:55], v[174:177], v[190:193], v[52:55]
	v_mfma_f32_16x16x32_bf16 v[48:51], v[182:185], v[190:193], v[48:51]
	v_mfma_f32_16x16x32_bf16 v[36:39], v[174:177], v[198:201], v[36:39]
	v_mfma_f32_16x16x32_bf16 v[32:35], v[182:185], v[198:201], v[32:35]
	v_mfma_f32_16x16x32_bf16 v[20:23], v[174:177], v[206:209], v[20:23]
	v_mfma_f32_16x16x32_bf16 v[16:19], v[182:185], v[206:209], v[16:19]
	v_mfma_f32_16x16x32_bf16 v[4:7], v[174:177], v[214:217], v[4:7]
	v_mfma_f32_16x16x32_bf16 v[0:3], v[182:185], v[214:217], v[0:3]
	s_setprio 0
	s_barrier
	s_add_i32 s57, 0, 0x18000
	v_add_u32_e32 v153, s57, v147
	s_add_i32 s58, 0, 0x1c000
	ds_read_b128 v[140:143], v153
	ds_read_b128 v[158:161], v153 offset:1024
	ds_read_b128 v[162:165], v153 offset:2048
	ds_read_b128 v[166:169], v153 offset:3072
	v_add_u32_e32 v153, s58, v147
	ds_read_b128 v[170:173], v153
	ds_read_b128 v[174:177], v153 offset:1024
	ds_read_b128 v[178:181], v153 offset:2048
	ds_read_b128 v[182:185], v153 offset:3072
	s_add_u32 s34, s34, 0x80000
	s_addc_u32 s35, s35, 0
	s_mov_b32 m0, s42
	v_lshl_add_u64 v[222:223], s[34:35], 0, v[128:129]
	ds_read_b128 v[186:189], v151 offset:32768
	ds_read_b128 v[190:193], v151 offset:33792
	ds_read_b128 v[194:197], v151 offset:34816
	ds_read_b128 v[198:201], v151 offset:35840
	ds_read_b128 v[202:205], v151 offset:36864
	ds_read_b128 v[206:209], v151 offset:37888
	ds_read_b128 v[210:213], v151 offset:38912
	ds_read_b128 v[214:217], v151 offset:39936
	global_load_lds_dwordx4 v[222:223], off
	v_lshl_add_u64 v[222:223], s[34:35], 0, v[130:131]
	s_mov_b32 m0, s43
	s_nop 0
	global_load_lds_dwordx4 v[222:223], off
	s_waitcnt vmcnt(8)
	s_waitcnt lgkmcnt(0)
	s_barrier
	s_setprio 1
	s_waitcnt lgkmcnt(0)
	v_mfma_f32_16x16x32_bf16 v[124:127], v[140:143], v[186:189], v[124:127]
	v_mfma_f32_16x16x32_bf16 v[120:123], v[162:165], v[186:189], v[120:123]
	v_mfma_f32_16x16x32_bf16 v[108:111], v[140:143], v[194:197], v[108:111]
	v_mfma_f32_16x16x32_bf16 v[104:107], v[162:165], v[194:197], v[104:107]
	v_mfma_f32_16x16x32_bf16 v[92:95], v[140:143], v[202:205], v[92:95]
	v_mfma_f32_16x16x32_bf16 v[88:91], v[162:165], v[202:205], v[88:91]
	v_mfma_f32_16x16x32_bf16 v[76:79], v[140:143], v[210:213], v[76:79]
	v_mfma_f32_16x16x32_bf16 v[72:75], v[162:165], v[210:213], v[72:75]
	v_mfma_f32_16x16x32_bf16 v[124:127], v[158:161], v[190:193], v[124:127]
	v_mfma_f32_16x16x32_bf16 v[120:123], v[166:169], v[190:193], v[120:123]
	v_mfma_f32_16x16x32_bf16 v[108:111], v[158:161], v[198:201], v[108:111]
	v_mfma_f32_16x16x32_bf16 v[104:107], v[166:169], v[198:201], v[104:107]
	v_mfma_f32_16x16x32_bf16 v[92:95], v[158:161], v[206:209], v[92:95]
	v_mfma_f32_16x16x32_bf16 v[88:91], v[166:169], v[206:209], v[88:91]
	v_mfma_f32_16x16x32_bf16 v[76:79], v[158:161], v[214:217], v[76:79]
	v_mfma_f32_16x16x32_bf16 v[72:75], v[166:169], v[214:217], v[72:75]
	v_mfma_f32_16x16x32_bf16 v[116:119], v[170:173], v[186:189], v[116:119]
	v_mfma_f32_16x16x32_bf16 v[112:115], v[178:181], v[186:189], v[112:115]
	v_mfma_f32_16x16x32_bf16 v[100:103], v[170:173], v[194:197], v[100:103]
	v_mfma_f32_16x16x32_bf16 v[96:99], v[178:181], v[194:197], v[96:99]
	v_mfma_f32_16x16x32_bf16 v[84:87], v[170:173], v[202:205], v[84:87]
	v_mfma_f32_16x16x32_bf16 v[80:83], v[178:181], v[202:205], v[80:83]
	v_mfma_f32_16x16x32_bf16 v[68:71], v[170:173], v[210:213], v[68:71]
	v_mfma_f32_16x16x32_bf16 v[64:67], v[178:181], v[210:213], v[64:67]
	v_mfma_f32_16x16x32_bf16 v[116:119], v[174:177], v[190:193], v[116:119]
	v_mfma_f32_16x16x32_bf16 v[112:115], v[182:185], v[190:193], v[112:115]
	v_mfma_f32_16x16x32_bf16 v[100:103], v[174:177], v[198:201], v[100:103]
	v_mfma_f32_16x16x32_bf16 v[96:99], v[182:185], v[198:201], v[96:99]
	v_mfma_f32_16x16x32_bf16 v[84:87], v[174:177], v[206:209], v[84:87]
	v_mfma_f32_16x16x32_bf16 v[80:83], v[182:185], v[206:209], v[80:83]
	v_mfma_f32_16x16x32_bf16 v[68:71], v[174:177], v[214:217], v[68:71]
	v_mfma_f32_16x16x32_bf16 v[64:67], v[182:185], v[214:217], v[64:67]
	s_setprio 0
	s_barrier
; #define PG8_STAGE(bufoff, gbase, voff) do { _Pragma("unroll") for (int _i = 0; _i < 2; ++_i) \
;         __builtin_amdgcn_global_load_lds((const unsigned*)((const char*)(gbase) + (voff)[_i]), (PG8_LAS unsigned*)(lds + (bufoff) + ldsw + _i * 8192), 16, 0, 0); } while (0)
; #define PG8_LDA(dst, b, h) do { _Pragma("unroll") for (int m = 0; m < 4; ++m) _Pragma("unroll") for (int k = 0; k < 2; ++k) dst[m][k] = *(const PG8_LAS bf16x8*)(lds + PG8_SA(b, h) + aoff + m * 2048 + k * 1024); } while (0)
; #define PG8_MMA(ai, bj, At, Bt) do { __builtin_amdgcn_s_setprio(1); _Pragma("unroll") for (int m = 0; m < 4; ++m) _Pragma("unroll") for (int n = 0; n < 2; ++n) _Pragma("unroll") for (int k = 0; k < 2; ++k) \
;         acc[ai][bj][m][n] = __builtin_amdgcn_mfma_f32_16x16x32_bf16(Bt[n][k], At[m][k], acc[ai][bj][m][n], 0, 0, 0); __builtin_amdgcn_s_setprio(0); } while (0)
; #define PG8_WAIT_V(n) asm volatile("s_waitcnt vmcnt(" #n ")" ::: "memory")
; #define PG8_WAIT_L(n) asm volatile("s_waitcnt lgkmcnt(" #n ")" ::: "memory")
; #define PG8_BAR __builtin_amdgcn_s_barrier()
; #define PG8_SCHED __builtin_amdgcn_sched_barrier(0)
; template <class Epi, class Sched, bool ALIGN_EPI = false, bool SP2 = false>
; __device__ __forceinline__ void gemm_phase(PG8_LAS unsigned char* lds, const Gemm g, const Sched& S, const Epi& E) {
;     ...
;         for (int t = 0; t < nt; t += 2) {
;     ...
;             PG8_LDA(At, 1, 1); PG8_STAGE(PG8_SB(1, 0), b3, voffB); PG8_STAGE(PG8_SB(1, 1), b3 + hstepB, voffB); PG8_STAGE(PG8_SA(1, 0), a3, voffA);
;             PG8_WAIT_V(8); PG8_WAIT_L(0); PG8_BAR; PG8_MMA(1, 0, At, B0); PG8_MMA(1, 1, At, B1); PG8_BAR; PG8_SCHED;
	s_add_i32 s34, s57, s40
	v_lshl_add_u64 v[144:145], v[144:145], 0, s[14:15]
	s_mov_b32 m0, s34
	ds_read_b128 v[186:189], v151 offset:49152
	ds_read_b128 v[190:193], v151 offset:50176
	ds_read_b128 v[194:197], v151 offset:51200
	ds_read_b128 v[198:201], v151 offset:52224
	ds_read_b128 v[202:205], v151 offset:53248
	ds_read_b128 v[206:209], v151 offset:54272
	ds_read_b128 v[210:213], v151 offset:55296
	ds_read_b128 v[214:217], v151 offset:56320
	global_load_lds_dwordx4 v[144:145], off
	s_add_i32 m0, s34, 0x2000
	s_add_u32 s30, s30, 0x80080
	v_lshl_add_u64 v[144:145], v[154:155], 0, s[14:15]
	s_addc_u32 s31, s31, 0
	s_add_i32 s34, s58, s40
	global_load_lds_dwordx4 v[144:145], off
	v_lshl_add_u64 v[144:145], s[30:31], 0, v[128:129]
	s_mov_b32 m0, s34
	s_nop 0
	global_load_lds_dwordx4 v[144:145], off
	v_lshl_add_u64 v[144:145], s[30:31], 0, v[130:131]
	s_add_i32 m0, s34, 0x2000
	s_nop 0
	global_load_lds_dwordx4 v[144:145], off
	v_lshl_add_u64 v[144:145], v[218:219], 0, s[14:15]
	s_mov_b32 m0, s45
	s_nop 0
	global_load_lds_dwordx4 v[144:145], off
	v_lshl_add_u64 v[144:145], v[220:221], 0, s[14:15]
	s_mov_b32 m0, s46
	s_nop 0
	global_load_lds_dwordx4 v[144:145], off
	s_waitcnt vmcnt(8)
	s_waitcnt lgkmcnt(0)
	s_barrier
	s_setprio 1
	s_waitcnt lgkmcnt(0)
	v_mfma_f32_16x16x32_bf16 v[60:63], v[140:143], v[186:189], v[60:63]
	v_mfma_f32_16x16x32_bf16 v[56:59], v[162:165], v[186:189], v[56:59]
	v_mfma_f32_16x16x32_bf16 v[44:47], v[140:143], v[194:197], v[44:47]
	v_mfma_f32_16x16x32_bf16 v[40:43], v[162:165], v[194:197], v[40:43]
	v_mfma_f32_16x16x32_bf16 v[28:31], v[140:143], v[202:205], v[28:31]
	v_mfma_f32_16x16x32_bf16 v[24:27], v[162:165], v[202:205], v[24:27]
	v_mfma_f32_16x16x32_bf16 v[12:15], v[140:143], v[210:213], v[12:15]
	v_mfma_f32_16x16x32_bf16 v[8:11], v[162:165], v[210:213], v[8:11]
	v_mfma_f32_16x16x32_bf16 v[60:63], v[158:161], v[190:193], v[60:63]
	v_mfma_f32_16x16x32_bf16 v[56:59], v[166:169], v[190:193], v[56:59]
	v_mfma_f32_16x16x32_bf16 v[44:47], v[158:161], v[198:201], v[44:47]
	v_mfma_f32_16x16x32_bf16 v[40:43], v[166:169], v[198:201], v[40:43]
	v_mfma_f32_16x16x32_bf16 v[28:31], v[158:161], v[206:209], v[28:31]
	v_mfma_f32_16x16x32_bf16 v[24:27], v[166:169], v[206:209], v[24:27]
	v_mfma_f32_16x16x32_bf16 v[12:15], v[158:161], v[214:217], v[12:15]
	v_mfma_f32_16x16x32_bf16 v[8:11], v[166:169], v[214:217], v[8:11]
	v_mfma_f32_16x16x32_bf16 v[52:55], v[170:173], v[186:189], v[52:55]
	v_mfma_f32_16x16x32_bf16 v[48:51], v[178:181], v[186:189], v[48:51]
	v_mfma_f32_16x16x32_bf16 v[36:39], v[170:173], v[194:197], v[36:39]
	v_mfma_f32_16x16x32_bf16 v[32:35], v[178:181], v[194:197], v[32:35]
	v_mfma_f32_16x16x32_bf16 v[20:23], v[170:173], v[202:205], v[20:23]
	v_mfma_f32_16x16x32_bf16 v[16:19], v[178:181], v[202:205], v[16:19]
	v_mfma_f32_16x16x32_bf16 v[4:7], v[170:173], v[210:213], v[4:7]
	v_mfma_f32_16x16x32_bf16 v[0:3], v[178:181], v[210:213], v[0:3]
	v_mfma_f32_16x16x32_bf16 v[52:55], v[174:177], v[190:193], v[52:55]
	v_mfma_f32_16x16x32_bf16 v[48:51], v[182:185], v[190:193], v[48:51]
	v_mfma_f32_16x16x32_bf16 v[36:39], v[174:177], v[198:201], v[36:39]
	v_mfma_f32_16x16x32_bf16 v[32:35], v[182:185], v[198:201], v[32:35]
	v_mfma_f32_16x16x32_bf16 v[20:23], v[174:177], v[206:209], v[20:23]
	v_mfma_f32_16x16x32_bf16 v[16:19], v[182:185], v[206:209], v[16:19]
	v_mfma_f32_16x16x32_bf16 v[4:7], v[174:177], v[214:217], v[4:7]
	v_mfma_f32_16x16x32_bf16 v[0:3], v[182:185], v[214:217], v[0:3]
	s_setprio 0
	s_barrier
	s_add_i32 s56, s56, 2
	s_add_u32 s28, s28, 0x100
	s_addc_u32 s29, s29, 0
	s_add_u32 s54, s54, 0x100
	s_addc_u32 s55, s55, 0
	s_cmp_gt_u32 s56, 29
	s_cbranch_scc0 .LBB0_733
	s_and_b64 vcc, exec, s[16:17]
	s_cbranch_vccz .LBB0_736
	s_barrier

; #define PG8_STAGE(bufoff, gbase, voff) do { _Pragma("unroll") for (int _i = 0; _i < 2; ++_i) \
;         __builtin_amdgcn_global_load_lds((const unsigned*)((const char*)(gbase) + (voff)[_i]), (PG8_LAS unsigned*)(lds + (bufoff) + ldsw + _i * 8192), 16, 0, 0); } while (0)
; #define PG8_LDA(dst, b, h) do { _Pragma("unroll") for (int m = 0; m < 4; ++m) _Pragma("unroll") for (int k = 0; k < 2; ++k) dst[m][k] = *(const PG8_LAS bf16x8*)(lds + PG8_SA(b, h) + aoff + m * 2048 + k * 1024); } while (0)
; #define PG8_LDB(dst, b, h) do { _Pragma("unroll") for (int n = 0; n < 2; ++n) _Pragma("unroll") for (int k = 0; k < 2; ++k) dst[n][k] = *(const PG8_LAS bf16x8*)(lds + PG8_SB(b, h) + boff + n * 2048 + k * 1024); } while (0)
; #define PG8_MMA(ai, bj, At, Bt) do { __builtin_amdgcn_s_setprio(1); _Pragma("unroll") for (int m = 0; m < 4; ++m) _Pragma("unroll") for (int n = 0; n < 2; ++n) _Pragma("unroll") for (int k = 0; k < 2; ++k) \
;         acc[ai][bj][m][n] = __builtin_amdgcn_mfma_f32_16x16x32_bf16(Bt[n][k], At[m][k], acc[ai][bj][m][n], 0, 0, 0); __builtin_amdgcn_s_setprio(0); } while (0)
; #define PG8_WAIT_V(n) asm volatile("s_waitcnt vmcnt(" #n ")" ::: "memory")
; #define PG8_WAIT_L(n) asm volatile("s_waitcnt lgkmcnt(" #n ")" ::: "memory")
; #define PG8_BAR __builtin_amdgcn_s_barrier()
; #define PG8_SCHED __builtin_amdgcn_sched_barrier(0)
; template <class Epi, class Sched, bool ALIGN_EPI = false, bool SP2 = false>
; __device__ __forceinline__ void gemm_phase(PG8_LAS unsigned char* lds, const Gemm g, const Sched& S, const Epi& E) {
;     ...
;             PG8_LDB(B0, 0, 0); PG8_LDB(B1, 0, 1); PG8_SCHED; PG8_LDA(At, 0, 0); PG8_STAGE(PG8_SA(1, 1), a1 + hstepA, voffA);
;             PG8_WAIT_V(8); PG8_WAIT_L(0); PG8_BAR; PG8_MMA(0, 0, At, B0); PG8_MMA(0, 1, At, B1); PG8_BAR; PG8_SCHED;
;             PG8_LDA(At, 0, 1); PG8_STAGE(PG8_SB(0, 0), b2, voffB); PG8_STAGE(PG8_SB(0, 1), b2 + hstepB, voffB); PG8_STAGE(PG8_SA(0, 0), a2, voffA);
;             PG8_WAIT_V(8); PG8_WAIT_L(0); PG8_BAR; PG8_MMA(1, 0, At, B0); PG8_MMA(1, 1, At, B1); PG8_BAR; PG8_SCHED;
.LBB0_824:
	ds_read_b128 v[144:147], v155
	ds_read_b128 v[148:151], v155 offset:1024
	ds_read_b128 v[162:165], v155 offset:2048
	ds_read_b128 v[166:169], v155 offset:3072
	ds_read_b128 v[170:173], v158
	ds_read_b128 v[174:177], v158 offset:1024
	ds_read_b128 v[178:181], v158 offset:2048
	ds_read_b128 v[182:185], v158 offset:3072
	s_add_u32 s36, s4, 0xfff80080
	s_addc_u32 s37, s5, -1
	s_cmp_eq_u32 s65, 28
	s_cselect_b32 s39, s29, s37
	s_cselect_b32 s38, s61, s36
	s_cselect_b32 s37, s27, s64
	s_cselect_b32 s36, s62, s63
	v_lshl_add_u64 v[218:219], s[4:5], 0, v[136:137]
	s_add_i32 m0, s3, 0xc000
	ds_read_b128 v[186:189], v159
	ds_read_b128 v[190:193], v159 offset:1024
	ds_read_b128 v[194:197], v159 offset:2048
	ds_read_b128 v[198:201], v159 offset:3072
	ds_read_b128 v[202:205], v159 offset:4096
	ds_read_b128 v[206:209], v159 offset:5120
	ds_read_b128 v[210:213], v159 offset:6144
	ds_read_b128 v[214:217], v159 offset:7168
	global_load_lds_dwordx4 v[218:219], off
	v_lshl_add_u64 v[218:219], s[4:5], 0, v[138:139]
	s_add_i32 m0, s3, 0xe000
	s_nop 0
	global_load_lds_dwordx4 v[218:219], off
	s_waitcnt vmcnt(8)
	s_waitcnt lgkmcnt(0)
	s_barrier
	s_setprio 1
	s_waitcnt lgkmcnt(0)
	v_mfma_f32_16x16x32_bf16 v[124:127], v[144:147], v[186:189], v[124:127]
	v_mfma_f32_16x16x32_bf16 v[120:123], v[162:165], v[186:189], v[120:123]
	v_mfma_f32_16x16x32_bf16 v[108:111], v[144:147], v[194:197], v[108:111]
	v_mfma_f32_16x16x32_bf16 v[104:107], v[162:165], v[194:197], v[104:107]
	v_mfma_f32_16x16x32_bf16 v[92:95], v[144:147], v[202:205], v[92:95]
	v_mfma_f32_16x16x32_bf16 v[88:91], v[162:165], v[202:205], v[88:91]
	v_mfma_f32_16x16x32_bf16 v[76:79], v[144:147], v[210:213], v[76:79]
	v_mfma_f32_16x16x32_bf16 v[72:75], v[162:165], v[210:213], v[72:75]
	v_mfma_f32_16x16x32_bf16 v[124:127], v[148:151], v[190:193], v[124:127]
	v_mfma_f32_16x16x32_bf16 v[120:123], v[166:169], v[190:193], v[120:123]
	v_mfma_f32_16x16x32_bf16 v[108:111], v[148:151], v[198:201], v[108:111]
	v_mfma_f32_16x16x32_bf16 v[104:107], v[166:169], v[198:201], v[104:107]
	v_mfma_f32_16x16x32_bf16 v[92:95], v[148:151], v[206:209], v[92:95]
	v_mfma_f32_16x16x32_bf16 v[88:91], v[166:169], v[206:209], v[88:91]
	v_mfma_f32_16x16x32_bf16 v[76:79], v[148:151], v[214:217], v[76:79]
	v_mfma_f32_16x16x32_bf16 v[72:75], v[166:169], v[214:217], v[72:75]
	v_mfma_f32_16x16x32_bf16 v[116:119], v[170:173], v[186:189], v[116:119]
	v_mfma_f32_16x16x32_bf16 v[112:115], v[178:181], v[186:189], v[112:115]
	v_mfma_f32_16x16x32_bf16 v[100:103], v[170:173], v[194:197], v[100:103]
	v_mfma_f32_16x16x32_bf16 v[96:99], v[178:181], v[194:197], v[96:99]
	v_mfma_f32_16x16x32_bf16 v[84:87], v[170:173], v[202:205], v[84:87]
	v_mfma_f32_16x16x32_bf16 v[80:83], v[178:181], v[202:205], v[80:83]
	v_mfma_f32_16x16x32_bf16 v[68:71], v[170:173], v[210:213], v[68:71]
	v_mfma_f32_16x16x32_bf16 v[64:67], v[178:181], v[210:213], v[64:67]
	v_mfma_f32_16x16x32_bf16 v[116:119], v[174:177], v[190:193], v[116:119]
	v_mfma_f32_16x16x32_bf16 v[112:115], v[182:185], v[190:193], v[112:115]
	v_mfma_f32_16x16x32_bf16 v[100:103], v[174:177], v[198:201], v[100:103]
	v_mfma_f32_16x16x32_bf16 v[96:99], v[182:185], v[198:201], v[96:99]
	v_mfma_f32_16x16x32_bf16 v[84:87], v[174:177], v[206:209], v[84:87]
	v_mfma_f32_16x16x32_bf16 v[80:83], v[182:185], v[206:209], v[80:83]
	v_mfma_f32_16x16x32_bf16 v[68:71], v[174:177], v[214:217], v[68:71]
	v_mfma_f32_16x16x32_bf16 v[64:67], v[182:185], v[214:217], v[64:67]
	s_setprio 0
	s_barrier
	s_add_i32 s66, s53, s45
	v_lshl_add_u64 v[218:219], s[36:37], 0, v[130:131]
	s_mov_b32 m0, s66
	ds_read_b128 v[186:189], v159 offset:16384
	ds_read_b128 v[190:193], v159 offset:17408
	ds_read_b128 v[194:197], v159 offset:18432
	ds_read_b128 v[198:201], v159 offset:19456
	ds_read_b128 v[202:205], v159 offset:20480
	ds_read_b128 v[206:209], v159 offset:21504
	ds_read_b128 v[210:213], v159 offset:22528
	ds_read_b128 v[214:217], v159 offset:23552
	global_load_lds_dwordx4 v[218:219], off
	s_add_i32 m0, s66, 0x2000
	s_add_u32 s66, s36, 0x80000
	v_lshl_add_u64 v[220:221], s[36:37], 0, v[134:135]
	s_addc_u32 s67, s37, 0
	s_add_i32 s68, s54, s45
	global_load_lds_dwordx4 v[220:221], off
	v_lshl_add_u64 v[222:223], s[66:67], 0, v[130:131]
	s_mov_b32 m0, s68
	v_lshl_add_u64 v[224:225], s[38:39], 0, v[132:133]
	global_load_lds_dwordx4 v[222:223], off
	v_lshl_add_u64 v[222:223], s[66:67], 0, v[134:135]
	s_add_i32 m0, s68, 0x2000
	s_nop 0
	global_load_lds_dwordx4 v[222:223], off
	v_lshl_add_u64 v[222:223], s[38:39], 0, v[128:129]
	s_mov_b32 m0, s3
	s_nop 0
	global_load_lds_dwordx4 v[222:223], off
	s_mov_b32 m0, s46
	s_nop 0
	global_load_lds_dwordx4 v[224:225], off
	s_waitcnt vmcnt(8)
	s_waitcnt lgkmcnt(0)
	s_barrier
; #define PG8_STAGE(bufoff, gbase, voff) do { _Pragma("unroll") for (int _i = 0; _i < 2; ++_i) \
;         __builtin_amdgcn_global_load_lds((const unsigned*)((const char*)(gbase) + (voff)[_i]), (PG8_LAS unsigned*)(lds + (bufoff) + ldsw + _i * 8192), 16, 0, 0); } while (0)
; #define PG8_LDA(dst, b, h) do { _Pragma("unroll") for (int m = 0; m < 4; ++m) _Pragma("unroll") for (int k = 0; k < 2; ++k) dst[m][k] = *(const PG8_LAS bf16x8*)(lds + PG8_SA(b, h) + aoff + m * 2048 + k * 1024); } while (0)
; #define PG8_LDB(dst, b, h) do { _Pragma("unroll") for (int n = 0; n < 2; ++n) _Pragma("unroll") for (int k = 0; k < 2; ++k) dst[n][k] = *(const PG8_LAS bf16x8*)(lds + PG8_SB(b, h) + boff + n * 2048 + k * 1024); } while (0)
; #define PG8_MMA(ai, bj, At, Bt) do { __builtin_amdgcn_s_setprio(1); _Pragma("unroll") for (int m = 0; m < 4; ++m) _Pragma("unroll") for (int n = 0; n < 2; ++n) _Pragma("unroll") for (int k = 0; k < 2; ++k) \
;         acc[ai][bj][m][n] = __builtin_amdgcn_mfma_f32_16x16x32_bf16(Bt[n][k], At[m][k], acc[ai][bj][m][n], 0, 0, 0); __builtin_amdgcn_s_setprio(0); } while (0)
; #define PG8_WAIT_V(n) asm volatile("s_waitcnt vmcnt(" #n ")" ::: "memory")
; #define PG8_WAIT_L(n) asm volatile("s_waitcnt lgkmcnt(" #n ")" ::: "memory")
; #define PG8_BAR __builtin_amdgcn_s_barrier()
; #define PG8_SCHED __builtin_amdgcn_sched_barrier(0)
; template <class Epi, class Sched, bool ALIGN_EPI = false, bool SP2 = false>
; __device__ __forceinline__ void gemm_phase(PG8_LAS unsigned char* lds, const Gemm g, const Sched& S, const Epi& E) {
;     ...
;             PG8_WAIT_V(8); PG8_WAIT_L(0); PG8_BAR; PG8_MMA(1, 0, At, B0); PG8_MMA(1, 1, At, B1); PG8_BAR; PG8_SCHED;
;             PG8_LDB(B0, 1, 0); PG8_LDB(B1, 1, 1); PG8_SCHED; PG8_LDA(At, 1, 0); PG8_STAGE(PG8_SA(0, 1), a2 + hstepA, voffA);
;             PG8_WAIT_V(8); PG8_WAIT_L(0); PG8_BAR; PG8_MMA(0, 0, At, B0); PG8_MMA(0, 1, At, B1); PG8_BAR; PG8_SCHED;
	s_setprio 1
	s_waitcnt lgkmcnt(0)
	v_mfma_f32_16x16x32_bf16 v[60:63], v[144:147], v[186:189], v[60:63]
	v_mfma_f32_16x16x32_bf16 v[56:59], v[162:165], v[186:189], v[56:59]
	v_mfma_f32_16x16x32_bf16 v[44:47], v[144:147], v[194:197], v[44:47]
	v_mfma_f32_16x16x32_bf16 v[40:43], v[162:165], v[194:197], v[40:43]
	v_mfma_f32_16x16x32_bf16 v[28:31], v[144:147], v[202:205], v[28:31]
	v_mfma_f32_16x16x32_bf16 v[24:27], v[162:165], v[202:205], v[24:27]
	v_mfma_f32_16x16x32_bf16 v[12:15], v[144:147], v[210:213], v[12:15]
	v_mfma_f32_16x16x32_bf16 v[8:11], v[162:165], v[210:213], v[8:11]
	v_mfma_f32_16x16x32_bf16 v[60:63], v[148:151], v[190:193], v[60:63]
	v_mfma_f32_16x16x32_bf16 v[56:59], v[166:169], v[190:193], v[56:59]
	v_mfma_f32_16x16x32_bf16 v[44:47], v[148:151], v[198:201], v[44:47]
	v_mfma_f32_16x16x32_bf16 v[40:43], v[166:169], v[198:201], v[40:43]
	v_mfma_f32_16x16x32_bf16 v[28:31], v[148:151], v[206:209], v[28:31]
	v_mfma_f32_16x16x32_bf16 v[24:27], v[166:169], v[206:209], v[24:27]
	v_mfma_f32_16x16x32_bf16 v[12:15], v[148:151], v[214:217], v[12:15]
	v_mfma_f32_16x16x32_bf16 v[8:11], v[166:169], v[214:217], v[8:11]
	v_mfma_f32_16x16x32_bf16 v[52:55], v[170:173], v[186:189], v[52:55]
	v_mfma_f32_16x16x32_bf16 v[48:51], v[178:181], v[186:189], v[48:51]
	v_mfma_f32_16x16x32_bf16 v[36:39], v[170:173], v[194:197], v[36:39]
	v_mfma_f32_16x16x32_bf16 v[32:35], v[178:181], v[194:197], v[32:35]
	v_mfma_f32_16x16x32_bf16 v[20:23], v[170:173], v[202:205], v[20:23]
	v_mfma_f32_16x16x32_bf16 v[16:19], v[178:181], v[202:205], v[16:19]
	v_mfma_f32_16x16x32_bf16 v[4:7], v[170:173], v[210:213], v[4:7]
	v_mfma_f32_16x16x32_bf16 v[0:3], v[178:181], v[210:213], v[0:3]
	v_mfma_f32_16x16x32_bf16 v[52:55], v[174:177], v[190:193], v[52:55]
	v_mfma_f32_16x16x32_bf16 v[48:51], v[182:185], v[190:193], v[48:51]
	v_mfma_f32_16x16x32_bf16 v[36:39], v[174:177], v[198:201], v[36:39]
	v_mfma_f32_16x16x32_bf16 v[32:35], v[182:185], v[198:201], v[32:35]
	v_mfma_f32_16x16x32_bf16 v[20:23], v[174:177], v[206:209], v[20:23]
	v_mfma_f32_16x16x32_bf16 v[16:19], v[182:185], v[206:209], v[16:19]
	v_mfma_f32_16x16x32_bf16 v[4:7], v[174:177], v[214:217], v[4:7]
	v_mfma_f32_16x16x32_bf16 v[0:3], v[182:185], v[214:217], v[0:3]
	s_setprio 0
	s_barrier
	s_add_i32 s66, 0, 0x18000
	s_add_i32 s67, 0, 0x1c000
	v_add_u32_e32 v166, s66, v153
	v_add_u32_e32 v182, s67, v153
	ds_read_b128 v[144:147], v166
	ds_read_b128 v[148:151], v166 offset:1024
	ds_read_b128 v[162:165], v166 offset:2048
	ds_read_b128 v[166:169], v166 offset:3072
	ds_read_b128 v[170:173], v182
	ds_read_b128 v[174:177], v182 offset:1024
	ds_read_b128 v[178:181], v182 offset:2048
	ds_read_b128 v[182:185], v182 offset:3072
	s_add_u32 s38, s38, 0x80000
	s_addc_u32 s39, s39, 0
	s_mov_b32 m0, s47
	v_lshl_add_u64 v[226:227], s[38:39], 0, v[128:129]
	ds_read_b128 v[186:189], v159 offset:32768
	ds_read_b128 v[190:193], v159 offset:33792
	ds_read_b128 v[194:197], v159 offset:34816
	ds_read_b128 v[198:201], v159 offset:35840
	ds_read_b128 v[202:205], v159 offset:36864
	ds_read_b128 v[206:209], v159 offset:37888
	ds_read_b128 v[210:213], v159 offset:38912
	ds_read_b128 v[214:217], v159 offset:39936
	global_load_lds_dwordx4 v[226:227], off
	v_lshl_add_u64 v[226:227], s[38:39], 0, v[132:133]
	s_mov_b32 m0, s48
	s_nop 0
	global_load_lds_dwordx4 v[226:227], off
	s_waitcnt vmcnt(8)
	s_waitcnt lgkmcnt(0)
	s_barrier
	s_setprio 1
	s_waitcnt lgkmcnt(0)
	v_mfma_f32_16x16x32_bf16 v[124:127], v[144:147], v[186:189], v[124:127]
	v_mfma_f32_16x16x32_bf16 v[120:123], v[162:165], v[186:189], v[120:123]
	v_mfma_f32_16x16x32_bf16 v[108:111], v[144:147], v[194:197], v[108:111]
	v_mfma_f32_16x16x32_bf16 v[104:107], v[162:165], v[194:197], v[104:107]
	v_mfma_f32_16x16x32_bf16 v[92:95], v[144:147], v[202:205], v[92:95]
	v_mfma_f32_16x16x32_bf16 v[88:91], v[162:165], v[202:205], v[88:91]
	v_mfma_f32_16x16x32_bf16 v[76:79], v[144:147], v[210:213], v[76:79]
	v_mfma_f32_16x16x32_bf16 v[72:75], v[162:165], v[210:213], v[72:75]
	v_mfma_f32_16x16x32_bf16 v[124:127], v[148:151], v[190:193], v[124:127]
	v_mfma_f32_16x16x32_bf16 v[120:123], v[166:169], v[190:193], v[120:123]
	v_mfma_f32_16x16x32_bf16 v[108:111], v[148:151], v[198:201], v[108:111]
	v_mfma_f32_16x16x32_bf16 v[104:107], v[166:169], v[198:201], v[104:107]
	v_mfma_f32_16x16x32_bf16 v[92:95], v[148:151], v[206:209], v[92:95]
	v_mfma_f32_16x16x32_bf16 v[88:91], v[166:169], v[206:209], v[88:91]
	v_mfma_f32_16x16x32_bf16 v[76:79], v[148:151], v[214:217], v[76:79]
	v_mfma_f32_16x16x32_bf16 v[72:75], v[166:169], v[214:217], v[72:75]
	v_mfma_f32_16x16x32_bf16 v[116:119], v[170:173], v[186:189], v[116:119]
	v_mfma_f32_16x16x32_bf16 v[112:115], v[178:181], v[186:189], v[112:115]
	v_mfma_f32_16x16x32_bf16 v[100:103], v[170:173], v[194:197], v[100:103]
	v_mfma_f32_16x16x32_bf16 v[96:99], v[178:181], v[194:197], v[96:99]
	v_mfma_f32_16x16x32_bf16 v[84:87], v[170:173], v[202:205], v[84:87]
	v_mfma_f32_16x16x32_bf16 v[80:83], v[178:181], v[202:205], v[80:83]
	v_mfma_f32_16x16x32_bf16 v[68:71], v[170:173], v[210:213], v[68:71]
	v_mfma_f32_16x16x32_bf16 v[64:67], v[178:181], v[210:213], v[64:67]
	v_mfma_f32_16x16x32_bf16 v[116:119], v[174:177], v[190:193], v[116:119]
	v_mfma_f32_16x16x32_bf16 v[112:115], v[182:185], v[190:193], v[112:115]
	v_mfma_f32_16x16x32_bf16 v[100:103], v[174:177], v[198:201], v[100:103]
	v_mfma_f32_16x16x32_bf16 v[96:99], v[182:185], v[198:201], v[96:99]
	v_mfma_f32_16x16x32_bf16 v[84:87], v[174:177], v[206:209], v[84:87]
	v_mfma_f32_16x16x32_bf16 v[80:83], v[182:185], v[206:209], v[80:83]
	v_mfma_f32_16x16x32_bf16 v[68:71], v[174:177], v[214:217], v[68:71]
	v_mfma_f32_16x16x32_bf16 v[64:67], v[182:185], v[214:217], v[64:67]
	s_setprio 0
	s_barrier
; #define PG8_STAGE(bufoff, gbase, voff) do { _Pragma("unroll") for (int _i = 0; _i < 2; ++_i) \
;         __builtin_amdgcn_global_load_lds((const unsigned*)((const char*)(gbase) + (voff)[_i]), (PG8_LAS unsigned*)(lds + (bufoff) + ldsw + _i * 8192), 16, 0, 0); } while (0)
; #define PG8_LDA(dst, b, h) do { _Pragma("unroll") for (int m = 0; m < 4; ++m) _Pragma("unroll") for (int k = 0; k < 2; ++k) dst[m][k] = *(const PG8_LAS bf16x8*)(lds + PG8_SA(b, h) + aoff + m * 2048 + k * 1024); } while (0)
; #define PG8_MMA(ai, bj, At, Bt) do { __builtin_amdgcn_s_setprio(1); _Pragma("unroll") for (int m = 0; m < 4; ++m) _Pragma("unroll") for (int n = 0; n < 2; ++n) _Pragma("unroll") for (int k = 0; k < 2; ++k) \
;         acc[ai][bj][m][n] = __builtin_amdgcn_mfma_f32_16x16x32_bf16(Bt[n][k], At[m][k], acc[ai][bj][m][n], 0, 0, 0); __builtin_amdgcn_s_setprio(0); } while (0)
; #define PG8_WAIT_V(n) asm volatile("s_waitcnt vmcnt(" #n ")" ::: "memory")
; #define PG8_WAIT_L(n) asm volatile("s_waitcnt lgkmcnt(" #n ")" ::: "memory")
; #define PG8_BAR __builtin_amdgcn_s_barrier()
; #define PG8_SCHED __builtin_amdgcn_sched_barrier(0)
; template <class Epi, class Sched, bool ALIGN_EPI = false, bool SP2 = false>
; __device__ __forceinline__ void gemm_phase(PG8_LAS unsigned char* lds, const Gemm g, const Sched& S, const Epi& E) {
;     ...
;         for (int t = 0; t < nt; t += 2) {
;     ...
;             PG8_LDA(At, 1, 1); PG8_STAGE(PG8_SB(1, 0), b3, voffB); PG8_STAGE(PG8_SB(1, 1), b3 + hstepB, voffB); PG8_STAGE(PG8_SA(1, 0), a3, voffA);
;             PG8_WAIT_V(8); PG8_WAIT_L(0); PG8_BAR; PG8_MMA(1, 0, At, B0); PG8_MMA(1, 1, At, B1); PG8_BAR; PG8_SCHED;
	s_add_i32 s38, s66, s45
	v_lshl_add_u64 v[218:219], v[218:219], 0, s[14:15]
	s_mov_b32 m0, s38
	ds_read_b128 v[186:189], v159 offset:49152
	ds_read_b128 v[190:193], v159 offset:50176
	ds_read_b128 v[194:197], v159 offset:51200
	ds_read_b128 v[198:201], v159 offset:52224
	ds_read_b128 v[202:205], v159 offset:53248
	ds_read_b128 v[206:209], v159 offset:54272
	ds_read_b128 v[210:213], v159 offset:55296
	ds_read_b128 v[214:217], v159 offset:56320
	global_load_lds_dwordx4 v[218:219], off
	s_add_i32 m0, s38, 0x2000
	s_add_u32 s36, s36, 0x80080
	v_lshl_add_u64 v[218:219], v[220:221], 0, s[14:15]
	s_addc_u32 s37, s37, 0
	s_add_i32 s38, s67, s45
	global_load_lds_dwordx4 v[218:219], off
	v_lshl_add_u64 v[218:219], s[36:37], 0, v[130:131]
	s_mov_b32 m0, s38
	s_nop 0
	global_load_lds_dwordx4 v[218:219], off
	v_lshl_add_u64 v[218:219], s[36:37], 0, v[134:135]
	s_add_i32 m0, s38, 0x2000
	s_nop 0
	global_load_lds_dwordx4 v[218:219], off
	v_lshl_add_u64 v[218:219], v[222:223], 0, s[14:15]
	s_mov_b32 m0, s50
	s_nop 0
	global_load_lds_dwordx4 v[218:219], off
	v_lshl_add_u64 v[218:219], v[224:225], 0, s[14:15]
	s_mov_b32 m0, s51
	s_nop 0
	global_load_lds_dwordx4 v[218:219], off
	s_waitcnt vmcnt(8)
	s_waitcnt lgkmcnt(0)
	s_barrier
	s_setprio 1
	s_waitcnt lgkmcnt(0)
	v_mfma_f32_16x16x32_bf16 v[60:63], v[144:147], v[186:189], v[60:63]
	v_mfma_f32_16x16x32_bf16 v[56:59], v[162:165], v[186:189], v[56:59]
	v_mfma_f32_16x16x32_bf16 v[44:47], v[144:147], v[194:197], v[44:47]
	v_mfma_f32_16x16x32_bf16 v[40:43], v[162:165], v[194:197], v[40:43]
	v_mfma_f32_16x16x32_bf16 v[28:31], v[144:147], v[202:205], v[28:31]
	v_mfma_f32_16x16x32_bf16 v[24:27], v[162:165], v[202:205], v[24:27]
	v_mfma_f32_16x16x32_bf16 v[12:15], v[144:147], v[210:213], v[12:15]
	v_mfma_f32_16x16x32_bf16 v[8:11], v[162:165], v[210:213], v[8:11]
	v_mfma_f32_16x16x32_bf16 v[60:63], v[148:151], v[190:193], v[60:63]
	v_mfma_f32_16x16x32_bf16 v[56:59], v[166:169], v[190:193], v[56:59]
	v_mfma_f32_16x16x32_bf16 v[44:47], v[148:151], v[198:201], v[44:47]
	v_mfma_f32_16x16x32_bf16 v[40:43], v[166:169], v[198:201], v[40:43]
	v_mfma_f32_16x16x32_bf16 v[28:31], v[148:151], v[206:209], v[28:31]
	v_mfma_f32_16x16x32_bf16 v[24:27], v[166:169], v[206:209], v[24:27]
	v_mfma_f32_16x16x32_bf16 v[12:15], v[148:151], v[214:217], v[12:15]
	v_mfma_f32_16x16x32_bf16 v[8:11], v[166:169], v[214:217], v[8:11]
	v_mfma_f32_16x16x32_bf16 v[52:55], v[170:173], v[186:189], v[52:55]
	v_mfma_f32_16x16x32_bf16 v[48:51], v[178:181], v[186:189], v[48:51]
	v_mfma_f32_16x16x32_bf16 v[36:39], v[170:173], v[194:197], v[36:39]
	v_mfma_f32_16x16x32_bf16 v[32:35], v[178:181], v[194:197], v[32:35]
	v_mfma_f32_16x16x32_bf16 v[20:23], v[170:173], v[202:205], v[20:23]
	v_mfma_f32_16x16x32_bf16 v[16:19], v[178:181], v[202:205], v[16:19]
	v_mfma_f32_16x16x32_bf16 v[4:7], v[170:173], v[210:213], v[4:7]
	v_mfma_f32_16x16x32_bf16 v[0:3], v[178:181], v[210:213], v[0:3]
	v_mfma_f32_16x16x32_bf16 v[52:55], v[174:177], v[190:193], v[52:55]
	v_mfma_f32_16x16x32_bf16 v[48:51], v[182:185], v[190:193], v[48:51]
	v_mfma_f32_16x16x32_bf16 v[36:39], v[174:177], v[198:201], v[36:39]
	v_mfma_f32_16x16x32_bf16 v[32:35], v[182:185], v[198:201], v[32:35]
	v_mfma_f32_16x16x32_bf16 v[20:23], v[174:177], v[206:209], v[20:23]
	v_mfma_f32_16x16x32_bf16 v[16:19], v[182:185], v[206:209], v[16:19]
	v_mfma_f32_16x16x32_bf16 v[4:7], v[174:177], v[214:217], v[4:7]
	v_mfma_f32_16x16x32_bf16 v[0:3], v[182:185], v[214:217], v[0:3]
	s_setprio 0
	s_barrier
	s_add_i32 s65, s65, 2
	s_add_u32 s4, s4, 0x100
	s_addc_u32 s5, s5, 0
	s_add_u32 s63, s63, 0x100
	s_addc_u32 s64, s64, 0
	s_cmp_gt_u32 s65, 29
	s_cbranch_scc0 .LBB0_824
	s_and_b64 vcc, exec, s[16:17]
	s_cbranch_vccz .LBB0_827
	s_barrier

; #define PG8_STAGE(bufoff, gbase, voff) do { _Pragma("unroll") for (int _i = 0; _i < 2; ++_i) \
;         __builtin_amdgcn_global_load_lds((const unsigned*)((const char*)(gbase) + (voff)[_i]), (PG8_LAS unsigned*)(lds + (bufoff) + ldsw + _i * 8192), 16, 0, 0); } while (0)
; #define PG8_LDA(dst, b, h) do { _Pragma("unroll") for (int m = 0; m < 4; ++m) _Pragma("unroll") for (int k = 0; k < 2; ++k) dst[m][k] = *(const PG8_LAS bf16x8*)(lds + PG8_SA(b, h) + aoff + m * 2048 + k * 1024); } while (0)
; #define PG8_LDB(dst, b, h) do { _Pragma("unroll") for (int n = 0; n < 2; ++n) _Pragma("unroll") for (int k = 0; k < 2; ++k) dst[n][k] = *(const PG8_LAS bf16x8*)(lds + PG8_SB(b, h) + boff + n * 2048 + k * 1024); } while (0)
; #define PG8_MMA(ai, bj, At, Bt) do { __builtin_amdgcn_s_setprio(1); _Pragma("unroll") for (int m = 0; m < 4; ++m) _Pragma("unroll") for (int n = 0; n < 2; ++n) _Pragma("unroll") for (int k = 0; k < 2; ++k) \
;         acc[ai][bj][m][n] = __builtin_amdgcn_mfma_f32_16x16x32_bf16(Bt[n][k], At[m][k], acc[ai][bj][m][n], 0, 0, 0); __builtin_amdgcn_s_setprio(0); } while (0)
; #define PG8_WAIT_V(n) asm volatile("s_waitcnt vmcnt(" #n ")" ::: "memory")
; #define PG8_WAIT_L(n) asm volatile("s_waitcnt lgkmcnt(" #n ")" ::: "memory")
; #define PG8_BAR __builtin_amdgcn_s_barrier()
; #define PG8_SCHED __builtin_amdgcn_sched_barrier(0)
; template <class Epi, class Sched, bool ALIGN_EPI = false, bool SP2 = false>
; __device__ __forceinline__ void gemm_phase(PG8_LAS unsigned char* lds, const Gemm g, const Sched& S, const Epi& E) {
;     ...
;             PG8_LDB(B0, 0, 0); PG8_LDB(B1, 0, 1); PG8_SCHED; PG8_LDA(At, 0, 0); PG8_STAGE(PG8_SA(1, 1), a1 + hstepA, voffA);
;             PG8_WAIT_V(8); PG8_WAIT_L(0); PG8_BAR; PG8_MMA(0, 0, At, B0); PG8_MMA(0, 1, At, B1); PG8_BAR; PG8_SCHED;
;             PG8_LDA(At, 0, 1); PG8_STAGE(PG8_SB(0, 0), b2, voffB); PG8_STAGE(PG8_SB(0, 1), b2 + hstepB, voffB); PG8_STAGE(PG8_SA(0, 0), a2, voffA);
;             PG8_WAIT_V(8); PG8_WAIT_L(0); PG8_BAR; PG8_MMA(1, 0, At, B0); PG8_MMA(1, 1, At, B1); PG8_BAR; PG8_SCHED;
.LBB0_901:
	ds_read_b128 v[140:143], v147
	ds_read_b128 v[152:155], v147 offset:1024
	ds_read_b128 v[158:161], v147 offset:2048
	ds_read_b128 v[162:165], v147 offset:3072
	ds_read_b128 v[166:169], v148
	ds_read_b128 v[170:173], v148 offset:1024
	ds_read_b128 v[174:177], v148 offset:2048
	ds_read_b128 v[178:181], v148 offset:3072
	s_add_u32 s28, s26, 0xffe00080
	s_addc_u32 s29, s27, -1
	s_cmpk_eq_i32 s52, 0x7c
	s_cselect_b32 s31, s19, s29
	s_cselect_b32 s30, s23, s28
	s_cselect_b32 s29, s17, s51
	s_cselect_b32 s28, s49, s50
	v_lshl_add_u64 v[214:215], s[26:27], 0, v[132:133]
	s_add_i32 m0, s25, 0xc000
	ds_read_b128 v[182:185], v149
	ds_read_b128 v[186:189], v149 offset:1024
	ds_read_b128 v[190:193], v149 offset:2048
	ds_read_b128 v[194:197], v149 offset:3072
	ds_read_b128 v[198:201], v149 offset:4096
	ds_read_b128 v[202:205], v149 offset:5120
	ds_read_b128 v[206:209], v149 offset:6144
	ds_read_b128 v[210:213], v149 offset:7168
	global_load_lds_dwordx4 v[214:215], off
	v_lshl_add_u64 v[214:215], s[26:27], 0, v[134:135]
	s_add_i32 m0, s25, 0xe000
	s_nop 0
	global_load_lds_dwordx4 v[214:215], off
	s_waitcnt vmcnt(8)
	s_waitcnt lgkmcnt(0)
	s_barrier
	s_setprio 1
	s_waitcnt lgkmcnt(0)
	v_mfma_f32_16x16x32_bf16 v[124:127], v[140:143], v[182:185], v[124:127]
	v_mfma_f32_16x16x32_bf16 v[120:123], v[158:161], v[182:185], v[120:123]
	v_mfma_f32_16x16x32_bf16 v[108:111], v[140:143], v[190:193], v[108:111]
	v_mfma_f32_16x16x32_bf16 v[104:107], v[158:161], v[190:193], v[104:107]
	v_mfma_f32_16x16x32_bf16 v[92:95], v[140:143], v[198:201], v[92:95]
	v_mfma_f32_16x16x32_bf16 v[88:91], v[158:161], v[198:201], v[88:91]
	v_mfma_f32_16x16x32_bf16 v[76:79], v[140:143], v[206:209], v[76:79]
	v_mfma_f32_16x16x32_bf16 v[72:75], v[158:161], v[206:209], v[72:75]
	v_mfma_f32_16x16x32_bf16 v[124:127], v[152:155], v[186:189], v[124:127]
	v_mfma_f32_16x16x32_bf16 v[120:123], v[162:165], v[186:189], v[120:123]
	v_mfma_f32_16x16x32_bf16 v[108:111], v[152:155], v[194:197], v[108:111]
	v_mfma_f32_16x16x32_bf16 v[104:107], v[162:165], v[194:197], v[104:107]
	v_mfma_f32_16x16x32_bf16 v[92:95], v[152:155], v[202:205], v[92:95]
	v_mfma_f32_16x16x32_bf16 v[88:91], v[162:165], v[202:205], v[88:91]
	v_mfma_f32_16x16x32_bf16 v[76:79], v[152:155], v[210:213], v[76:79]
	v_mfma_f32_16x16x32_bf16 v[72:75], v[162:165], v[210:213], v[72:75]
	v_mfma_f32_16x16x32_bf16 v[116:119], v[166:169], v[182:185], v[116:119]
	v_mfma_f32_16x16x32_bf16 v[112:115], v[174:177], v[182:185], v[112:115]
	v_mfma_f32_16x16x32_bf16 v[100:103], v[166:169], v[190:193], v[100:103]
	v_mfma_f32_16x16x32_bf16 v[96:99], v[174:177], v[190:193], v[96:99]
	v_mfma_f32_16x16x32_bf16 v[84:87], v[166:169], v[198:201], v[84:87]
	v_mfma_f32_16x16x32_bf16 v[80:83], v[174:177], v[198:201], v[80:83]
	v_mfma_f32_16x16x32_bf16 v[68:71], v[166:169], v[206:209], v[68:71]
	v_mfma_f32_16x16x32_bf16 v[64:67], v[174:177], v[206:209], v[64:67]
	v_mfma_f32_16x16x32_bf16 v[116:119], v[170:173], v[186:189], v[116:119]
	v_mfma_f32_16x16x32_bf16 v[112:115], v[178:181], v[186:189], v[112:115]
	v_mfma_f32_16x16x32_bf16 v[100:103], v[170:173], v[194:197], v[100:103]
	v_mfma_f32_16x16x32_bf16 v[96:99], v[178:181], v[194:197], v[96:99]
	v_mfma_f32_16x16x32_bf16 v[84:87], v[170:173], v[202:205], v[84:87]
	v_mfma_f32_16x16x32_bf16 v[80:83], v[178:181], v[202:205], v[80:83]
	v_mfma_f32_16x16x32_bf16 v[68:71], v[170:173], v[210:213], v[68:71]
	v_mfma_f32_16x16x32_bf16 v[64:67], v[178:181], v[210:213], v[64:67]
	s_setprio 0
	s_barrier
	s_add_i32 s53, s47, s38
	v_lshl_add_u64 v[214:215], s[28:29], 0, v[128:129]
	s_mov_b32 m0, s53
	ds_read_b128 v[182:185], v149 offset:16384
	ds_read_b128 v[186:189], v149 offset:17408
	ds_read_b128 v[190:193], v149 offset:18432
	ds_read_b128 v[194:197], v149 offset:19456
	ds_read_b128 v[198:201], v149 offset:20480
	ds_read_b128 v[202:205], v149 offset:21504
	ds_read_b128 v[206:209], v149 offset:22528
	ds_read_b128 v[210:213], v149 offset:23552
	global_load_lds_dwordx4 v[214:215], off
	s_add_i32 m0, s53, 0x2000
	s_add_u32 s54, s28, 0x200000
	v_lshl_add_u64 v[216:217], s[28:29], 0, v[130:131]
	s_addc_u32 s55, s29, 0
	s_add_i32 s53, s48, s38
	global_load_lds_dwordx4 v[216:217], off
	v_lshl_add_u64 v[218:219], s[54:55], 0, v[128:129]
	s_mov_b32 m0, s53
	v_lshl_add_u64 v[220:221], s[30:31], 0, v[130:131]
	global_load_lds_dwordx4 v[218:219], off
	v_lshl_add_u64 v[218:219], s[54:55], 0, v[130:131]
	s_add_i32 m0, s53, 0x2000
	s_nop 0
	global_load_lds_dwordx4 v[218:219], off
	v_lshl_add_u64 v[218:219], s[30:31], 0, v[128:129]
	s_mov_b32 m0, s25
	s_nop 0
	global_load_lds_dwordx4 v[218:219], off
	s_mov_b32 m0, s39
	s_nop 0
	global_load_lds_dwordx4 v[220:221], off
	s_waitcnt vmcnt(8)
	s_waitcnt lgkmcnt(0)
	s_barrier
; #define PG8_STAGE(bufoff, gbase, voff) do { _Pragma("unroll") for (int _i = 0; _i < 2; ++_i) \
;         __builtin_amdgcn_global_load_lds((const unsigned*)((const char*)(gbase) + (voff)[_i]), (PG8_LAS unsigned*)(lds + (bufoff) + ldsw + _i * 8192), 16, 0, 0); } while (0)
; #define PG8_LDA(dst, b, h) do { _Pragma("unroll") for (int m = 0; m < 4; ++m) _Pragma("unroll") for (int k = 0; k < 2; ++k) dst[m][k] = *(const PG8_LAS bf16x8*)(lds + PG8_SA(b, h) + aoff + m * 2048 + k * 1024); } while (0)
; #define PG8_LDB(dst, b, h) do { _Pragma("unroll") for (int n = 0; n < 2; ++n) _Pragma("unroll") for (int k = 0; k < 2; ++k) dst[n][k] = *(const PG8_LAS bf16x8*)(lds + PG8_SB(b, h) + boff + n * 2048 + k * 1024); } while (0)
; #define PG8_MMA(ai, bj, At, Bt) do { __builtin_amdgcn_s_setprio(1); _Pragma("unroll") for (int m = 0; m < 4; ++m) _Pragma("unroll") for (int n = 0; n < 2; ++n) _Pragma("unroll") for (int k = 0; k < 2; ++k) \
;         acc[ai][bj][m][n] = __builtin_amdgcn_mfma_f32_16x16x32_bf16(Bt[n][k], At[m][k], acc[ai][bj][m][n], 0, 0, 0); __builtin_amdgcn_s_setprio(0); } while (0)
; #define PG8_WAIT_V(n) asm volatile("s_waitcnt vmcnt(" #n ")" ::: "memory")
; #define PG8_WAIT_L(n) asm volatile("s_waitcnt lgkmcnt(" #n ")" ::: "memory")
; #define PG8_BAR __builtin_amdgcn_s_barrier()
; #define PG8_SCHED __builtin_amdgcn_sched_barrier(0)
; template <class Epi, class Sched, bool ALIGN_EPI = false, bool SP2 = false>
; __device__ __forceinline__ void gemm_phase(PG8_LAS unsigned char* lds, const Gemm g, const Sched& S, const Epi& E) {
;     ...
;             PG8_WAIT_V(8); PG8_WAIT_L(0); PG8_BAR; PG8_MMA(1, 0, At, B0); PG8_MMA(1, 1, At, B1); PG8_BAR; PG8_SCHED;
;             PG8_LDB(B0, 1, 0); PG8_LDB(B1, 1, 1); PG8_SCHED; PG8_LDA(At, 1, 0); PG8_STAGE(PG8_SA(0, 1), a2 + hstepA, voffA);
;             PG8_WAIT_V(8); PG8_WAIT_L(0); PG8_BAR; PG8_MMA(0, 0, At, B0); PG8_MMA(0, 1, At, B1); PG8_BAR; PG8_SCHED;
	s_setprio 1
	s_waitcnt lgkmcnt(0)
	v_mfma_f32_16x16x32_bf16 v[60:63], v[140:143], v[182:185], v[60:63]
	v_mfma_f32_16x16x32_bf16 v[56:59], v[158:161], v[182:185], v[56:59]
	v_mfma_f32_16x16x32_bf16 v[44:47], v[140:143], v[190:193], v[44:47]
	v_mfma_f32_16x16x32_bf16 v[40:43], v[158:161], v[190:193], v[40:43]
	v_mfma_f32_16x16x32_bf16 v[28:31], v[140:143], v[198:201], v[28:31]
	v_mfma_f32_16x16x32_bf16 v[24:27], v[158:161], v[198:201], v[24:27]
	v_mfma_f32_16x16x32_bf16 v[12:15], v[140:143], v[206:209], v[12:15]
	v_mfma_f32_16x16x32_bf16 v[8:11], v[158:161], v[206:209], v[8:11]
	v_mfma_f32_16x16x32_bf16 v[60:63], v[152:155], v[186:189], v[60:63]
	v_mfma_f32_16x16x32_bf16 v[56:59], v[162:165], v[186:189], v[56:59]
	v_mfma_f32_16x16x32_bf16 v[44:47], v[152:155], v[194:197], v[44:47]
	v_mfma_f32_16x16x32_bf16 v[40:43], v[162:165], v[194:197], v[40:43]
	v_mfma_f32_16x16x32_bf16 v[28:31], v[152:155], v[202:205], v[28:31]
	v_mfma_f32_16x16x32_bf16 v[24:27], v[162:165], v[202:205], v[24:27]
	v_mfma_f32_16x16x32_bf16 v[12:15], v[152:155], v[210:213], v[12:15]
	v_mfma_f32_16x16x32_bf16 v[8:11], v[162:165], v[210:213], v[8:11]
	v_mfma_f32_16x16x32_bf16 v[52:55], v[166:169], v[182:185], v[52:55]
	v_mfma_f32_16x16x32_bf16 v[48:51], v[174:177], v[182:185], v[48:51]
	v_mfma_f32_16x16x32_bf16 v[36:39], v[166:169], v[190:193], v[36:39]
	v_mfma_f32_16x16x32_bf16 v[32:35], v[174:177], v[190:193], v[32:35]
	v_mfma_f32_16x16x32_bf16 v[20:23], v[166:169], v[198:201], v[20:23]
	v_mfma_f32_16x16x32_bf16 v[16:19], v[174:177], v[198:201], v[16:19]
	v_mfma_f32_16x16x32_bf16 v[4:7], v[166:169], v[206:209], v[4:7]
	v_mfma_f32_16x16x32_bf16 v[0:3], v[174:177], v[206:209], v[0:3]
	v_mfma_f32_16x16x32_bf16 v[52:55], v[170:173], v[186:189], v[52:55]
	v_mfma_f32_16x16x32_bf16 v[48:51], v[178:181], v[186:189], v[48:51]
	v_mfma_f32_16x16x32_bf16 v[36:39], v[170:173], v[194:197], v[36:39]
	v_mfma_f32_16x16x32_bf16 v[32:35], v[178:181], v[194:197], v[32:35]
	v_mfma_f32_16x16x32_bf16 v[20:23], v[170:173], v[202:205], v[20:23]
	v_mfma_f32_16x16x32_bf16 v[16:19], v[178:181], v[202:205], v[16:19]
	v_mfma_f32_16x16x32_bf16 v[4:7], v[170:173], v[210:213], v[4:7]
	v_mfma_f32_16x16x32_bf16 v[0:3], v[178:181], v[210:213], v[0:3]
	s_setprio 0
	s_barrier
	s_add_i32 s53, 0, 0x18000
	v_add_u32_e32 v151, s53, v145
	s_add_i32 s54, 0, 0x1c000
	ds_read_b128 v[140:143], v151
	ds_read_b128 v[152:155], v151 offset:1024
	ds_read_b128 v[158:161], v151 offset:2048
	ds_read_b128 v[162:165], v151 offset:3072
	v_add_u32_e32 v151, s54, v145
	ds_read_b128 v[166:169], v151
	ds_read_b128 v[170:173], v151 offset:1024
	ds_read_b128 v[174:177], v151 offset:2048
	ds_read_b128 v[178:181], v151 offset:3072
	s_add_u32 s30, s30, 0x200000
	s_addc_u32 s31, s31, 0
	s_mov_b32 m0, s40
	v_lshl_add_u64 v[222:223], s[30:31], 0, v[128:129]
	ds_read_b128 v[182:185], v149 offset:32768
	ds_read_b128 v[186:189], v149 offset:33792
	ds_read_b128 v[190:193], v149 offset:34816
	ds_read_b128 v[194:197], v149 offset:35840
	ds_read_b128 v[198:201], v149 offset:36864
	ds_read_b128 v[202:205], v149 offset:37888
	ds_read_b128 v[206:209], v149 offset:38912
	ds_read_b128 v[210:213], v149 offset:39936
	global_load_lds_dwordx4 v[222:223], off
	v_lshl_add_u64 v[222:223], s[30:31], 0, v[130:131]
	s_mov_b32 m0, s41
	s_nop 0
	global_load_lds_dwordx4 v[222:223], off
	s_waitcnt vmcnt(8)
	s_waitcnt lgkmcnt(0)
	s_barrier
	s_setprio 1
	s_waitcnt lgkmcnt(0)
	v_mfma_f32_16x16x32_bf16 v[124:127], v[140:143], v[182:185], v[124:127]
	v_mfma_f32_16x16x32_bf16 v[120:123], v[158:161], v[182:185], v[120:123]
	v_mfma_f32_16x16x32_bf16 v[108:111], v[140:143], v[190:193], v[108:111]
	v_mfma_f32_16x16x32_bf16 v[104:107], v[158:161], v[190:193], v[104:107]
	v_mfma_f32_16x16x32_bf16 v[92:95], v[140:143], v[198:201], v[92:95]
	v_mfma_f32_16x16x32_bf16 v[88:91], v[158:161], v[198:201], v[88:91]
	v_mfma_f32_16x16x32_bf16 v[76:79], v[140:143], v[206:209], v[76:79]
	v_mfma_f32_16x16x32_bf16 v[72:75], v[158:161], v[206:209], v[72:75]
	v_mfma_f32_16x16x32_bf16 v[124:127], v[152:155], v[186:189], v[124:127]
	v_mfma_f32_16x16x32_bf16 v[120:123], v[162:165], v[186:189], v[120:123]
	v_mfma_f32_16x16x32_bf16 v[108:111], v[152:155], v[194:197], v[108:111]
	v_mfma_f32_16x16x32_bf16 v[104:107], v[162:165], v[194:197], v[104:107]
	v_mfma_f32_16x16x32_bf16 v[92:95], v[152:155], v[202:205], v[92:95]
	v_mfma_f32_16x16x32_bf16 v[88:91], v[162:165], v[202:205], v[88:91]
	v_mfma_f32_16x16x32_bf16 v[76:79], v[152:155], v[210:213], v[76:79]
	v_mfma_f32_16x16x32_bf16 v[72:75], v[162:165], v[210:213], v[72:75]
	v_mfma_f32_16x16x32_bf16 v[116:119], v[166:169], v[182:185], v[116:119]
	v_mfma_f32_16x16x32_bf16 v[112:115], v[174:177], v[182:185], v[112:115]
	v_mfma_f32_16x16x32_bf16 v[100:103], v[166:169], v[190:193], v[100:103]
	v_mfma_f32_16x16x32_bf16 v[96:99], v[174:177], v[190:193], v[96:99]
	v_mfma_f32_16x16x32_bf16 v[84:87], v[166:169], v[198:201], v[84:87]
	v_mfma_f32_16x16x32_bf16 v[80:83], v[174:177], v[198:201], v[80:83]
	v_mfma_f32_16x16x32_bf16 v[68:71], v[166:169], v[206:209], v[68:71]
	v_mfma_f32_16x16x32_bf16 v[64:67], v[174:177], v[206:209], v[64:67]
	v_mfma_f32_16x16x32_bf16 v[116:119], v[170:173], v[186:189], v[116:119]
	v_mfma_f32_16x16x32_bf16 v[112:115], v[178:181], v[186:189], v[112:115]
	v_mfma_f32_16x16x32_bf16 v[100:103], v[170:173], v[194:197], v[100:103]
	v_mfma_f32_16x16x32_bf16 v[96:99], v[178:181], v[194:197], v[96:99]
	v_mfma_f32_16x16x32_bf16 v[84:87], v[170:173], v[202:205], v[84:87]
	v_mfma_f32_16x16x32_bf16 v[80:83], v[178:181], v[202:205], v[80:83]
	v_mfma_f32_16x16x32_bf16 v[68:71], v[170:173], v[210:213], v[68:71]
	v_mfma_f32_16x16x32_bf16 v[64:67], v[178:181], v[210:213], v[64:67]
	s_setprio 0
	s_barrier
; #define PG8_STAGE(bufoff, gbase, voff) do { _Pragma("unroll") for (int _i = 0; _i < 2; ++_i) \
;         __builtin_amdgcn_global_load_lds((const unsigned*)((const char*)(gbase) + (voff)[_i]), (PG8_LAS unsigned*)(lds + (bufoff) + ldsw + _i * 8192), 16, 0, 0); } while (0)
; #define PG8_LDA(dst, b, h) do { _Pragma("unroll") for (int m = 0; m < 4; ++m) _Pragma("unroll") for (int k = 0; k < 2; ++k) dst[m][k] = *(const PG8_LAS bf16x8*)(lds + PG8_SA(b, h) + aoff + m * 2048 + k * 1024); } while (0)
; #define PG8_MMA(ai, bj, At, Bt) do { __builtin_amdgcn_s_setprio(1); _Pragma("unroll") for (int m = 0; m < 4; ++m) _Pragma("unroll") for (int n = 0; n < 2; ++n) _Pragma("unroll") for (int k = 0; k < 2; ++k) \
;         acc[ai][bj][m][n] = __builtin_amdgcn_mfma_f32_16x16x32_bf16(Bt[n][k], At[m][k], acc[ai][bj][m][n], 0, 0, 0); __builtin_amdgcn_s_setprio(0); } while (0)
; #define PG8_WAIT_V(n) asm volatile("s_waitcnt vmcnt(" #n ")" ::: "memory")
; #define PG8_WAIT_L(n) asm volatile("s_waitcnt lgkmcnt(" #n ")" ::: "memory")
; #define PG8_BAR __builtin_amdgcn_s_barrier()
; #define PG8_SCHED __builtin_amdgcn_sched_barrier(0)
; template <class Epi, class Sched, bool ALIGN_EPI = false, bool SP2 = false>
; __device__ __forceinline__ void gemm_phase(PG8_LAS unsigned char* lds, const Gemm g, const Sched& S, const Epi& E) {
;     ...
;         for (int t = 0; t < nt; t += 2) {
;     ...
;             PG8_LDA(At, 1, 1); PG8_STAGE(PG8_SB(1, 0), b3, voffB); PG8_STAGE(PG8_SB(1, 1), b3 + hstepB, voffB); PG8_STAGE(PG8_SA(1, 0), a3, voffA);
;             PG8_WAIT_V(8); PG8_WAIT_L(0); PG8_BAR; PG8_MMA(1, 0, At, B0); PG8_MMA(1, 1, At, B1); PG8_BAR; PG8_SCHED;
	s_add_i32 s30, s53, s38
	v_lshl_add_u64 v[214:215], v[214:215], 0, s[12:13]
	s_mov_b32 m0, s30
	ds_read_b128 v[182:185], v149 offset:49152
	ds_read_b128 v[186:189], v149 offset:50176
	ds_read_b128 v[190:193], v149 offset:51200
	ds_read_b128 v[194:197], v149 offset:52224
	ds_read_b128 v[198:201], v149 offset:53248
	ds_read_b128 v[202:205], v149 offset:54272
	ds_read_b128 v[206:209], v149 offset:55296
	ds_read_b128 v[210:213], v149 offset:56320
	global_load_lds_dwordx4 v[214:215], off
	s_add_i32 m0, s30, 0x2000
	s_add_u32 s28, s28, 0x200080
	v_lshl_add_u64 v[214:215], v[216:217], 0, s[12:13]
	s_addc_u32 s29, s29, 0
	s_add_i32 s30, s54, s38
	global_load_lds_dwordx4 v[214:215], off
	v_lshl_add_u64 v[214:215], s[28:29], 0, v[128:129]
	s_mov_b32 m0, s30
	s_nop 0
	global_load_lds_dwordx4 v[214:215], off
	v_lshl_add_u64 v[214:215], s[28:29], 0, v[130:131]
	s_add_i32 m0, s30, 0x2000
	s_nop 0
	global_load_lds_dwordx4 v[214:215], off
	v_lshl_add_u64 v[214:215], v[218:219], 0, s[12:13]
	s_mov_b32 m0, s43
	s_nop 0
	global_load_lds_dwordx4 v[214:215], off
	v_lshl_add_u64 v[214:215], v[220:221], 0, s[12:13]
	s_mov_b32 m0, s44
	s_nop 0
	global_load_lds_dwordx4 v[214:215], off
	s_waitcnt vmcnt(8)
	s_waitcnt lgkmcnt(0)
	s_barrier
	s_setprio 1
	s_waitcnt lgkmcnt(0)
	v_mfma_f32_16x16x32_bf16 v[60:63], v[140:143], v[182:185], v[60:63]
	v_mfma_f32_16x16x32_bf16 v[56:59], v[158:161], v[182:185], v[56:59]
	v_mfma_f32_16x16x32_bf16 v[44:47], v[140:143], v[190:193], v[44:47]
	v_mfma_f32_16x16x32_bf16 v[40:43], v[158:161], v[190:193], v[40:43]
	v_mfma_f32_16x16x32_bf16 v[28:31], v[140:143], v[198:201], v[28:31]
	v_mfma_f32_16x16x32_bf16 v[24:27], v[158:161], v[198:201], v[24:27]
	v_mfma_f32_16x16x32_bf16 v[12:15], v[140:143], v[206:209], v[12:15]
	v_mfma_f32_16x16x32_bf16 v[8:11], v[158:161], v[206:209], v[8:11]
	v_mfma_f32_16x16x32_bf16 v[60:63], v[152:155], v[186:189], v[60:63]
	v_mfma_f32_16x16x32_bf16 v[56:59], v[162:165], v[186:189], v[56:59]
	v_mfma_f32_16x16x32_bf16 v[44:47], v[152:155], v[194:197], v[44:47]
	v_mfma_f32_16x16x32_bf16 v[40:43], v[162:165], v[194:197], v[40:43]
	v_mfma_f32_16x16x32_bf16 v[28:31], v[152:155], v[202:205], v[28:31]
	v_mfma_f32_16x16x32_bf16 v[24:27], v[162:165], v[202:205], v[24:27]
	v_mfma_f32_16x16x32_bf16 v[12:15], v[152:155], v[210:213], v[12:15]
	v_mfma_f32_16x16x32_bf16 v[8:11], v[162:165], v[210:213], v[8:11]
	v_mfma_f32_16x16x32_bf16 v[52:55], v[166:169], v[182:185], v[52:55]
	v_mfma_f32_16x16x32_bf16 v[48:51], v[174:177], v[182:185], v[48:51]
	v_mfma_f32_16x16x32_bf16 v[36:39], v[166:169], v[190:193], v[36:39]
	v_mfma_f32_16x16x32_bf16 v[32:35], v[174:177], v[190:193], v[32:35]
	v_mfma_f32_16x16x32_bf16 v[20:23], v[166:169], v[198:201], v[20:23]
	v_mfma_f32_16x16x32_bf16 v[16:19], v[174:177], v[198:201], v[16:19]
	v_mfma_f32_16x16x32_bf16 v[4:7], v[166:169], v[206:209], v[4:7]
	v_mfma_f32_16x16x32_bf16 v[0:3], v[174:177], v[206:209], v[0:3]
	v_mfma_f32_16x16x32_bf16 v[52:55], v[170:173], v[186:189], v[52:55]
	v_mfma_f32_16x16x32_bf16 v[48:51], v[178:181], v[186:189], v[48:51]
	v_mfma_f32_16x16x32_bf16 v[36:39], v[170:173], v[194:197], v[36:39]
	v_mfma_f32_16x16x32_bf16 v[32:35], v[178:181], v[194:197], v[32:35]
	v_mfma_f32_16x16x32_bf16 v[20:23], v[170:173], v[202:205], v[20:23]
	v_mfma_f32_16x16x32_bf16 v[16:19], v[178:181], v[202:205], v[16:19]
	v_mfma_f32_16x16x32_bf16 v[4:7], v[170:173], v[210:213], v[4:7]
	v_mfma_f32_16x16x32_bf16 v[0:3], v[178:181], v[210:213], v[0:3]
	s_setprio 0
	s_barrier
	s_add_i32 s52, s52, 2
	s_add_u32 s26, s26, 0x100
	s_addc_u32 s27, s27, 0
	s_add_u32 s50, s50, 0x100
	s_addc_u32 s51, s51, 0
	s_cmpk_gt_u32 s52, 0x7d
	s_cbranch_scc0 .LBB0_901
	s_and_b64 vcc, exec, s[14:15]
	s_cbranch_vccz .LBB0_904
	s_barrier
